# template loops: reorder each 16-MFMA burst so both k-halves of one accumulator issue back to back (acc chaining), on top of epilogue version
# speedup vs baseline: 1.0141x; 1.0141x over previous
.LBB0_147:
	ds_read_b128 v[144:147], v165
	v_xor_b32_e32 v177, 64, v165
	ds_read_b128 v[148:151], v177
	ds_read_b128 v[170:173], v165 offset:2048
	ds_read_b128 v[174:177], v177 offset:2048
	s_add_u32 s18, s16, 0xfff80080
	s_addc_u32 s19, s17, -1
	s_cmp_eq_u32 s47, 28
	s_cselect_b32 s21, s11, s19
	s_cselect_b32 s20, s41, s18
	s_cselect_b32 s19, s9, s46
	s_cselect_b32 s18, s44, s45
	v_lshl_add_u64 v[210:211], s[16:17], 0, v[136:137]
	s_add_i32 m0, s1, 0xc000
	ds_read_b128 v[178:181], v166
	v_xor_b32_e32 v209, 64, v166
	ds_read_b128 v[182:185], v209
	ds_read_b128 v[186:189], v166 offset:2048
	ds_read_b128 v[190:193], v209 offset:2048
	ds_read_b128 v[194:197], v166 offset:4096
	ds_read_b128 v[198:201], v209 offset:4096
	ds_read_b128 v[202:205], v166 offset:6144
	ds_read_b128 v[206:209], v209 offset:6144
	global_load_lds_dwordx4 v[210:211], off
	v_lshl_add_u64 v[210:211], s[16:17], 0, v[138:139]
	s_add_i32 m0, s1, 0xe000
	s_nop 0
	global_load_lds_dwordx4 v[210:211], off
	s_waitcnt lgkmcnt(8)
	s_barrier
	s_waitcnt lgkmcnt(0)
	s_setprio 1
	s_waitcnt lgkmcnt(0)
	v_mfma_f32_16x16x32_bf16 v[124:127], v[144:147], v[178:181], v[124:127]
	v_mfma_f32_16x16x32_bf16 v[124:127], v[148:151], v[182:185], v[124:127]
	v_mfma_f32_16x16x32_bf16 v[120:123], v[170:173], v[178:181], v[120:123]
	v_mfma_f32_16x16x32_bf16 v[120:123], v[174:177], v[182:185], v[120:123]
	v_mfma_f32_16x16x32_bf16 v[108:111], v[144:147], v[186:189], v[108:111]
	v_mfma_f32_16x16x32_bf16 v[108:111], v[148:151], v[190:193], v[108:111]
	v_mfma_f32_16x16x32_bf16 v[104:107], v[170:173], v[186:189], v[104:107]
	v_mfma_f32_16x16x32_bf16 v[104:107], v[174:177], v[190:193], v[104:107]
	v_mfma_f32_16x16x32_bf16 v[92:95], v[144:147], v[194:197], v[92:95]
	v_mfma_f32_16x16x32_bf16 v[92:95], v[148:151], v[198:201], v[92:95]
	v_mfma_f32_16x16x32_bf16 v[88:91], v[170:173], v[194:197], v[88:91]
	v_mfma_f32_16x16x32_bf16 v[88:91], v[174:177], v[198:201], v[88:91]
	v_mfma_f32_16x16x32_bf16 v[76:79], v[144:147], v[202:205], v[76:79]
	v_mfma_f32_16x16x32_bf16 v[76:79], v[148:151], v[206:209], v[76:79]
	v_mfma_f32_16x16x32_bf16 v[72:75], v[170:173], v[202:205], v[72:75]
	v_mfma_f32_16x16x32_bf16 v[72:75], v[174:177], v[206:209], v[72:75]
	s_setprio 0
	s_barrier
	s_add_i32 s48, s35, s24
	v_lshl_add_u64 v[220:221], s[18:19], 0, v[132:133]
	s_mov_b32 m0, s48
	ds_read_b128 v[210:213], v167
	v_xor_b32_e32 v233, 64, v167
	ds_read_b128 v[214:217], v233
	ds_read_b128 v[226:229], v167 offset:2048
	ds_read_b128 v[230:233], v233 offset:2048
	global_load_lds_dwordx4 v[220:221], off
	v_lshl_add_u64 v[234:235], s[18:19], 0, v[128:129]
	s_add_i32 m0, s48, 0x2000
	s_nop 0
	global_load_lds_dwordx4 v[234:235], off
	s_barrier
	s_waitcnt lgkmcnt(0)
	s_setprio 1
	s_waitcnt lgkmcnt(0)
	v_mfma_f32_16x16x32_bf16 v[116:119], v[210:213], v[178:181], v[116:119]
	v_mfma_f32_16x16x32_bf16 v[116:119], v[214:217], v[182:185], v[116:119]
	v_mfma_f32_16x16x32_bf16 v[112:115], v[226:229], v[178:181], v[112:115]
	v_mfma_f32_16x16x32_bf16 v[112:115], v[230:233], v[182:185], v[112:115]
	v_mfma_f32_16x16x32_bf16 v[100:103], v[210:213], v[186:189], v[100:103]
	v_mfma_f32_16x16x32_bf16 v[100:103], v[214:217], v[190:193], v[100:103]
	v_mfma_f32_16x16x32_bf16 v[96:99], v[226:229], v[186:189], v[96:99]
	v_mfma_f32_16x16x32_bf16 v[96:99], v[230:233], v[190:193], v[96:99]
	v_mfma_f32_16x16x32_bf16 v[84:87], v[210:213], v[194:197], v[84:87]
	v_mfma_f32_16x16x32_bf16 v[84:87], v[214:217], v[198:201], v[84:87]
	v_mfma_f32_16x16x32_bf16 v[80:83], v[226:229], v[194:197], v[80:83]
	v_mfma_f32_16x16x32_bf16 v[80:83], v[230:233], v[198:201], v[80:83]
	v_mfma_f32_16x16x32_bf16 v[68:71], v[210:213], v[202:205], v[68:71]
	v_mfma_f32_16x16x32_bf16 v[68:71], v[214:217], v[206:209], v[68:71]
	v_mfma_f32_16x16x32_bf16 v[64:67], v[226:229], v[202:205], v[64:67]
	v_mfma_f32_16x16x32_bf16 v[64:67], v[230:233], v[206:209], v[64:67]
	s_setprio 0
	s_mov_b32 m0, s1
	v_lshl_add_u64 v[236:237], s[20:21], 0, v[134:135]
	s_barrier
	ds_read_b128 v[178:181], v166 offset:16384
	v_xor_b32_e32 v209, 64, v166
	ds_read_b128 v[182:185], v209 offset:16384
	ds_read_b128 v[186:189], v166 offset:18432
	ds_read_b128 v[190:193], v209 offset:18432
	ds_read_b128 v[194:197], v166 offset:20480
	ds_read_b128 v[198:201], v209 offset:20480
	ds_read_b128 v[202:205], v166 offset:22528
	ds_read_b128 v[206:209], v209 offset:22528
	global_load_lds_dwordx4 v[236:237], off
	v_lshl_add_u64 v[240:241], s[20:21], 0, v[130:131]
	s_mov_b32 m0, s26
	s_nop 0
	global_load_lds_dwordx4 v[240:241], off
	s_barrier
	s_waitcnt lgkmcnt(0)
	s_setprio 1
	s_waitcnt lgkmcnt(0)
	v_mfma_f32_16x16x32_bf16 v[60:63], v[144:147], v[178:181], v[60:63]
	v_mfma_f32_16x16x32_bf16 v[60:63], v[148:151], v[182:185], v[60:63]
	v_mfma_f32_16x16x32_bf16 v[56:59], v[170:173], v[178:181], v[56:59]
	v_mfma_f32_16x16x32_bf16 v[56:59], v[174:177], v[182:185], v[56:59]
	v_mfma_f32_16x16x32_bf16 v[44:47], v[144:147], v[186:189], v[44:47]
	v_mfma_f32_16x16x32_bf16 v[44:47], v[148:151], v[190:193], v[44:47]
	v_mfma_f32_16x16x32_bf16 v[40:43], v[170:173], v[186:189], v[40:43]
	v_mfma_f32_16x16x32_bf16 v[40:43], v[174:177], v[190:193], v[40:43]
	v_mfma_f32_16x16x32_bf16 v[28:31], v[144:147], v[194:197], v[28:31]
	v_mfma_f32_16x16x32_bf16 v[28:31], v[148:151], v[198:201], v[28:31]
	v_mfma_f32_16x16x32_bf16 v[24:27], v[170:173], v[194:197], v[24:27]
	v_mfma_f32_16x16x32_bf16 v[24:27], v[174:177], v[198:201], v[24:27]
	v_mfma_f32_16x16x32_bf16 v[12:15], v[144:147], v[202:205], v[12:15]
	v_mfma_f32_16x16x32_bf16 v[12:15], v[148:151], v[206:209], v[12:15]
	v_mfma_f32_16x16x32_bf16 v[8:11], v[170:173], v[202:205], v[8:11]
	v_mfma_f32_16x16x32_bf16 v[8:11], v[174:177], v[206:209], v[8:11]
	s_setprio 0
	s_barrier
	s_add_u32 s48, s18, 0x80000
	s_addc_u32 s49, s19, 0
	s_add_i32 s52, s38, s24
	v_lshl_add_u64 v[144:145], s[48:49], 0, v[132:133]
	s_mov_b32 m0, s52
	s_nop 0
	global_load_lds_dwordx4 v[144:145], off
	v_lshl_add_u64 v[144:145], s[48:49], 0, v[128:129]
	s_add_i32 m0, s52, 0x2000
	s_nop 0
	global_load_lds_dwordx4 v[144:145], off
	s_waitcnt vmcnt(6)
	s_barrier
	s_setprio 1
	v_mfma_f32_16x16x32_bf16 v[52:55], v[210:213], v[178:181], v[52:55]
	v_mfma_f32_16x16x32_bf16 v[52:55], v[214:217], v[182:185], v[52:55]
	v_mfma_f32_16x16x32_bf16 v[48:51], v[226:229], v[178:181], v[48:51]
	v_mfma_f32_16x16x32_bf16 v[48:51], v[230:233], v[182:185], v[48:51]
	v_mfma_f32_16x16x32_bf16 v[36:39], v[210:213], v[186:189], v[36:39]
	v_mfma_f32_16x16x32_bf16 v[36:39], v[214:217], v[190:193], v[36:39]
	v_mfma_f32_16x16x32_bf16 v[32:35], v[226:229], v[186:189], v[32:35]
	v_mfma_f32_16x16x32_bf16 v[32:35], v[230:233], v[190:193], v[32:35]
	v_mfma_f32_16x16x32_bf16 v[20:23], v[210:213], v[194:197], v[20:23]
	v_mfma_f32_16x16x32_bf16 v[20:23], v[214:217], v[198:201], v[20:23]
	v_mfma_f32_16x16x32_bf16 v[16:19], v[226:229], v[194:197], v[16:19]
	v_mfma_f32_16x16x32_bf16 v[16:19], v[230:233], v[198:201], v[16:19]
	v_mfma_f32_16x16x32_bf16 v[4:7], v[210:213], v[202:205], v[4:7]
	v_mfma_f32_16x16x32_bf16 v[4:7], v[214:217], v[206:209], v[4:7]
	v_mfma_f32_16x16x32_bf16 v[0:3], v[226:229], v[202:205], v[0:3]
	v_mfma_f32_16x16x32_bf16 v[0:3], v[230:233], v[206:209], v[0:3]
	s_setprio 0
	s_add_i32 s48, 0, 0x18000
	v_add_u32_e32 v169, s48, v161
	s_barrier
	ds_read_b128 v[144:147], v169
	v_xor_b32_e32 v177, 64, v169
	ds_read_b128 v[148:151], v177
	ds_read_b128 v[170:173], v169 offset:2048
	ds_read_b128 v[174:177], v177 offset:2048
	s_add_u32 s20, s20, 0x80000
	s_addc_u32 s21, s21, 0
	s_mov_b32 m0, s27
	v_lshl_add_u64 v[210:211], s[20:21], 0, v[134:135]
	ds_read_b128 v[178:181], v166 offset:32768
	v_xor_b32_e32 v209, 64, v166
	ds_read_b128 v[182:185], v209 offset:32768
	ds_read_b128 v[186:189], v166 offset:34816
	ds_read_b128 v[190:193], v209 offset:34816
	ds_read_b128 v[194:197], v166 offset:36864
	ds_read_b128 v[198:201], v209 offset:36864
	ds_read_b128 v[202:205], v166 offset:38912
	ds_read_b128 v[206:209], v209 offset:38912
	global_load_lds_dwordx4 v[210:211], off
	v_lshl_add_u64 v[210:211], s[20:21], 0, v[130:131]
	s_mov_b32 m0, s28
	s_nop 0
	global_load_lds_dwordx4 v[210:211], off
	s_waitcnt lgkmcnt(8)
	s_barrier
	s_waitcnt lgkmcnt(0)
	s_setprio 1
	s_waitcnt lgkmcnt(0)
	v_mfma_f32_16x16x32_bf16 v[124:127], v[144:147], v[178:181], v[124:127]
	v_mfma_f32_16x16x32_bf16 v[124:127], v[148:151], v[182:185], v[124:127]
	v_mfma_f32_16x16x32_bf16 v[120:123], v[170:173], v[178:181], v[120:123]
	v_mfma_f32_16x16x32_bf16 v[120:123], v[174:177], v[182:185], v[120:123]
	v_mfma_f32_16x16x32_bf16 v[108:111], v[144:147], v[186:189], v[108:111]
	v_mfma_f32_16x16x32_bf16 v[108:111], v[148:151], v[190:193], v[108:111]
	v_mfma_f32_16x16x32_bf16 v[104:107], v[170:173], v[186:189], v[104:107]
	v_mfma_f32_16x16x32_bf16 v[104:107], v[174:177], v[190:193], v[104:107]
	v_mfma_f32_16x16x32_bf16 v[92:95], v[144:147], v[194:197], v[92:95]
	v_mfma_f32_16x16x32_bf16 v[92:95], v[148:151], v[198:201], v[92:95]
	v_mfma_f32_16x16x32_bf16 v[88:91], v[170:173], v[194:197], v[88:91]
	v_mfma_f32_16x16x32_bf16 v[88:91], v[174:177], v[198:201], v[88:91]
	v_mfma_f32_16x16x32_bf16 v[76:79], v[144:147], v[202:205], v[76:79]
	v_mfma_f32_16x16x32_bf16 v[76:79], v[148:151], v[206:209], v[76:79]
	v_mfma_f32_16x16x32_bf16 v[72:75], v[170:173], v[202:205], v[72:75]
	v_mfma_f32_16x16x32_bf16 v[72:75], v[174:177], v[206:209], v[72:75]
	s_setprio 0
	s_barrier
	s_add_i32 s20, 0, 0x1c000
	s_add_i32 s21, s48, s24
	v_add_u32_e32 v169, s20, v161
	v_lshl_add_u64 v[220:221], v[220:221], 0, s[6:7]
	s_mov_b32 m0, s21
	ds_read_b128 v[210:213], v169
	v_xor_b32_e32 v233, 64, v169
	ds_read_b128 v[214:217], v233
	ds_read_b128 v[226:229], v169 offset:2048
	ds_read_b128 v[230:233], v233 offset:2048
	global_load_lds_dwordx4 v[220:221], off
	v_lshl_add_u64 v[220:221], v[234:235], 0, s[6:7]
	s_add_i32 m0, s21, 0x2000
	s_nop 0
	global_load_lds_dwordx4 v[220:221], off
	s_barrier
	s_waitcnt lgkmcnt(0)
	s_setprio 1
	s_waitcnt lgkmcnt(0)
	v_mfma_f32_16x16x32_bf16 v[116:119], v[210:213], v[178:181], v[116:119]
	v_mfma_f32_16x16x32_bf16 v[116:119], v[214:217], v[182:185], v[116:119]
	v_mfma_f32_16x16x32_bf16 v[112:115], v[226:229], v[178:181], v[112:115]
	v_mfma_f32_16x16x32_bf16 v[112:115], v[230:233], v[182:185], v[112:115]
	v_mfma_f32_16x16x32_bf16 v[100:103], v[210:213], v[186:189], v[100:103]
	v_mfma_f32_16x16x32_bf16 v[100:103], v[214:217], v[190:193], v[100:103]
	v_mfma_f32_16x16x32_bf16 v[96:99], v[226:229], v[186:189], v[96:99]
	v_mfma_f32_16x16x32_bf16 v[96:99], v[230:233], v[190:193], v[96:99]
	v_mfma_f32_16x16x32_bf16 v[84:87], v[210:213], v[194:197], v[84:87]
	v_mfma_f32_16x16x32_bf16 v[84:87], v[214:217], v[198:201], v[84:87]
	v_mfma_f32_16x16x32_bf16 v[80:83], v[226:229], v[194:197], v[80:83]
	v_mfma_f32_16x16x32_bf16 v[80:83], v[230:233], v[198:201], v[80:83]
	v_mfma_f32_16x16x32_bf16 v[68:71], v[210:213], v[202:205], v[68:71]
	v_mfma_f32_16x16x32_bf16 v[68:71], v[214:217], v[206:209], v[68:71]
	v_mfma_f32_16x16x32_bf16 v[64:67], v[226:229], v[202:205], v[64:67]
	v_mfma_f32_16x16x32_bf16 v[64:67], v[230:233], v[206:209], v[64:67]
	s_setprio 0
	s_mov_b32 m0, s30
	v_lshl_add_u64 v[220:221], v[236:237], 0, s[6:7]
	s_barrier
	ds_read_b128 v[178:181], v166 offset:49152
	v_xor_b32_e32 v209, 64, v166
	ds_read_b128 v[182:185], v209 offset:49152
	ds_read_b128 v[186:189], v166 offset:51200
	ds_read_b128 v[190:193], v209 offset:51200
	ds_read_b128 v[194:197], v166 offset:53248
	ds_read_b128 v[198:201], v209 offset:53248
	ds_read_b128 v[202:205], v166 offset:55296
	ds_read_b128 v[206:209], v209 offset:55296
	global_load_lds_dwordx4 v[220:221], off
	v_lshl_add_u64 v[220:221], v[240:241], 0, s[6:7]
	s_mov_b32 m0, s31
	s_nop 0
	global_load_lds_dwordx4 v[220:221], off
	s_barrier
	s_waitcnt lgkmcnt(0)
	s_setprio 1
	s_waitcnt lgkmcnt(0)
	v_mfma_f32_16x16x32_bf16 v[60:63], v[144:147], v[178:181], v[60:63]
	v_mfma_f32_16x16x32_bf16 v[60:63], v[148:151], v[182:185], v[60:63]
	v_mfma_f32_16x16x32_bf16 v[56:59], v[170:173], v[178:181], v[56:59]
	v_mfma_f32_16x16x32_bf16 v[56:59], v[174:177], v[182:185], v[56:59]
	v_mfma_f32_16x16x32_bf16 v[44:47], v[144:147], v[186:189], v[44:47]
	v_mfma_f32_16x16x32_bf16 v[44:47], v[148:151], v[190:193], v[44:47]
	v_mfma_f32_16x16x32_bf16 v[40:43], v[170:173], v[186:189], v[40:43]
	v_mfma_f32_16x16x32_bf16 v[40:43], v[174:177], v[190:193], v[40:43]
	v_mfma_f32_16x16x32_bf16 v[28:31], v[144:147], v[194:197], v[28:31]
	v_mfma_f32_16x16x32_bf16 v[28:31], v[148:151], v[198:201], v[28:31]
	v_mfma_f32_16x16x32_bf16 v[24:27], v[170:173], v[194:197], v[24:27]
	v_mfma_f32_16x16x32_bf16 v[24:27], v[174:177], v[198:201], v[24:27]
	v_mfma_f32_16x16x32_bf16 v[12:15], v[144:147], v[202:205], v[12:15]
	v_mfma_f32_16x16x32_bf16 v[12:15], v[148:151], v[206:209], v[12:15]
	v_mfma_f32_16x16x32_bf16 v[8:11], v[170:173], v[202:205], v[8:11]
	v_mfma_f32_16x16x32_bf16 v[8:11], v[174:177], v[206:209], v[8:11]
	s_setprio 0
	s_barrier
	s_add_u32 s18, s18, 0x80080
	s_addc_u32 s19, s19, 0
	s_add_i32 s20, s20, s24
	v_lshl_add_u64 v[144:145], s[18:19], 0, v[132:133]
	s_mov_b32 m0, s20
	s_nop 0
	global_load_lds_dwordx4 v[144:145], off
	v_lshl_add_u64 v[144:145], s[18:19], 0, v[128:129]
	s_add_i32 m0, s20, 0x2000
	s_nop 0
	global_load_lds_dwordx4 v[144:145], off
	s_waitcnt vmcnt(6)
	s_barrier
	s_setprio 1
	v_mfma_f32_16x16x32_bf16 v[52:55], v[210:213], v[178:181], v[52:55]
	v_mfma_f32_16x16x32_bf16 v[52:55], v[214:217], v[182:185], v[52:55]
	v_mfma_f32_16x16x32_bf16 v[48:51], v[226:229], v[178:181], v[48:51]
	v_mfma_f32_16x16x32_bf16 v[48:51], v[230:233], v[182:185], v[48:51]
	v_mfma_f32_16x16x32_bf16 v[36:39], v[210:213], v[186:189], v[36:39]
	v_mfma_f32_16x16x32_bf16 v[36:39], v[214:217], v[190:193], v[36:39]
	v_mfma_f32_16x16x32_bf16 v[32:35], v[226:229], v[186:189], v[32:35]
	v_mfma_f32_16x16x32_bf16 v[32:35], v[230:233], v[190:193], v[32:35]
	v_mfma_f32_16x16x32_bf16 v[20:23], v[210:213], v[194:197], v[20:23]
	v_mfma_f32_16x16x32_bf16 v[20:23], v[214:217], v[198:201], v[20:23]
	v_mfma_f32_16x16x32_bf16 v[16:19], v[226:229], v[194:197], v[16:19]
	v_mfma_f32_16x16x32_bf16 v[16:19], v[230:233], v[198:201], v[16:19]
	v_mfma_f32_16x16x32_bf16 v[4:7], v[210:213], v[202:205], v[4:7]
	v_mfma_f32_16x16x32_bf16 v[4:7], v[214:217], v[206:209], v[4:7]
	v_mfma_f32_16x16x32_bf16 v[0:3], v[226:229], v[202:205], v[0:3]
	v_mfma_f32_16x16x32_bf16 v[0:3], v[230:233], v[206:209], v[0:3]
	s_setprio 0
	s_add_i32 s47, s47, 2
	s_add_u32 s16, s16, 0x100
	s_addc_u32 s17, s17, 0
	s_add_u32 s45, s45, 0x100
	s_addc_u32 s46, s46, 0
	s_cmp_gt_u32 s47, 29
	s_barrier
	s_cbranch_scc0 .LBB0_147
	v_lshl_add_u32 v144, s0, 8, v160
	v_ashrrev_i32_e32 v145, 31, v144
	v_lshl_add_u64 v[150:151], v[144:145], 2, s[92:93]
	global_load_dword v176, v[150:151], off
	global_load_dword v177, v[150:151], off offset:64
	global_load_dword v178, v[150:151], off offset:128
	global_load_dword v179, v[150:151], off offset:192
	global_load_dword v180, v[150:151], off offset:512
	global_load_dword v181, v[150:151], off offset:576
	global_load_dword v182, v[150:151], off offset:640
	global_load_dword v183, v[150:151], off offset:704
	v_lshl_or_b32 v148, s40, 8, v164
	v_mov_b64_e32 v[146:147], s[96:97]
	v_ashrrev_i32_e32 v149, 31, v148
	v_mad_i64_i32 v[172:173], s[16:17], v144, s39, v[146:147]
	v_lshlrev_b64 v[148:149], 1, v[148:149]
	v_lshl_add_u64 v[172:173], v[172:173], 0, v[148:149]
	s_and_b64 vcc, exec, s[4:5]
	s_mov_b32 s40, s8
	s_mov_b32 s0, s10
	s_mov_b64 s[18:19], s[14:15]
	s_waitcnt vmcnt(0)
	v_fmamk_f32 v145, v176, 0x3a000000, v168
	v_rsq_f32_e32 v170, v145
	s_nop 0
	v_pk_mul_f32 v[126:127], v[126:127], v[170:171] op_sel_hi:[1,0]
	v_pk_mul_f32 v[124:125], v[124:125], v[170:171] op_sel_hi:[1,0]
	v_pk_mul_f32 v[122:123], v[122:123], v[170:171] op_sel_hi:[1,0]
	v_pk_mul_f32 v[120:121], v[120:121], v[170:171] op_sel_hi:[1,0]
	v_pk_mul_f32 v[118:119], v[118:119], v[170:171] op_sel_hi:[1,0]
	v_pk_mul_f32 v[116:117], v[116:117], v[170:171] op_sel_hi:[1,0]
	v_pk_mul_f32 v[174:175], v[114:115], v[170:171] op_sel_hi:[1,0]
	v_pk_mul_f32 v[170:171], v[112:113], v[170:171] op_sel_hi:[1,0]
	v_cvt_pk_bf16_f32 v112, v124, v125
	v_cvt_pk_bf16_f32 v113, v126, v127
	v_cvt_pk_bf16_f32 v114, v120, v121
	v_cvt_pk_bf16_f32 v115, v122, v123
	global_store_dwordx4 v[172:173], v[112:115], off
	s_nop 1
	v_cvt_pk_bf16_f32 v112, v116, v117
	v_cvt_pk_bf16_f32 v113, v118, v119
	v_cvt_pk_bf16_f32 v114, v170, v171
	v_cvt_pk_bf16_f32 v115, v174, v175
	global_store_dwordx4 v[172:173], v[112:115], off offset:256
	s_nop 0
	s_nop 0
	v_or_b32_e32 v113, 16, v144
	v_mad_i64_i32 v[114:115], s[16:17], v113, s39, v[146:147]
	v_lshl_add_u64 v[114:115], v[114:115], 0, v[148:149]
	s_nop 0
	v_fmamk_f32 v112, v177, 0x3a000000, v168
	v_rsq_f32_e32 v112, v112
	s_nop 0
	v_pk_mul_f32 v[110:111], v[110:111], v[112:113] op_sel_hi:[1,0]
	v_pk_mul_f32 v[108:109], v[108:109], v[112:113] op_sel_hi:[1,0]
	v_pk_mul_f32 v[106:107], v[106:107], v[112:113] op_sel_hi:[1,0]
	v_pk_mul_f32 v[104:105], v[104:105], v[112:113] op_sel_hi:[1,0]
	v_pk_mul_f32 v[102:103], v[102:103], v[112:113] op_sel_hi:[1,0]
	v_pk_mul_f32 v[100:101], v[100:101], v[112:113] op_sel_hi:[1,0]
	v_pk_mul_f32 v[116:117], v[98:99], v[112:113] op_sel_hi:[1,0]
	v_pk_mul_f32 v[112:113], v[96:97], v[112:113] op_sel_hi:[1,0]
	v_cvt_pk_bf16_f32 v96, v108, v109
	v_cvt_pk_bf16_f32 v97, v110, v111
	v_cvt_pk_bf16_f32 v98, v104, v105
	v_cvt_pk_bf16_f32 v99, v106, v107
	global_store_dwordx4 v[114:115], v[96:99], off
	s_nop 1
	v_cvt_pk_bf16_f32 v96, v100, v101
	v_cvt_pk_bf16_f32 v97, v102, v103
	v_cvt_pk_bf16_f32 v98, v112, v113
	v_cvt_pk_bf16_f32 v99, v116, v117
	global_store_dwordx4 v[114:115], v[96:99], off offset:256
	s_nop 0
	s_nop 0
	v_or_b32_e32 v97, 32, v144
	v_mad_i64_i32 v[98:99], s[16:17], v97, s39, v[146:147]
	v_lshl_add_u64 v[98:99], v[98:99], 0, v[148:149]
	s_nop 0
	v_fmamk_f32 v96, v178, 0x3a000000, v168
	v_rsq_f32_e32 v96, v96
	s_nop 0
	v_pk_mul_f32 v[94:95], v[94:95], v[96:97] op_sel_hi:[1,0]
	v_pk_mul_f32 v[92:93], v[92:93], v[96:97] op_sel_hi:[1,0]
	v_pk_mul_f32 v[90:91], v[90:91], v[96:97] op_sel_hi:[1,0]
	v_pk_mul_f32 v[88:89], v[88:89], v[96:97] op_sel_hi:[1,0]
	v_pk_mul_f32 v[86:87], v[86:87], v[96:97] op_sel_hi:[1,0]
	v_pk_mul_f32 v[84:85], v[84:85], v[96:97] op_sel_hi:[1,0]
	v_pk_mul_f32 v[100:101], v[82:83], v[96:97] op_sel_hi:[1,0]
	v_pk_mul_f32 v[96:97], v[80:81], v[96:97] op_sel_hi:[1,0]
	v_cvt_pk_bf16_f32 v80, v92, v93
	v_cvt_pk_bf16_f32 v81, v94, v95
	v_cvt_pk_bf16_f32 v82, v88, v89
	v_cvt_pk_bf16_f32 v83, v90, v91
	global_store_dwordx4 v[98:99], v[80:83], off
	s_nop 1
	v_cvt_pk_bf16_f32 v80, v84, v85
	v_cvt_pk_bf16_f32 v81, v86, v87
	v_cvt_pk_bf16_f32 v82, v96, v97
	v_cvt_pk_bf16_f32 v83, v100, v101
	global_store_dwordx4 v[98:99], v[80:83], off offset:256
	s_nop 0
	s_nop 0
	v_or_b32_e32 v81, 48, v144
	v_mad_i64_i32 v[82:83], s[16:17], v81, s39, v[146:147]
	v_lshl_add_u64 v[82:83], v[82:83], 0, v[148:149]
	s_nop 0
	v_fmamk_f32 v80, v179, 0x3a000000, v168
	v_rsq_f32_e32 v80, v80
	s_nop 0
	v_pk_mul_f32 v[78:79], v[78:79], v[80:81] op_sel_hi:[1,0]
	v_pk_mul_f32 v[76:77], v[76:77], v[80:81] op_sel_hi:[1,0]
	v_pk_mul_f32 v[74:75], v[74:75], v[80:81] op_sel_hi:[1,0]
	v_pk_mul_f32 v[72:73], v[72:73], v[80:81] op_sel_hi:[1,0]
	v_pk_mul_f32 v[70:71], v[70:71], v[80:81] op_sel_hi:[1,0]
	v_pk_mul_f32 v[68:69], v[68:69], v[80:81] op_sel_hi:[1,0]
	v_pk_mul_f32 v[84:85], v[66:67], v[80:81] op_sel_hi:[1,0]
	v_pk_mul_f32 v[80:81], v[64:65], v[80:81] op_sel_hi:[1,0]
	v_cvt_pk_bf16_f32 v64, v76, v77
	v_cvt_pk_bf16_f32 v65, v78, v79
	v_cvt_pk_bf16_f32 v66, v72, v73
	v_cvt_pk_bf16_f32 v67, v74, v75
	global_store_dwordx4 v[82:83], v[64:67], off
	s_nop 1
	v_cvt_pk_bf16_f32 v64, v68, v69
	v_cvt_pk_bf16_f32 v65, v70, v71
	v_cvt_pk_bf16_f32 v66, v80, v81
	v_cvt_pk_bf16_f32 v67, v84, v85
	global_store_dwordx4 v[82:83], v[64:67], off offset:256
	s_nop 0
	s_nop 0
	v_add_u32_e32 v65, 0x80, v144
	v_mad_i64_i32 v[66:67], s[16:17], v65, s39, v[146:147]
	v_lshl_add_u64 v[66:67], v[66:67], 0, v[148:149]
	s_nop 0
	v_fmamk_f32 v64, v180, 0x3a000000, v168
	v_rsq_f32_e32 v64, v64
	s_nop 0
	v_pk_mul_f32 v[62:63], v[62:63], v[64:65] op_sel_hi:[1,0]
	v_pk_mul_f32 v[60:61], v[60:61], v[64:65] op_sel_hi:[1,0]
	v_pk_mul_f32 v[58:59], v[58:59], v[64:65] op_sel_hi:[1,0]
	v_pk_mul_f32 v[56:57], v[56:57], v[64:65] op_sel_hi:[1,0]
	v_pk_mul_f32 v[54:55], v[54:55], v[64:65] op_sel_hi:[1,0]
	v_pk_mul_f32 v[52:53], v[52:53], v[64:65] op_sel_hi:[1,0]
	v_pk_mul_f32 v[68:69], v[50:51], v[64:65] op_sel_hi:[1,0]
	v_pk_mul_f32 v[64:65], v[48:49], v[64:65] op_sel_hi:[1,0]
	v_cvt_pk_bf16_f32 v48, v60, v61
	v_cvt_pk_bf16_f32 v49, v62, v63
	v_cvt_pk_bf16_f32 v50, v56, v57
	v_cvt_pk_bf16_f32 v51, v58, v59
	global_store_dwordx4 v[66:67], v[48:51], off
	s_nop 1
	v_cvt_pk_bf16_f32 v48, v52, v53
	v_cvt_pk_bf16_f32 v49, v54, v55
	v_cvt_pk_bf16_f32 v50, v64, v65
	v_cvt_pk_bf16_f32 v51, v68, v69
	global_store_dwordx4 v[66:67], v[48:51], off offset:256
	s_nop 0
	s_nop 0
	v_add_u32_e32 v49, 0x90, v144
	v_mad_i64_i32 v[50:51], s[16:17], v49, s39, v[146:147]
	v_lshl_add_u64 v[50:51], v[50:51], 0, v[148:149]
	s_nop 0
	v_fmamk_f32 v48, v181, 0x3a000000, v168
	v_rsq_f32_e32 v48, v48
	s_nop 0
	v_pk_mul_f32 v[46:47], v[46:47], v[48:49] op_sel_hi:[1,0]
	v_pk_mul_f32 v[44:45], v[44:45], v[48:49] op_sel_hi:[1,0]
	v_pk_mul_f32 v[42:43], v[42:43], v[48:49] op_sel_hi:[1,0]
	v_pk_mul_f32 v[40:41], v[40:41], v[48:49] op_sel_hi:[1,0]
	v_pk_mul_f32 v[38:39], v[38:39], v[48:49] op_sel_hi:[1,0]
	v_pk_mul_f32 v[36:37], v[36:37], v[48:49] op_sel_hi:[1,0]
	v_pk_mul_f32 v[52:53], v[34:35], v[48:49] op_sel_hi:[1,0]
	v_pk_mul_f32 v[48:49], v[32:33], v[48:49] op_sel_hi:[1,0]
	v_cvt_pk_bf16_f32 v32, v44, v45
	v_cvt_pk_bf16_f32 v33, v46, v47
	v_cvt_pk_bf16_f32 v34, v40, v41
	v_cvt_pk_bf16_f32 v35, v42, v43
	global_store_dwordx4 v[50:51], v[32:35], off
	s_nop 1
	v_cvt_pk_bf16_f32 v32, v36, v37
	v_cvt_pk_bf16_f32 v33, v38, v39
	v_cvt_pk_bf16_f32 v34, v48, v49
	v_cvt_pk_bf16_f32 v35, v52, v53
	global_store_dwordx4 v[50:51], v[32:35], off offset:256
	s_nop 0
	s_nop 0
	v_add_u32_e32 v33, 0xa0, v144
	v_mad_i64_i32 v[34:35], s[16:17], v33, s39, v[146:147]
	v_lshl_add_u64 v[34:35], v[34:35], 0, v[148:149]
	s_mov_b64 s[16:17], s[12:13]
	s_nop 0
	v_fmamk_f32 v32, v182, 0x3a000000, v168
	v_rsq_f32_e32 v32, v32
	s_nop 0
	v_pk_mul_f32 v[30:31], v[30:31], v[32:33] op_sel_hi:[1,0]
	v_pk_mul_f32 v[28:29], v[28:29], v[32:33] op_sel_hi:[1,0]
	v_pk_mul_f32 v[26:27], v[26:27], v[32:33] op_sel_hi:[1,0]
	v_pk_mul_f32 v[24:25], v[24:25], v[32:33] op_sel_hi:[1,0]
	v_pk_mul_f32 v[22:23], v[22:23], v[32:33] op_sel_hi:[1,0]
	v_pk_mul_f32 v[20:21], v[20:21], v[32:33] op_sel_hi:[1,0]
	v_pk_mul_f32 v[36:37], v[18:19], v[32:33] op_sel_hi:[1,0]
	v_pk_mul_f32 v[32:33], v[16:17], v[32:33] op_sel_hi:[1,0]
	v_cvt_pk_bf16_f32 v16, v28, v29
	v_cvt_pk_bf16_f32 v17, v30, v31
	v_cvt_pk_bf16_f32 v18, v24, v25
	v_cvt_pk_bf16_f32 v19, v26, v27
	global_store_dwordx4 v[34:35], v[16:19], off
	s_nop 1
	v_cvt_pk_bf16_f32 v16, v20, v21
	v_cvt_pk_bf16_f32 v17, v22, v23
	v_cvt_pk_bf16_f32 v18, v32, v33
	v_cvt_pk_bf16_f32 v19, v36, v37
	global_store_dwordx4 v[34:35], v[16:19], off offset:256
	s_nop 0
	s_nop 0
	v_add_u32_e32 v17, 0xb0, v144
	v_mad_i64_i32 v[18:19], s[4:5], v17, s39, v[146:147]
	v_lshl_add_u64 v[18:19], v[18:19], 0, v[148:149]
	s_nop 0
	v_fmamk_f32 v16, v183, 0x3a000000, v168
	v_rsq_f32_e32 v16, v16
	s_nop 0
	v_pk_mul_f32 v[14:15], v[14:15], v[16:17] op_sel_hi:[1,0]
	v_pk_mul_f32 v[12:13], v[12:13], v[16:17] op_sel_hi:[1,0]
	v_pk_mul_f32 v[10:11], v[10:11], v[16:17] op_sel_hi:[1,0]
	v_pk_mul_f32 v[8:9], v[8:9], v[16:17] op_sel_hi:[1,0]
	v_pk_mul_f32 v[6:7], v[6:7], v[16:17] op_sel_hi:[1,0]
	v_pk_mul_f32 v[4:5], v[4:5], v[16:17] op_sel_hi:[1,0]
	v_pk_mul_f32 v[20:21], v[2:3], v[16:17] op_sel_hi:[1,0]
	v_pk_mul_f32 v[16:17], v[0:1], v[16:17] op_sel_hi:[1,0]
	v_cvt_pk_bf16_f32 v0, v12, v13
	v_cvt_pk_bf16_f32 v1, v14, v15
	v_cvt_pk_bf16_f32 v2, v8, v9
	v_cvt_pk_bf16_f32 v3, v10, v11
	global_store_dwordx4 v[18:19], v[0:3], off
	s_nop 1
	v_cvt_pk_bf16_f32 v0, v4, v5
	v_cvt_pk_bf16_f32 v1, v6, v7
	v_cvt_pk_bf16_f32 v2, v16, v17
	v_cvt_pk_bf16_f32 v3, v20, v21
	global_store_dwordx4 v[18:19], v[0:3], off offset:256
	s_cbranch_vccz .LBB0_144
	s_waitcnt vmcnt(0)
	s_cmpk_gt_u32 s3, 0xff
	s_cbranch_scc1 .LBB0_151
	s_barrier

.LBB0_283:
	ds_read_b128 v[140:143], v146
	v_xor_b32_e32 v171, 64, v146
	ds_read_b128 v[154:157], v171
	ds_read_b128 v[158:161], v146 offset:2048
	ds_read_b128 v[168:171], v171 offset:2048
	s_add_u32 s18, s6, 0xffe80080
	s_addc_u32 s19, s7, -1
	s_cmp_eq_u32 s45, 28
	s_cselect_b32 s21, s15, s19
	s_cselect_b32 s20, s14, s18
	s_cselect_b32 s19, s1, s44
	s_cselect_b32 s18, s11, s43
	v_lshl_add_u64 v[150:151], s[6:7], 0, v[132:133]
	s_add_i32 m0, s25, 0xc000
	ds_read_b128 v[172:175], v147
	v_xor_b32_e32 v203, 64, v147
	ds_read_b128 v[176:179], v203
	ds_read_b128 v[180:183], v147 offset:2048
	ds_read_b128 v[184:187], v203 offset:2048
	ds_read_b128 v[188:191], v147 offset:4096
	ds_read_b128 v[192:195], v203 offset:4096
	ds_read_b128 v[196:199], v147 offset:6144
	ds_read_b128 v[200:203], v203 offset:6144
	global_load_lds_dwordx4 v[150:151], off
	v_lshl_add_u64 v[150:151], s[6:7], 0, v[134:135]
	s_add_i32 m0, s25, 0xe000
	s_nop 0
	global_load_lds_dwordx4 v[150:151], off
	s_waitcnt lgkmcnt(8)
	s_barrier
	s_waitcnt lgkmcnt(0)
	s_setprio 1
	s_waitcnt lgkmcnt(0)
	v_mfma_f32_16x16x32_bf16 v[124:127], v[140:143], v[172:175], v[124:127]
	v_mfma_f32_16x16x32_bf16 v[124:127], v[154:157], v[176:179], v[124:127]
	v_mfma_f32_16x16x32_bf16 v[120:123], v[158:161], v[172:175], v[120:123]
	v_mfma_f32_16x16x32_bf16 v[120:123], v[168:171], v[176:179], v[120:123]
	v_mfma_f32_16x16x32_bf16 v[108:111], v[140:143], v[180:183], v[108:111]
	v_mfma_f32_16x16x32_bf16 v[108:111], v[154:157], v[184:187], v[108:111]
	v_mfma_f32_16x16x32_bf16 v[104:107], v[158:161], v[180:183], v[104:107]
	v_mfma_f32_16x16x32_bf16 v[104:107], v[168:171], v[184:187], v[104:107]
	v_mfma_f32_16x16x32_bf16 v[92:95], v[140:143], v[188:191], v[92:95]
	v_mfma_f32_16x16x32_bf16 v[92:95], v[154:157], v[192:195], v[92:95]
	v_mfma_f32_16x16x32_bf16 v[88:91], v[158:161], v[188:191], v[88:91]
	v_mfma_f32_16x16x32_bf16 v[88:91], v[168:171], v[192:195], v[88:91]
	v_mfma_f32_16x16x32_bf16 v[76:79], v[140:143], v[196:199], v[76:79]
	v_mfma_f32_16x16x32_bf16 v[76:79], v[154:157], v[200:203], v[76:79]
	v_mfma_f32_16x16x32_bf16 v[72:75], v[158:161], v[196:199], v[72:75]
	v_mfma_f32_16x16x32_bf16 v[72:75], v[168:171], v[200:203], v[72:75]
	s_setprio 0
	s_barrier
	s_add_i32 s46, s39, s24
	v_lshl_add_u64 v[150:151], s[18:19], 0, v[164:165]
	s_mov_b32 m0, s46
	ds_read_b128 v[204:207], v148
	v_xor_b32_e32 v245, 64, v148
	ds_read_b128 v[208:211], v245
	ds_read_b128 v[212:215], v148 offset:2048
	ds_read_b128 v[242:245], v245 offset:2048
	global_load_lds_dwordx4 v[150:151], off
	v_lshl_add_u64 v[216:217], s[18:19], 0, v[166:167]
	s_add_i32 m0, s46, 0x2000
	s_nop 0
	global_load_lds_dwordx4 v[216:217], off
	s_barrier
	s_waitcnt lgkmcnt(0)
	s_setprio 1
	s_waitcnt lgkmcnt(0)
	v_mfma_f32_16x16x32_bf16 v[116:119], v[204:207], v[172:175], v[116:119]
	v_mfma_f32_16x16x32_bf16 v[116:119], v[208:211], v[176:179], v[116:119]
	v_mfma_f32_16x16x32_bf16 v[112:115], v[212:215], v[172:175], v[112:115]
	v_mfma_f32_16x16x32_bf16 v[112:115], v[242:245], v[176:179], v[112:115]
	v_mfma_f32_16x16x32_bf16 v[100:103], v[204:207], v[180:183], v[100:103]
	v_mfma_f32_16x16x32_bf16 v[100:103], v[208:211], v[184:187], v[100:103]
	v_mfma_f32_16x16x32_bf16 v[96:99], v[212:215], v[180:183], v[96:99]
	v_mfma_f32_16x16x32_bf16 v[96:99], v[242:245], v[184:187], v[96:99]
	v_mfma_f32_16x16x32_bf16 v[84:87], v[204:207], v[188:191], v[84:87]
	v_mfma_f32_16x16x32_bf16 v[84:87], v[208:211], v[192:195], v[84:87]
	v_mfma_f32_16x16x32_bf16 v[80:83], v[212:215], v[188:191], v[80:83]
	v_mfma_f32_16x16x32_bf16 v[80:83], v[242:245], v[192:195], v[80:83]
	v_mfma_f32_16x16x32_bf16 v[68:71], v[204:207], v[196:199], v[68:71]
	v_mfma_f32_16x16x32_bf16 v[68:71], v[208:211], v[200:203], v[68:71]
	v_mfma_f32_16x16x32_bf16 v[64:67], v[212:215], v[196:199], v[64:67]
	v_mfma_f32_16x16x32_bf16 v[64:67], v[242:245], v[200:203], v[64:67]
	s_setprio 0
	s_mov_b32 m0, s25
	v_lshl_add_u64 v[220:221], s[20:21], 0, v[128:129]
	s_barrier
	ds_read_b128 v[172:175], v147 offset:16384
	v_xor_b32_e32 v203, 64, v147
	ds_read_b128 v[176:179], v203 offset:16384
	ds_read_b128 v[180:183], v147 offset:18432
	ds_read_b128 v[184:187], v203 offset:18432
	ds_read_b128 v[188:191], v147 offset:20480
	ds_read_b128 v[192:195], v203 offset:20480
	ds_read_b128 v[196:199], v147 offset:22528
	ds_read_b128 v[200:203], v203 offset:22528
	global_load_lds_dwordx4 v[220:221], off
	v_lshl_add_u64 v[230:231], s[20:21], 0, v[130:131]
	s_mov_b32 m0, s26
	s_nop 0
	global_load_lds_dwordx4 v[230:231], off
	s_barrier
	s_waitcnt lgkmcnt(0)
	s_setprio 1
	s_waitcnt lgkmcnt(0)
	v_mfma_f32_16x16x32_bf16 v[60:63], v[140:143], v[172:175], v[60:63]
	v_mfma_f32_16x16x32_bf16 v[60:63], v[154:157], v[176:179], v[60:63]
	v_mfma_f32_16x16x32_bf16 v[56:59], v[158:161], v[172:175], v[56:59]
	v_mfma_f32_16x16x32_bf16 v[56:59], v[168:171], v[176:179], v[56:59]
	v_mfma_f32_16x16x32_bf16 v[44:47], v[140:143], v[180:183], v[44:47]
	v_mfma_f32_16x16x32_bf16 v[44:47], v[154:157], v[184:187], v[44:47]
	v_mfma_f32_16x16x32_bf16 v[40:43], v[158:161], v[180:183], v[40:43]
	v_mfma_f32_16x16x32_bf16 v[40:43], v[168:171], v[184:187], v[40:43]
	v_mfma_f32_16x16x32_bf16 v[28:31], v[140:143], v[188:191], v[28:31]
	v_mfma_f32_16x16x32_bf16 v[28:31], v[154:157], v[192:195], v[28:31]
	v_mfma_f32_16x16x32_bf16 v[24:27], v[158:161], v[188:191], v[24:27]
	v_mfma_f32_16x16x32_bf16 v[24:27], v[168:171], v[192:195], v[24:27]
	v_mfma_f32_16x16x32_bf16 v[12:15], v[140:143], v[196:199], v[12:15]
	v_mfma_f32_16x16x32_bf16 v[12:15], v[154:157], v[200:203], v[12:15]
	v_mfma_f32_16x16x32_bf16 v[8:11], v[158:161], v[196:199], v[8:11]
	v_mfma_f32_16x16x32_bf16 v[8:11], v[168:171], v[200:203], v[8:11]
	s_setprio 0
	s_barrier
	s_add_u32 s46, s18, 0x80000
	s_addc_u32 s47, s19, 0
	s_add_i32 s48, s40, s24
	v_lshl_add_u64 v[140:141], s[46:47], 0, v[164:165]
	s_mov_b32 m0, s48
	s_nop 0
	global_load_lds_dwordx4 v[140:141], off
	v_lshl_add_u64 v[140:141], s[46:47], 0, v[166:167]
	s_add_i32 m0, s48, 0x2000
	s_nop 0
	global_load_lds_dwordx4 v[140:141], off
	s_waitcnt vmcnt(6)
	s_barrier
	s_setprio 1
	v_mfma_f32_16x16x32_bf16 v[52:55], v[204:207], v[172:175], v[52:55]
	v_mfma_f32_16x16x32_bf16 v[52:55], v[208:211], v[176:179], v[52:55]
	v_mfma_f32_16x16x32_bf16 v[48:51], v[212:215], v[172:175], v[48:51]
	v_mfma_f32_16x16x32_bf16 v[48:51], v[242:245], v[176:179], v[48:51]
	v_mfma_f32_16x16x32_bf16 v[36:39], v[204:207], v[180:183], v[36:39]
	v_mfma_f32_16x16x32_bf16 v[36:39], v[208:211], v[184:187], v[36:39]
	v_mfma_f32_16x16x32_bf16 v[32:35], v[212:215], v[180:183], v[32:35]
	v_mfma_f32_16x16x32_bf16 v[32:35], v[242:245], v[184:187], v[32:35]
	v_mfma_f32_16x16x32_bf16 v[20:23], v[204:207], v[188:191], v[20:23]
	v_mfma_f32_16x16x32_bf16 v[20:23], v[208:211], v[192:195], v[20:23]
	v_mfma_f32_16x16x32_bf16 v[16:19], v[212:215], v[188:191], v[16:19]
	v_mfma_f32_16x16x32_bf16 v[16:19], v[242:245], v[192:195], v[16:19]
	v_mfma_f32_16x16x32_bf16 v[4:7], v[204:207], v[196:199], v[4:7]
	v_mfma_f32_16x16x32_bf16 v[4:7], v[208:211], v[200:203], v[4:7]
	v_mfma_f32_16x16x32_bf16 v[0:3], v[212:215], v[196:199], v[0:3]
	v_mfma_f32_16x16x32_bf16 v[0:3], v[242:245], v[200:203], v[0:3]
	s_setprio 0
	s_add_i32 s46, 0, 0x18000
	v_add_u32_e32 v168, s46, v145
	s_barrier
	ds_read_b128 v[140:143], v168
	v_xor_b32_e32 v171, 64, v168
	ds_read_b128 v[154:157], v171
	ds_read_b128 v[158:161], v168 offset:2048
	ds_read_b128 v[168:171], v171 offset:2048
	s_add_u32 s20, s20, 0x180000
	s_addc_u32 s21, s21, 0
	s_mov_b32 m0, s27
	v_lshl_add_u64 v[204:205], s[20:21], 0, v[128:129]
	ds_read_b128 v[172:175], v147 offset:32768
	v_xor_b32_e32 v203, 64, v147
	ds_read_b128 v[176:179], v203 offset:32768
	ds_read_b128 v[180:183], v147 offset:34816
	ds_read_b128 v[184:187], v203 offset:34816
	ds_read_b128 v[188:191], v147 offset:36864
	ds_read_b128 v[192:195], v203 offset:36864
	ds_read_b128 v[196:199], v147 offset:38912
	ds_read_b128 v[200:203], v203 offset:38912
	global_load_lds_dwordx4 v[204:205], off
	v_lshl_add_u64 v[204:205], s[20:21], 0, v[130:131]
	s_mov_b32 m0, s28
	s_nop 0
	global_load_lds_dwordx4 v[204:205], off
	s_waitcnt lgkmcnt(8)
	s_barrier
	s_waitcnt lgkmcnt(0)
	s_setprio 1
	s_waitcnt lgkmcnt(0)
	v_mfma_f32_16x16x32_bf16 v[124:127], v[140:143], v[172:175], v[124:127]
	v_mfma_f32_16x16x32_bf16 v[124:127], v[154:157], v[176:179], v[124:127]
	v_mfma_f32_16x16x32_bf16 v[120:123], v[158:161], v[172:175], v[120:123]
	v_mfma_f32_16x16x32_bf16 v[120:123], v[168:171], v[176:179], v[120:123]
	v_mfma_f32_16x16x32_bf16 v[108:111], v[140:143], v[180:183], v[108:111]
	v_mfma_f32_16x16x32_bf16 v[108:111], v[154:157], v[184:187], v[108:111]
	v_mfma_f32_16x16x32_bf16 v[104:107], v[158:161], v[180:183], v[104:107]
	v_mfma_f32_16x16x32_bf16 v[104:107], v[168:171], v[184:187], v[104:107]
	v_mfma_f32_16x16x32_bf16 v[92:95], v[140:143], v[188:191], v[92:95]
	v_mfma_f32_16x16x32_bf16 v[92:95], v[154:157], v[192:195], v[92:95]
	v_mfma_f32_16x16x32_bf16 v[88:91], v[158:161], v[188:191], v[88:91]
	v_mfma_f32_16x16x32_bf16 v[88:91], v[168:171], v[192:195], v[88:91]
	v_mfma_f32_16x16x32_bf16 v[76:79], v[140:143], v[196:199], v[76:79]
	v_mfma_f32_16x16x32_bf16 v[76:79], v[154:157], v[200:203], v[76:79]
	v_mfma_f32_16x16x32_bf16 v[72:75], v[158:161], v[196:199], v[72:75]
	v_mfma_f32_16x16x32_bf16 v[72:75], v[168:171], v[200:203], v[72:75]
	s_setprio 0
	s_barrier
	s_add_i32 s20, 0, 0x1c000
	s_add_i32 s21, s46, s24
	v_add_u32_e32 v223, s20, v145
	v_lshl_add_u64 v[150:151], v[150:151], 0, s[8:9]
	s_mov_b32 m0, s21
	ds_read_b128 v[204:207], v223
	v_xor_b32_e32 v245, 64, v223
	ds_read_b128 v[208:211], v245
	ds_read_b128 v[212:215], v223 offset:2048
	ds_read_b128 v[242:245], v245 offset:2048
	global_load_lds_dwordx4 v[150:151], off
	v_lshl_add_u64 v[150:151], v[216:217], 0, s[8:9]
	s_add_i32 m0, s21, 0x2000
	s_nop 0
	global_load_lds_dwordx4 v[150:151], off
	s_barrier
	s_waitcnt lgkmcnt(0)
	s_setprio 1
	s_waitcnt lgkmcnt(0)
	v_mfma_f32_16x16x32_bf16 v[116:119], v[204:207], v[172:175], v[116:119]
	v_mfma_f32_16x16x32_bf16 v[116:119], v[208:211], v[176:179], v[116:119]
	v_mfma_f32_16x16x32_bf16 v[112:115], v[212:215], v[172:175], v[112:115]
	v_mfma_f32_16x16x32_bf16 v[112:115], v[242:245], v[176:179], v[112:115]
	v_mfma_f32_16x16x32_bf16 v[100:103], v[204:207], v[180:183], v[100:103]
	v_mfma_f32_16x16x32_bf16 v[100:103], v[208:211], v[184:187], v[100:103]
	v_mfma_f32_16x16x32_bf16 v[96:99], v[212:215], v[180:183], v[96:99]
	v_mfma_f32_16x16x32_bf16 v[96:99], v[242:245], v[184:187], v[96:99]
	v_mfma_f32_16x16x32_bf16 v[84:87], v[204:207], v[188:191], v[84:87]
	v_mfma_f32_16x16x32_bf16 v[84:87], v[208:211], v[192:195], v[84:87]
	v_mfma_f32_16x16x32_bf16 v[80:83], v[212:215], v[188:191], v[80:83]
	v_mfma_f32_16x16x32_bf16 v[80:83], v[242:245], v[192:195], v[80:83]
	v_mfma_f32_16x16x32_bf16 v[68:71], v[204:207], v[196:199], v[68:71]
	v_mfma_f32_16x16x32_bf16 v[68:71], v[208:211], v[200:203], v[68:71]
	v_mfma_f32_16x16x32_bf16 v[64:67], v[212:215], v[196:199], v[64:67]
	v_mfma_f32_16x16x32_bf16 v[64:67], v[242:245], v[200:203], v[64:67]
	s_setprio 0
	s_mov_b32 m0, s33
	v_lshl_add_u64 v[150:151], v[220:221], 0, s[8:9]
	s_barrier
	ds_read_b128 v[172:175], v147 offset:49152
	v_xor_b32_e32 v203, 64, v147
	ds_read_b128 v[176:179], v203 offset:49152
	ds_read_b128 v[180:183], v147 offset:51200
	ds_read_b128 v[184:187], v203 offset:51200
	ds_read_b128 v[188:191], v147 offset:53248
	ds_read_b128 v[192:195], v203 offset:53248
	ds_read_b128 v[196:199], v147 offset:55296
	ds_read_b128 v[200:203], v203 offset:55296
	global_load_lds_dwordx4 v[150:151], off
	v_lshl_add_u64 v[150:151], v[230:231], 0, s[8:9]
	s_mov_b32 m0, s34
	s_nop 0
	global_load_lds_dwordx4 v[150:151], off
	s_barrier
	s_waitcnt lgkmcnt(0)
	s_setprio 1
	s_waitcnt lgkmcnt(0)
	v_mfma_f32_16x16x32_bf16 v[60:63], v[140:143], v[172:175], v[60:63]
	v_mfma_f32_16x16x32_bf16 v[60:63], v[154:157], v[176:179], v[60:63]
	v_mfma_f32_16x16x32_bf16 v[56:59], v[158:161], v[172:175], v[56:59]
	v_mfma_f32_16x16x32_bf16 v[56:59], v[168:171], v[176:179], v[56:59]
	v_mfma_f32_16x16x32_bf16 v[44:47], v[140:143], v[180:183], v[44:47]
	v_mfma_f32_16x16x32_bf16 v[44:47], v[154:157], v[184:187], v[44:47]
	v_mfma_f32_16x16x32_bf16 v[40:43], v[158:161], v[180:183], v[40:43]
	v_mfma_f32_16x16x32_bf16 v[40:43], v[168:171], v[184:187], v[40:43]
	v_mfma_f32_16x16x32_bf16 v[28:31], v[140:143], v[188:191], v[28:31]
	v_mfma_f32_16x16x32_bf16 v[28:31], v[154:157], v[192:195], v[28:31]
	v_mfma_f32_16x16x32_bf16 v[24:27], v[158:161], v[188:191], v[24:27]
	v_mfma_f32_16x16x32_bf16 v[24:27], v[168:171], v[192:195], v[24:27]
	v_mfma_f32_16x16x32_bf16 v[12:15], v[140:143], v[196:199], v[12:15]
	v_mfma_f32_16x16x32_bf16 v[12:15], v[154:157], v[200:203], v[12:15]
	v_mfma_f32_16x16x32_bf16 v[8:11], v[158:161], v[196:199], v[8:11]
	v_mfma_f32_16x16x32_bf16 v[8:11], v[168:171], v[200:203], v[8:11]
	s_setprio 0
	s_barrier
	s_add_u32 s18, s18, 0x80080
	s_addc_u32 s19, s19, 0
	s_add_i32 s20, s20, s24
	v_lshl_add_u64 v[140:141], s[18:19], 0, v[164:165]
	s_mov_b32 m0, s20
	s_nop 0
	global_load_lds_dwordx4 v[140:141], off
	v_lshl_add_u64 v[140:141], s[18:19], 0, v[166:167]
	s_add_i32 m0, s20, 0x2000
	s_nop 0
	global_load_lds_dwordx4 v[140:141], off
	s_waitcnt vmcnt(6)
	s_barrier
	s_setprio 1
	v_mfma_f32_16x16x32_bf16 v[52:55], v[204:207], v[172:175], v[52:55]
	v_mfma_f32_16x16x32_bf16 v[52:55], v[208:211], v[176:179], v[52:55]
	v_mfma_f32_16x16x32_bf16 v[48:51], v[212:215], v[172:175], v[48:51]
	v_mfma_f32_16x16x32_bf16 v[48:51], v[242:245], v[176:179], v[48:51]
	v_mfma_f32_16x16x32_bf16 v[36:39], v[204:207], v[180:183], v[36:39]
	v_mfma_f32_16x16x32_bf16 v[36:39], v[208:211], v[184:187], v[36:39]
	v_mfma_f32_16x16x32_bf16 v[32:35], v[212:215], v[180:183], v[32:35]
	v_mfma_f32_16x16x32_bf16 v[32:35], v[242:245], v[184:187], v[32:35]
	v_mfma_f32_16x16x32_bf16 v[20:23], v[204:207], v[188:191], v[20:23]
	v_mfma_f32_16x16x32_bf16 v[20:23], v[208:211], v[192:195], v[20:23]
	v_mfma_f32_16x16x32_bf16 v[16:19], v[212:215], v[188:191], v[16:19]
	v_mfma_f32_16x16x32_bf16 v[16:19], v[242:245], v[192:195], v[16:19]
	v_mfma_f32_16x16x32_bf16 v[4:7], v[204:207], v[196:199], v[4:7]
	v_mfma_f32_16x16x32_bf16 v[4:7], v[208:211], v[200:203], v[4:7]
	v_mfma_f32_16x16x32_bf16 v[0:3], v[212:215], v[196:199], v[0:3]
	v_mfma_f32_16x16x32_bf16 v[0:3], v[242:245], v[200:203], v[0:3]
	s_setprio 0
	s_add_i32 s45, s45, 2
	s_add_u32 s6, s6, 0x100
	s_addc_u32 s7, s7, 0
	s_add_u32 s43, s43, 0x100
	s_addc_u32 s44, s44, 0
	s_cmp_gt_u32 s45, 29
	s_barrier
	s_cbranch_scc0 .LBB0_283
	v_lshl_add_u32 v217, s42, 8, v163
	v_add_u32_e32 v217, s30, v217
	v_lshlrev_b32_e32 v208, 2, v217
	v_lshl_add_u32 v214, v225, 3, s31
	v_lshl_add_u32 v214, s0, 8, v214
	v_lshl_add_u32 v209, v217, 11, v214
	v_lshlrev_b32_e32 v209, 1, v209
	v_lshlrev_b32_e32 v210, 1, v209
	v_lshl_add_u32 v217, v225, 4, v163
	v_xor_b32_e32 v215, 16, v217
	v_lshlrev_b32_e32 v215, 2, v215
	v_xor_b32_e32 v216, 32, v217
	v_lshlrev_b32_e32 v216, 2, v216
	v_add_u32_e32 v212, 0x0, v210
	global_load_dwordx4 v[176:179], v212, s[36:37]
	global_load_dwordx4 v[180:183], v212, s[36:37] offset:16
	global_load_dwordx4 v[184:187], v212, s[36:37] offset:512
	global_load_dwordx4 v[188:191], v212, s[36:37] offset:528
	v_add_u32_e32 v212, 0x20000, v210
	global_load_dwordx4 v[192:195], v212, s[36:37]
	global_load_dwordx4 v[196:199], v212, s[36:37] offset:16
	global_load_dwordx4 v[200:203], v212, s[36:37] offset:512
	global_load_dwordx4 v[204:207], v212, s[36:37] offset:528
	s_waitcnt vmcnt(4)
	v_pk_add_f32 v[124:125], v[124:125], v[176:177]
	v_pk_add_f32 v[126:127], v[126:127], v[178:179]
	v_pk_add_f32 v[120:121], v[120:121], v[180:181]
	v_pk_add_f32 v[122:123], v[122:123], v[182:183]
	v_mul_f32_e32 v213, v124, v124
	v_fmac_f32_e32 v213, v125, v125
	v_fmac_f32_e32 v213, v126, v126
	v_fmac_f32_e32 v213, v127, v127
	v_fmac_f32_e32 v213, v120, v120
	v_fmac_f32_e32 v213, v121, v121
	v_fmac_f32_e32 v213, v122, v122
	v_fmac_f32_e32 v213, v123, v123
	v_cvt_pk_bf16_f32 v176, v124, v125
	v_cvt_pk_bf16_f32 v177, v126, v127
	v_cvt_pk_bf16_f32 v178, v120, v121
	v_cvt_pk_bf16_f32 v179, v122, v123
	v_add_u32_e32 v217, 0x0, v209
	global_store_dwordx4 v217, v[176:179], s[80:81]
	v_pk_add_f32 v[116:117], v[116:117], v[184:185]
	v_pk_add_f32 v[118:119], v[118:119], v[186:187]
	v_pk_add_f32 v[112:113], v[112:113], v[188:189]
	v_pk_add_f32 v[114:115], v[114:115], v[190:191]
	v_fmac_f32_e32 v213, v116, v116
	v_fmac_f32_e32 v213, v117, v117
	v_fmac_f32_e32 v213, v118, v118
	v_fmac_f32_e32 v213, v119, v119
	v_fmac_f32_e32 v213, v112, v112
	v_fmac_f32_e32 v213, v113, v113
	v_fmac_f32_e32 v213, v114, v114
	v_fmac_f32_e32 v213, v115, v115
	v_cvt_pk_bf16_f32 v184, v116, v117
	v_cvt_pk_bf16_f32 v185, v118, v119
	v_cvt_pk_bf16_f32 v186, v112, v113
	v_cvt_pk_bf16_f32 v187, v114, v115
	global_store_dwordx4 v217, v[184:187], s[80:81] offset:256
	ds_bpermute_b32 v214, v215, v213
	s_waitcnt lgkmcnt(0)
	v_add_f32_e32 v213, v213, v214
	ds_bpermute_b32 v214, v216, v213
	s_waitcnt lgkmcnt(0)
	v_add_f32_e32 v213, v213, v214
	s_mov_b64 exec, 0xffff
	global_atomic_add_f32 v208, v213, s[12:13]
	s_mov_b64 exec, -1
	v_add_u32_e32 v212, 0x40000, v210
	global_load_dwordx4 v[176:179], v212, s[36:37]
	global_load_dwordx4 v[180:183], v212, s[36:37] offset:16
	global_load_dwordx4 v[184:187], v212, s[36:37] offset:512
	global_load_dwordx4 v[188:191], v212, s[36:37] offset:528
	s_waitcnt vmcnt(7)
	v_pk_add_f32 v[108:109], v[108:109], v[192:193]
	v_pk_add_f32 v[110:111], v[110:111], v[194:195]
	v_pk_add_f32 v[104:105], v[104:105], v[196:197]
	v_pk_add_f32 v[106:107], v[106:107], v[198:199]
	v_mul_f32_e32 v213, v108, v108
	v_fmac_f32_e32 v213, v109, v109
	v_fmac_f32_e32 v213, v110, v110
	v_fmac_f32_e32 v213, v111, v111
	v_fmac_f32_e32 v213, v104, v104
	v_fmac_f32_e32 v213, v105, v105
	v_fmac_f32_e32 v213, v106, v106
	v_fmac_f32_e32 v213, v107, v107
	v_cvt_pk_bf16_f32 v192, v108, v109
	v_cvt_pk_bf16_f32 v193, v110, v111
	v_cvt_pk_bf16_f32 v194, v104, v105
	v_cvt_pk_bf16_f32 v195, v106, v107
	v_add_u32_e32 v217, 0x10000, v209
	global_store_dwordx4 v217, v[192:195], s[80:81]
	v_pk_add_f32 v[100:101], v[100:101], v[200:201]
	v_pk_add_f32 v[102:103], v[102:103], v[202:203]
	v_pk_add_f32 v[96:97], v[96:97], v[204:205]
	v_pk_add_f32 v[98:99], v[98:99], v[206:207]
	v_fmac_f32_e32 v213, v100, v100
	v_fmac_f32_e32 v213, v101, v101
	v_fmac_f32_e32 v213, v102, v102
	v_fmac_f32_e32 v213, v103, v103
	v_fmac_f32_e32 v213, v96, v96
	v_fmac_f32_e32 v213, v97, v97
	v_fmac_f32_e32 v213, v98, v98
	v_fmac_f32_e32 v213, v99, v99
	v_cvt_pk_bf16_f32 v200, v100, v101
	v_cvt_pk_bf16_f32 v201, v102, v103
	v_cvt_pk_bf16_f32 v202, v96, v97
	v_cvt_pk_bf16_f32 v203, v98, v99
	global_store_dwordx4 v217, v[200:203], s[80:81] offset:256
	ds_bpermute_b32 v214, v215, v213
	s_waitcnt lgkmcnt(0)
	v_add_f32_e32 v213, v213, v214
	ds_bpermute_b32 v214, v216, v213
	s_waitcnt lgkmcnt(0)
	v_add_f32_e32 v213, v213, v214
	s_mov_b64 exec, 0xffff
	global_atomic_add_f32 v208, v213, s[12:13] offset:64
	s_mov_b64 exec, -1
	v_add_u32_e32 v212, 0x60000, v210
	global_load_dwordx4 v[192:195], v212, s[36:37]
	global_load_dwordx4 v[196:199], v212, s[36:37] offset:16
	global_load_dwordx4 v[200:203], v212, s[36:37] offset:512
	global_load_dwordx4 v[204:207], v212, s[36:37] offset:528
	s_waitcnt vmcnt(7)
	v_pk_add_f32 v[92:93], v[92:93], v[176:177]
	v_pk_add_f32 v[94:95], v[94:95], v[178:179]
	v_pk_add_f32 v[88:89], v[88:89], v[180:181]
	v_pk_add_f32 v[90:91], v[90:91], v[182:183]
	v_mul_f32_e32 v213, v92, v92
	v_fmac_f32_e32 v213, v93, v93
	v_fmac_f32_e32 v213, v94, v94
	v_fmac_f32_e32 v213, v95, v95
	v_fmac_f32_e32 v213, v88, v88
	v_fmac_f32_e32 v213, v89, v89
	v_fmac_f32_e32 v213, v90, v90
	v_fmac_f32_e32 v213, v91, v91
	v_cvt_pk_bf16_f32 v176, v92, v93
	v_cvt_pk_bf16_f32 v177, v94, v95
	v_cvt_pk_bf16_f32 v178, v88, v89
	v_cvt_pk_bf16_f32 v179, v90, v91
	v_add_u32_e32 v217, 0x20000, v209
	global_store_dwordx4 v217, v[176:179], s[80:81]
	v_pk_add_f32 v[84:85], v[84:85], v[184:185]
	v_pk_add_f32 v[86:87], v[86:87], v[186:187]
	v_pk_add_f32 v[80:81], v[80:81], v[188:189]
	v_pk_add_f32 v[82:83], v[82:83], v[190:191]
	v_fmac_f32_e32 v213, v84, v84
	v_fmac_f32_e32 v213, v85, v85
	v_fmac_f32_e32 v213, v86, v86
	v_fmac_f32_e32 v213, v87, v87
	v_fmac_f32_e32 v213, v80, v80
	v_fmac_f32_e32 v213, v81, v81
	v_fmac_f32_e32 v213, v82, v82
	v_fmac_f32_e32 v213, v83, v83
	v_cvt_pk_bf16_f32 v184, v84, v85
	v_cvt_pk_bf16_f32 v185, v86, v87
	v_cvt_pk_bf16_f32 v186, v80, v81
	v_cvt_pk_bf16_f32 v187, v82, v83
	global_store_dwordx4 v217, v[184:187], s[80:81] offset:256
	ds_bpermute_b32 v214, v215, v213
	s_waitcnt lgkmcnt(0)
	v_add_f32_e32 v213, v213, v214
	ds_bpermute_b32 v214, v216, v213
	s_waitcnt lgkmcnt(0)
	v_add_f32_e32 v213, v213, v214
	s_mov_b64 exec, 0xffff
	global_atomic_add_f32 v208, v213, s[12:13] offset:128
	s_mov_b64 exec, -1
	v_add_u32_e32 v212, 0x100000, v210
	global_load_dwordx4 v[176:179], v212, s[36:37]
	global_load_dwordx4 v[180:183], v212, s[36:37] offset:16
	global_load_dwordx4 v[184:187], v212, s[36:37] offset:512
	global_load_dwordx4 v[188:191], v212, s[36:37] offset:528
	s_waitcnt vmcnt(7)
	v_pk_add_f32 v[76:77], v[76:77], v[192:193]
	v_pk_add_f32 v[78:79], v[78:79], v[194:195]
	v_pk_add_f32 v[72:73], v[72:73], v[196:197]
	v_pk_add_f32 v[74:75], v[74:75], v[198:199]
	v_mul_f32_e32 v213, v76, v76
	v_fmac_f32_e32 v213, v77, v77
	v_fmac_f32_e32 v213, v78, v78
	v_fmac_f32_e32 v213, v79, v79
	v_fmac_f32_e32 v213, v72, v72
	v_fmac_f32_e32 v213, v73, v73
	v_fmac_f32_e32 v213, v74, v74
	v_fmac_f32_e32 v213, v75, v75
	v_cvt_pk_bf16_f32 v192, v76, v77
	v_cvt_pk_bf16_f32 v193, v78, v79
	v_cvt_pk_bf16_f32 v194, v72, v73
	v_cvt_pk_bf16_f32 v195, v74, v75
	v_add_u32_e32 v217, 0x30000, v209
	global_store_dwordx4 v217, v[192:195], s[80:81]
	v_pk_add_f32 v[68:69], v[68:69], v[200:201]
	v_pk_add_f32 v[70:71], v[70:71], v[202:203]
	v_pk_add_f32 v[64:65], v[64:65], v[204:205]
	v_pk_add_f32 v[66:67], v[66:67], v[206:207]
	v_fmac_f32_e32 v213, v68, v68
	v_fmac_f32_e32 v213, v69, v69
	v_fmac_f32_e32 v213, v70, v70
	v_fmac_f32_e32 v213, v71, v71
	v_fmac_f32_e32 v213, v64, v64
	v_fmac_f32_e32 v213, v65, v65
	v_fmac_f32_e32 v213, v66, v66
	v_fmac_f32_e32 v213, v67, v67
	v_cvt_pk_bf16_f32 v200, v68, v69
	v_cvt_pk_bf16_f32 v201, v70, v71
	v_cvt_pk_bf16_f32 v202, v64, v65
	v_cvt_pk_bf16_f32 v203, v66, v67
	global_store_dwordx4 v217, v[200:203], s[80:81] offset:256
	ds_bpermute_b32 v214, v215, v213
	s_waitcnt lgkmcnt(0)
	v_add_f32_e32 v213, v213, v214
	ds_bpermute_b32 v214, v216, v213
	s_waitcnt lgkmcnt(0)
	v_add_f32_e32 v213, v213, v214
	s_mov_b64 exec, 0xffff
	global_atomic_add_f32 v208, v213, s[12:13] offset:192
	s_mov_b64 exec, -1
	v_add_u32_e32 v212, 0x120000, v210
	global_load_dwordx4 v[192:195], v212, s[36:37]
	global_load_dwordx4 v[196:199], v212, s[36:37] offset:16
	global_load_dwordx4 v[200:203], v212, s[36:37] offset:512
	global_load_dwordx4 v[204:207], v212, s[36:37] offset:528
	s_waitcnt vmcnt(7)
	v_pk_add_f32 v[60:61], v[60:61], v[176:177]
	v_pk_add_f32 v[62:63], v[62:63], v[178:179]
	v_pk_add_f32 v[56:57], v[56:57], v[180:181]
	v_pk_add_f32 v[58:59], v[58:59], v[182:183]
	v_mul_f32_e32 v213, v60, v60
	v_fmac_f32_e32 v213, v61, v61
	v_fmac_f32_e32 v213, v62, v62
	v_fmac_f32_e32 v213, v63, v63
	v_fmac_f32_e32 v213, v56, v56
	v_fmac_f32_e32 v213, v57, v57
	v_fmac_f32_e32 v213, v58, v58
	v_fmac_f32_e32 v213, v59, v59
	v_cvt_pk_bf16_f32 v176, v60, v61
	v_cvt_pk_bf16_f32 v177, v62, v63
	v_cvt_pk_bf16_f32 v178, v56, v57
	v_cvt_pk_bf16_f32 v179, v58, v59
	v_add_u32_e32 v217, 0x80000, v209
	global_store_dwordx4 v217, v[176:179], s[80:81]
	v_pk_add_f32 v[52:53], v[52:53], v[184:185]
	v_pk_add_f32 v[54:55], v[54:55], v[186:187]
	v_pk_add_f32 v[48:49], v[48:49], v[188:189]
	v_pk_add_f32 v[50:51], v[50:51], v[190:191]
	v_fmac_f32_e32 v213, v52, v52
	v_fmac_f32_e32 v213, v53, v53
	v_fmac_f32_e32 v213, v54, v54
	v_fmac_f32_e32 v213, v55, v55
	v_fmac_f32_e32 v213, v48, v48
	v_fmac_f32_e32 v213, v49, v49
	v_fmac_f32_e32 v213, v50, v50
	v_fmac_f32_e32 v213, v51, v51
	v_cvt_pk_bf16_f32 v184, v52, v53
	v_cvt_pk_bf16_f32 v185, v54, v55
	v_cvt_pk_bf16_f32 v186, v48, v49
	v_cvt_pk_bf16_f32 v187, v50, v51
	global_store_dwordx4 v217, v[184:187], s[80:81] offset:256
	ds_bpermute_b32 v214, v215, v213
	s_waitcnt lgkmcnt(0)
	v_add_f32_e32 v213, v213, v214
	ds_bpermute_b32 v214, v216, v213
	s_waitcnt lgkmcnt(0)
	v_add_f32_e32 v213, v213, v214
	s_mov_b64 exec, 0xffff
	global_atomic_add_f32 v208, v213, s[12:13] offset:512
	s_mov_b64 exec, -1
	v_add_u32_e32 v212, 0x140000, v210
	global_load_dwordx4 v[176:179], v212, s[36:37]
	global_load_dwordx4 v[180:183], v212, s[36:37] offset:16
	global_load_dwordx4 v[184:187], v212, s[36:37] offset:512
	global_load_dwordx4 v[188:191], v212, s[36:37] offset:528
	s_waitcnt vmcnt(7)
	v_pk_add_f32 v[44:45], v[44:45], v[192:193]
	v_pk_add_f32 v[46:47], v[46:47], v[194:195]
	v_pk_add_f32 v[40:41], v[40:41], v[196:197]
	v_pk_add_f32 v[42:43], v[42:43], v[198:199]
	v_mul_f32_e32 v213, v44, v44
	v_fmac_f32_e32 v213, v45, v45
	v_fmac_f32_e32 v213, v46, v46
	v_fmac_f32_e32 v213, v47, v47
	v_fmac_f32_e32 v213, v40, v40
	v_fmac_f32_e32 v213, v41, v41
	v_fmac_f32_e32 v213, v42, v42
	v_fmac_f32_e32 v213, v43, v43
	v_cvt_pk_bf16_f32 v192, v44, v45
	v_cvt_pk_bf16_f32 v193, v46, v47
	v_cvt_pk_bf16_f32 v194, v40, v41
	v_cvt_pk_bf16_f32 v195, v42, v43
	v_add_u32_e32 v217, 0x90000, v209
	global_store_dwordx4 v217, v[192:195], s[80:81]
	v_pk_add_f32 v[36:37], v[36:37], v[200:201]
	v_pk_add_f32 v[38:39], v[38:39], v[202:203]
	v_pk_add_f32 v[32:33], v[32:33], v[204:205]
	v_pk_add_f32 v[34:35], v[34:35], v[206:207]
	v_fmac_f32_e32 v213, v36, v36
	v_fmac_f32_e32 v213, v37, v37
	v_fmac_f32_e32 v213, v38, v38
	v_fmac_f32_e32 v213, v39, v39
	v_fmac_f32_e32 v213, v32, v32
	v_fmac_f32_e32 v213, v33, v33
	v_fmac_f32_e32 v213, v34, v34
	v_fmac_f32_e32 v213, v35, v35
	v_cvt_pk_bf16_f32 v200, v36, v37
	v_cvt_pk_bf16_f32 v201, v38, v39
	v_cvt_pk_bf16_f32 v202, v32, v33
	v_cvt_pk_bf16_f32 v203, v34, v35
	global_store_dwordx4 v217, v[200:203], s[80:81] offset:256
	ds_bpermute_b32 v214, v215, v213
	s_waitcnt lgkmcnt(0)
	v_add_f32_e32 v213, v213, v214
	ds_bpermute_b32 v214, v216, v213
	s_waitcnt lgkmcnt(0)
	v_add_f32_e32 v213, v213, v214
	s_mov_b64 exec, 0xffff
	global_atomic_add_f32 v208, v213, s[12:13] offset:576
	s_mov_b64 exec, -1
	v_add_u32_e32 v212, 0x160000, v210
	global_load_dwordx4 v[192:195], v212, s[36:37]
	global_load_dwordx4 v[196:199], v212, s[36:37] offset:16
	global_load_dwordx4 v[200:203], v212, s[36:37] offset:512
	global_load_dwordx4 v[204:207], v212, s[36:37] offset:528
	s_waitcnt vmcnt(7)
	v_pk_add_f32 v[28:29], v[28:29], v[176:177]
	v_pk_add_f32 v[30:31], v[30:31], v[178:179]
	v_pk_add_f32 v[24:25], v[24:25], v[180:181]
	v_pk_add_f32 v[26:27], v[26:27], v[182:183]
	v_mul_f32_e32 v213, v28, v28
	v_fmac_f32_e32 v213, v29, v29
	v_fmac_f32_e32 v213, v30, v30
	v_fmac_f32_e32 v213, v31, v31
	v_fmac_f32_e32 v213, v24, v24
	v_fmac_f32_e32 v213, v25, v25
	v_fmac_f32_e32 v213, v26, v26
	v_fmac_f32_e32 v213, v27, v27
	v_cvt_pk_bf16_f32 v176, v28, v29
	v_cvt_pk_bf16_f32 v177, v30, v31
	v_cvt_pk_bf16_f32 v178, v24, v25
	v_cvt_pk_bf16_f32 v179, v26, v27
	v_add_u32_e32 v217, 0xa0000, v209
	global_store_dwordx4 v217, v[176:179], s[80:81]
	v_pk_add_f32 v[20:21], v[20:21], v[184:185]
	v_pk_add_f32 v[22:23], v[22:23], v[186:187]
	v_pk_add_f32 v[16:17], v[16:17], v[188:189]
	v_pk_add_f32 v[18:19], v[18:19], v[190:191]
	v_fmac_f32_e32 v213, v20, v20
	v_fmac_f32_e32 v213, v21, v21
	v_fmac_f32_e32 v213, v22, v22
	v_fmac_f32_e32 v213, v23, v23
	v_fmac_f32_e32 v213, v16, v16
	v_fmac_f32_e32 v213, v17, v17
	v_fmac_f32_e32 v213, v18, v18
	v_fmac_f32_e32 v213, v19, v19
	v_cvt_pk_bf16_f32 v184, v20, v21
	v_cvt_pk_bf16_f32 v185, v22, v23
	v_cvt_pk_bf16_f32 v186, v16, v17
	v_cvt_pk_bf16_f32 v187, v18, v19
	global_store_dwordx4 v217, v[184:187], s[80:81] offset:256
	ds_bpermute_b32 v214, v215, v213
	s_waitcnt lgkmcnt(0)
	v_add_f32_e32 v213, v213, v214
	ds_bpermute_b32 v214, v216, v213
	s_waitcnt lgkmcnt(0)
	v_add_f32_e32 v213, v213, v214
	s_mov_b64 exec, 0xffff
	global_atomic_add_f32 v208, v213, s[12:13] offset:640
	s_mov_b64 exec, -1
	s_waitcnt vmcnt(3)
	v_pk_add_f32 v[12:13], v[12:13], v[192:193]
	v_pk_add_f32 v[14:15], v[14:15], v[194:195]
	v_pk_add_f32 v[8:9], v[8:9], v[196:197]
	v_pk_add_f32 v[10:11], v[10:11], v[198:199]
	v_mul_f32_e32 v213, v12, v12
	v_fmac_f32_e32 v213, v13, v13
	v_fmac_f32_e32 v213, v14, v14
	v_fmac_f32_e32 v213, v15, v15
	v_fmac_f32_e32 v213, v8, v8
	v_fmac_f32_e32 v213, v9, v9
	v_fmac_f32_e32 v213, v10, v10
	v_fmac_f32_e32 v213, v11, v11
	v_cvt_pk_bf16_f32 v192, v12, v13
	v_cvt_pk_bf16_f32 v193, v14, v15
	v_cvt_pk_bf16_f32 v194, v8, v9
	v_cvt_pk_bf16_f32 v195, v10, v11
	v_add_u32_e32 v217, 0xb0000, v209
	global_store_dwordx4 v217, v[192:195], s[80:81]
	v_pk_add_f32 v[4:5], v[4:5], v[200:201]
	v_pk_add_f32 v[6:7], v[6:7], v[202:203]
	v_pk_add_f32 v[0:1], v[0:1], v[204:205]
	v_pk_add_f32 v[2:3], v[2:3], v[206:207]
	v_fmac_f32_e32 v213, v4, v4
	v_fmac_f32_e32 v213, v5, v5
	v_fmac_f32_e32 v213, v6, v6
	v_fmac_f32_e32 v213, v7, v7
	v_fmac_f32_e32 v213, v0, v0
	v_fmac_f32_e32 v213, v1, v1
	v_fmac_f32_e32 v213, v2, v2
	v_fmac_f32_e32 v213, v3, v3
	v_cvt_pk_bf16_f32 v200, v4, v5
	v_cvt_pk_bf16_f32 v201, v6, v7
	v_cvt_pk_bf16_f32 v202, v0, v1
	v_cvt_pk_bf16_f32 v203, v2, v3
	global_store_dwordx4 v217, v[200:203], s[80:81] offset:256
	ds_bpermute_b32 v214, v215, v213
	s_waitcnt lgkmcnt(0)
	v_add_f32_e32 v213, v213, v214
	ds_bpermute_b32 v214, v216, v213
	s_waitcnt lgkmcnt(0)
	v_add_f32_e32 v213, v213, v214
	s_mov_b64 exec, 0xffff
	global_atomic_add_f32 v208, v213, s[12:13] offset:704
	s_mov_b64 exec, -1
	s_branch .LBB0_273

.LBB0_363:
	ds_read_b128 v[76:79], v231
	v_xor_b32_e32 v91, 64, v231
	ds_read_b128 v[80:83], v91
	ds_read_b128 v[84:87], v231 offset:2048
	ds_read_b128 v[88:91], v91 offset:2048
	s_add_u32 s8, s6, 0x100
	s_addc_u32 s9, s7, 0
	s_cmp_eq_u32 s65, 28
	s_cselect_b32 s39, s31, s9
	s_cselect_b32 s38, s33, s8
	s_cselect_b32 s11, s29, s64
	s_cselect_b32 s10, s62, s63
	v_lshl_add_u64 v[108:109], s[6:7], 0, v[172:173]
	s_add_i32 m0, s44, 0xc000
	ds_read_b128 v[92:95], v241
	v_xor_b32_e32 v195, 64, v241
	ds_read_b128 v[96:99], v195
	ds_read_b128 v[100:103], v241 offset:2048
	ds_read_b128 v[104:107], v195 offset:2048
	ds_read_b128 v[180:183], v241 offset:4096
	ds_read_b128 v[184:187], v195 offset:4096
	ds_read_b128 v[188:191], v241 offset:6144
	ds_read_b128 v[192:195], v195 offset:6144
	global_load_lds_dwordx4 v[108:109], off
	v_lshl_add_u64 v[108:109], s[6:7], 0, v[174:175]
	s_add_i32 m0, s44, 0xe000
	s_nop 0
	global_load_lds_dwordx4 v[108:109], off
	s_waitcnt lgkmcnt(8)
	s_barrier
	s_waitcnt lgkmcnt(0)
	s_setprio 1
	s_waitcnt lgkmcnt(0)
	v_mfma_f32_16x16x32_bf16 v[158:161], v[76:79], v[92:95], v[158:161]
	v_mfma_f32_16x16x32_bf16 v[158:161], v[80:83], v[96:99], v[158:161]
	v_mfma_f32_16x16x32_bf16 v[60:63], v[84:87], v[92:95], v[60:63]
	v_mfma_f32_16x16x32_bf16 v[60:63], v[88:91], v[96:99], v[60:63]
	v_mfma_f32_16x16x32_bf16 v[150:153], v[76:79], v[100:103], v[150:153]
	v_mfma_f32_16x16x32_bf16 v[150:153], v[80:83], v[104:107], v[150:153]
	v_mfma_f32_16x16x32_bf16 v[52:55], v[84:87], v[100:103], v[52:55]
	v_mfma_f32_16x16x32_bf16 v[52:55], v[88:91], v[104:107], v[52:55]
	v_mfma_f32_16x16x32_bf16 v[146:149], v[76:79], v[180:183], v[146:149]
	v_mfma_f32_16x16x32_bf16 v[146:149], v[80:83], v[184:187], v[146:149]
	v_mfma_f32_16x16x32_bf16 v[48:51], v[84:87], v[180:183], v[48:51]
	v_mfma_f32_16x16x32_bf16 v[48:51], v[88:91], v[184:187], v[48:51]
	v_mfma_f32_16x16x32_bf16 v[138:141], v[76:79], v[188:191], v[138:141]
	v_mfma_f32_16x16x32_bf16 v[138:141], v[80:83], v[192:195], v[138:141]
	v_mfma_f32_16x16x32_bf16 v[40:43], v[84:87], v[188:191], v[40:43]
	v_mfma_f32_16x16x32_bf16 v[40:43], v[88:91], v[192:195], v[40:43]
	s_setprio 0
	s_barrier
	s_add_i32 s6, s58, s42
	v_lshl_add_u64 v[216:217], s[10:11], 0, v[164:165]
	s_mov_b32 m0, s6
	ds_read_b128 v[196:199], v242
	v_xor_b32_e32 v211, 64, v242
	ds_read_b128 v[200:203], v211
	ds_read_b128 v[204:207], v242 offset:2048
	ds_read_b128 v[208:211], v211 offset:2048
	global_load_lds_dwordx4 v[216:217], off
	v_lshl_add_u64 v[244:245], s[10:11], 0, v[166:167]
	s_add_i32 m0, s6, 0x2000
	s_nop 0
	global_load_lds_dwordx4 v[244:245], off
	s_barrier
	s_waitcnt lgkmcnt(0)
	s_setprio 1
	s_waitcnt lgkmcnt(0)
	v_mfma_f32_16x16x32_bf16 v[154:157], v[196:199], v[92:95], v[154:157]
	v_mfma_f32_16x16x32_bf16 v[56:59], v[204:207], v[92:95], v[56:59]
	v_mfma_f32_16x16x32_bf16 v[44:47], v[204:207], v[100:103], v[44:47]
	v_mfma_f32_16x16x32_bf16 v[36:39], v[204:207], v[180:183], v[36:39]
	v_mfma_f32_16x16x32_bf16 v[32:35], v[204:207], v[188:191], v[32:35]
	v_mfma_f32_16x16x32_bf16 v[154:157], v[200:203], v[96:99], v[154:157]
	v_mfma_f32_16x16x32_bf16 v[56:59], v[208:211], v[96:99], v[56:59]
	v_mfma_f32_16x16x32_bf16 v[92:95], v[196:199], v[100:103], v[142:145]
	v_mfma_f32_16x16x32_bf16 v[44:47], v[208:211], v[104:107], v[44:47]
	v_mfma_f32_16x16x32_bf16 v[96:99], v[196:199], v[180:183], v[134:137]
	v_mfma_f32_16x16x32_bf16 v[36:39], v[208:211], v[184:187], v[36:39]
	v_mfma_f32_16x16x32_bf16 v[100:103], v[196:199], v[188:191], v[130:133]
	v_mfma_f32_16x16x32_bf16 v[32:35], v[208:211], v[192:195], v[32:35]
	v_mfma_f32_16x16x32_bf16 v[92:95], v[200:203], v[104:107], v[92:95]
	v_mfma_f32_16x16x32_bf16 v[96:99], v[200:203], v[184:187], v[96:99]
	v_mfma_f32_16x16x32_bf16 v[100:103], v[200:203], v[192:195], v[100:103]
	s_setprio 0
	s_mov_b32 m0, s44
	v_lshl_add_u64 v[246:247], s[38:39], 0, v[170:171]
	s_barrier
	ds_read_b128 v[104:107], v241 offset:16384
	v_xor_b32_e32 v195, 64, v241
	ds_read_b128 v[130:133], v195 offset:16384
	ds_read_b128 v[134:137], v241 offset:18432
	ds_read_b128 v[142:145], v195 offset:18432
	ds_read_b128 v[180:183], v241 offset:20480
	ds_read_b128 v[184:187], v195 offset:20480
	ds_read_b128 v[188:191], v241 offset:22528
	ds_read_b128 v[192:195], v195 offset:22528
	global_load_lds_dwordx4 v[246:247], off
	v_lshl_add_u64 v[248:249], s[38:39], 0, v[168:169]
	s_mov_b32 m0, s45
	s_nop 0
	global_load_lds_dwordx4 v[248:249], off
	s_barrier
	s_waitcnt lgkmcnt(0)
	s_setprio 1
	s_waitcnt lgkmcnt(0)
	v_mfma_f32_16x16x32_bf16 v[126:129], v[76:79], v[104:107], v[126:129]
	v_mfma_f32_16x16x32_bf16 v[126:129], v[80:83], v[130:133], v[126:129]
	v_mfma_f32_16x16x32_bf16 v[28:31], v[84:87], v[104:107], v[28:31]
	v_mfma_f32_16x16x32_bf16 v[28:31], v[88:91], v[130:133], v[28:31]
	v_mfma_f32_16x16x32_bf16 v[122:125], v[76:79], v[134:137], v[122:125]
	v_mfma_f32_16x16x32_bf16 v[122:125], v[80:83], v[142:145], v[122:125]
	v_mfma_f32_16x16x32_bf16 v[24:27], v[84:87], v[134:137], v[24:27]
	v_mfma_f32_16x16x32_bf16 v[24:27], v[88:91], v[142:145], v[24:27]
	v_mfma_f32_16x16x32_bf16 v[114:117], v[76:79], v[180:183], v[114:117]
	v_mfma_f32_16x16x32_bf16 v[114:117], v[80:83], v[184:187], v[114:117]
	v_mfma_f32_16x16x32_bf16 v[20:23], v[84:87], v[180:183], v[20:23]
	v_mfma_f32_16x16x32_bf16 v[20:23], v[88:91], v[184:187], v[20:23]
	v_mfma_f32_16x16x32_bf16 v[72:75], v[76:79], v[188:191], v[72:75]
	v_mfma_f32_16x16x32_bf16 v[72:75], v[80:83], v[192:195], v[72:75]
	v_mfma_f32_16x16x32_bf16 v[4:7], v[84:87], v[188:191], v[4:7]
	v_mfma_f32_16x16x32_bf16 v[4:7], v[88:91], v[192:195], v[4:7]
	s_setprio 0
	s_barrier
	s_add_u32 s6, s10, 0x1600000
	s_addc_u32 s7, s11, 0
	s_add_i32 s66, s59, s42
	v_lshl_add_u64 v[76:77], s[6:7], 0, v[164:165]
	s_mov_b32 m0, s66
	s_nop 0
	global_load_lds_dwordx4 v[76:77], off
	v_lshl_add_u64 v[76:77], s[6:7], 0, v[166:167]
	s_add_i32 m0, s66, 0x2000
	s_nop 0
	global_load_lds_dwordx4 v[76:77], off
	s_waitcnt vmcnt(6)
	s_barrier
	s_setprio 1
	v_mfma_f32_16x16x32_bf16 v[16:19], v[204:207], v[104:107], v[16:19]
	v_mfma_f32_16x16x32_bf16 v[12:15], v[204:207], v[134:137], v[12:15]
	v_mfma_f32_16x16x32_bf16 v[68:71], v[196:199], v[180:183], v[68:71]
	v_mfma_f32_16x16x32_bf16 v[8:11], v[204:207], v[180:183], v[8:11]
	v_mfma_f32_16x16x32_bf16 v[64:67], v[196:199], v[188:191], v[64:67]
	v_mfma_f32_16x16x32_bf16 v[0:3], v[204:207], v[188:191], v[0:3]
	v_mfma_f32_16x16x32_bf16 v[76:79], v[196:199], v[104:107], v[118:121]
	v_mfma_f32_16x16x32_bf16 v[16:19], v[208:211], v[130:133], v[16:19]
	v_mfma_f32_16x16x32_bf16 v[80:83], v[196:199], v[134:137], v[110:113]
	v_mfma_f32_16x16x32_bf16 v[12:15], v[208:211], v[142:145], v[12:15]
	v_mfma_f32_16x16x32_bf16 v[68:71], v[200:203], v[184:187], v[68:71]
	v_mfma_f32_16x16x32_bf16 v[8:11], v[208:211], v[184:187], v[8:11]
	v_mfma_f32_16x16x32_bf16 v[64:67], v[200:203], v[192:195], v[64:67]
	v_mfma_f32_16x16x32_bf16 v[0:3], v[208:211], v[192:195], v[0:3]
	v_mfma_f32_16x16x32_bf16 v[76:79], v[200:203], v[130:133], v[76:79]
	v_mfma_f32_16x16x32_bf16 v[80:83], v[200:203], v[142:145], v[80:83]
	s_setprio 0
	s_add_i32 s66, 0, 0x18000
	v_add_u32_e32 v108, s66, v229
	s_barrier
	ds_read_b128 v[84:87], v108
	v_xor_b32_e32 v111, 64, v108
	ds_read_b128 v[88:91], v111
	ds_read_b128 v[104:107], v108 offset:2048
	ds_read_b128 v[108:111], v111 offset:2048
	s_add_u32 s6, s38, 0x40000
	s_addc_u32 s7, s39, 0
	s_mov_b32 m0, s46
	v_lshl_add_u64 v[112:113], s[6:7], 0, v[170:171]
	ds_read_b128 v[118:121], v241 offset:32768
	v_xor_b32_e32 v199, 64, v241
	ds_read_b128 v[130:133], v199 offset:32768
	ds_read_b128 v[134:137], v241 offset:34816
	ds_read_b128 v[180:183], v199 offset:34816
	ds_read_b128 v[184:187], v241 offset:36864
	ds_read_b128 v[188:191], v199 offset:36864
	ds_read_b128 v[192:195], v241 offset:38912
	ds_read_b128 v[196:199], v199 offset:38912
	global_load_lds_dwordx4 v[112:113], off
	v_lshl_add_u64 v[112:113], s[6:7], 0, v[168:169]
	s_mov_b32 m0, s47
	s_nop 0
	global_load_lds_dwordx4 v[112:113], off
	s_waitcnt lgkmcnt(8)
	s_barrier
	s_waitcnt lgkmcnt(0)
	s_setprio 1
	s_waitcnt lgkmcnt(0)
	v_mfma_f32_16x16x32_bf16 v[142:145], v[84:87], v[118:121], v[158:161]
	v_mfma_f32_16x16x32_bf16 v[158:161], v[88:91], v[130:133], v[142:145]
	v_mfma_f32_16x16x32_bf16 v[142:145], v[84:87], v[134:137], v[150:153]
	v_mfma_f32_16x16x32_bf16 v[60:63], v[104:107], v[118:121], v[60:63]
	v_mfma_f32_16x16x32_bf16 v[150:153], v[88:91], v[180:183], v[142:145]
	v_mfma_f32_16x16x32_bf16 v[52:55], v[104:107], v[134:137], v[52:55]
	v_mfma_f32_16x16x32_bf16 v[142:145], v[84:87], v[184:187], v[146:149]
	v_mfma_f32_16x16x32_bf16 v[48:51], v[104:107], v[184:187], v[48:51]
	v_mfma_f32_16x16x32_bf16 v[138:141], v[84:87], v[192:195], v[138:141]
	v_mfma_f32_16x16x32_bf16 v[40:43], v[104:107], v[192:195], v[40:43]
	v_mfma_f32_16x16x32_bf16 v[60:63], v[108:111], v[130:133], v[60:63]
	v_mfma_f32_16x16x32_bf16 v[52:55], v[108:111], v[180:183], v[52:55]
	v_mfma_f32_16x16x32_bf16 v[146:149], v[88:91], v[188:191], v[142:145]
	v_mfma_f32_16x16x32_bf16 v[48:51], v[108:111], v[188:191], v[48:51]
	v_mfma_f32_16x16x32_bf16 v[138:141], v[88:91], v[196:199], v[138:141]
	v_mfma_f32_16x16x32_bf16 v[40:43], v[108:111], v[196:199], v[40:43]
	s_setprio 0
	s_barrier
	s_add_i32 s38, 0, 0x1c000
	v_add_u32_e32 v112, s38, v229
	s_add_i32 s6, s66, s42
	ds_read_b128 v[200:203], v112
	v_xor_b32_e32 v215, 64, v112
	ds_read_b128 v[204:207], v215
	ds_read_b128 v[208:211], v112 offset:2048
	ds_read_b128 v[212:215], v215 offset:2048
	v_lshl_add_u64 v[112:113], v[216:217], 0, s[14:15]
	s_mov_b32 m0, s6
	s_nop 0
	global_load_lds_dwordx4 v[112:113], off
	v_lshl_add_u64 v[112:113], v[244:245], 0, s[14:15]
	s_add_i32 m0, s6, 0x2000
	s_nop 0
	global_load_lds_dwordx4 v[112:113], off
	s_barrier
	s_waitcnt lgkmcnt(0)
	s_setprio 1
	s_waitcnt lgkmcnt(0)
	v_mfma_f32_16x16x32_bf16 v[142:145], v[200:203], v[118:121], v[154:157]
	v_mfma_f32_16x16x32_bf16 v[92:95], v[200:203], v[134:137], v[92:95]
	v_mfma_f32_16x16x32_bf16 v[154:157], v[204:207], v[130:133], v[142:145]
	v_mfma_f32_16x16x32_bf16 v[142:145], v[204:207], v[180:183], v[92:95]
	v_mfma_f32_16x16x32_bf16 v[92:95], v[200:203], v[184:187], v[96:99]
	v_mfma_f32_16x16x32_bf16 v[56:59], v[208:211], v[118:121], v[56:59]
	v_mfma_f32_16x16x32_bf16 v[44:47], v[208:211], v[134:137], v[44:47]
	v_mfma_f32_16x16x32_bf16 v[134:137], v[204:207], v[188:191], v[92:95]
	v_mfma_f32_16x16x32_bf16 v[36:39], v[208:211], v[184:187], v[36:39]
	v_mfma_f32_16x16x32_bf16 v[92:95], v[200:203], v[192:195], v[100:103]
	v_mfma_f32_16x16x32_bf16 v[32:35], v[208:211], v[192:195], v[32:35]
	v_mfma_f32_16x16x32_bf16 v[56:59], v[212:215], v[130:133], v[56:59]
	v_mfma_f32_16x16x32_bf16 v[44:47], v[212:215], v[180:183], v[44:47]
	v_mfma_f32_16x16x32_bf16 v[36:39], v[212:215], v[188:191], v[36:39]
	v_mfma_f32_16x16x32_bf16 v[130:133], v[204:207], v[196:199], v[92:95]
	v_mfma_f32_16x16x32_bf16 v[32:35], v[212:215], v[196:199], v[32:35]
	s_setprio 0
	s_mov_b32 m0, s52
	v_lshl_add_u64 v[112:113], v[246:247], 0, s[14:15]
	s_barrier
	ds_read_b128 v[92:95], v241 offset:49152
	v_xor_b32_e32 v199, 64, v241
	ds_read_b128 v[96:99], v199 offset:49152
	ds_read_b128 v[100:103], v241 offset:51200
	ds_read_b128 v[180:183], v199 offset:51200
	ds_read_b128 v[184:187], v241 offset:53248
	ds_read_b128 v[188:191], v199 offset:53248
	ds_read_b128 v[192:195], v241 offset:55296
	ds_read_b128 v[196:199], v199 offset:55296
	global_load_lds_dwordx4 v[112:113], off
	v_lshl_add_u64 v[112:113], v[248:249], 0, s[14:15]
	s_mov_b32 m0, s53
	s_nop 0
	global_load_lds_dwordx4 v[112:113], off
	s_barrier
	s_waitcnt lgkmcnt(0)
	s_setprio 1
	s_waitcnt lgkmcnt(0)
	v_mfma_f32_16x16x32_bf16 v[118:121], v[84:87], v[92:95], v[126:129]
	v_mfma_f32_16x16x32_bf16 v[126:129], v[88:91], v[96:99], v[118:121]
	v_mfma_f32_16x16x32_bf16 v[28:31], v[104:107], v[92:95], v[28:31]
	v_mfma_f32_16x16x32_bf16 v[118:121], v[84:87], v[100:103], v[122:125]
	v_mfma_f32_16x16x32_bf16 v[24:27], v[104:107], v[100:103], v[24:27]
	v_mfma_f32_16x16x32_bf16 v[112:115], v[84:87], v[184:187], v[114:117]
	v_mfma_f32_16x16x32_bf16 v[20:23], v[104:107], v[184:187], v[20:23]
	v_mfma_f32_16x16x32_bf16 v[72:75], v[84:87], v[192:195], v[72:75]
	v_mfma_f32_16x16x32_bf16 v[4:7], v[104:107], v[192:195], v[4:7]
	v_mfma_f32_16x16x32_bf16 v[28:31], v[108:111], v[96:99], v[28:31]
	v_mfma_f32_16x16x32_bf16 v[122:125], v[88:91], v[180:183], v[118:121]
	v_mfma_f32_16x16x32_bf16 v[24:27], v[108:111], v[180:183], v[24:27]
	v_mfma_f32_16x16x32_bf16 v[114:117], v[88:91], v[188:191], v[112:115]
	v_mfma_f32_16x16x32_bf16 v[20:23], v[108:111], v[188:191], v[20:23]
	v_mfma_f32_16x16x32_bf16 v[72:75], v[88:91], v[196:199], v[72:75]
	v_mfma_f32_16x16x32_bf16 v[4:7], v[108:111], v[196:199], v[4:7]
	s_setprio 0
	s_barrier
	s_add_u32 s6, s10, 0x1600080
	s_addc_u32 s7, s11, 0
	s_add_i32 s10, s38, s42
	v_lshl_add_u64 v[84:85], s[6:7], 0, v[164:165]
	s_mov_b32 m0, s10
	s_nop 0
	global_load_lds_dwordx4 v[84:85], off
	v_lshl_add_u64 v[84:85], s[6:7], 0, v[166:167]
	s_add_i32 m0, s10, 0x2000
	s_nop 0
	global_load_lds_dwordx4 v[84:85], off
	s_waitcnt vmcnt(6)
	s_barrier
	s_setprio 1
	v_mfma_f32_16x16x32_bf16 v[76:79], v[200:203], v[92:95], v[76:79]
	v_mfma_f32_16x16x32_bf16 v[118:121], v[204:207], v[96:99], v[76:79]
	v_mfma_f32_16x16x32_bf16 v[16:19], v[208:211], v[92:95], v[16:19]
	v_mfma_f32_16x16x32_bf16 v[76:79], v[200:203], v[100:103], v[80:83]
	v_mfma_f32_16x16x32_bf16 v[12:15], v[208:211], v[100:103], v[12:15]
	v_mfma_f32_16x16x32_bf16 v[68:71], v[200:203], v[184:187], v[68:71]
	v_mfma_f32_16x16x32_bf16 v[8:11], v[208:211], v[184:187], v[8:11]
	v_mfma_f32_16x16x32_bf16 v[64:67], v[200:203], v[192:195], v[64:67]
	v_mfma_f32_16x16x32_bf16 v[0:3], v[208:211], v[192:195], v[0:3]
	v_mfma_f32_16x16x32_bf16 v[16:19], v[212:215], v[96:99], v[16:19]
	v_mfma_f32_16x16x32_bf16 v[110:113], v[204:207], v[180:183], v[76:79]
	v_mfma_f32_16x16x32_bf16 v[12:15], v[212:215], v[180:183], v[12:15]
	v_mfma_f32_16x16x32_bf16 v[68:71], v[204:207], v[188:191], v[68:71]
	v_mfma_f32_16x16x32_bf16 v[8:11], v[212:215], v[188:191], v[8:11]
	v_mfma_f32_16x16x32_bf16 v[64:67], v[204:207], v[196:199], v[64:67]
	v_mfma_f32_16x16x32_bf16 v[0:3], v[212:215], v[196:199], v[0:3]
	s_setprio 0
	s_add_i32 s65, s65, 2
	s_add_u32 s63, s63, 0x100
	s_addc_u32 s64, s64, 0
	s_cmp_gt_u32 s65, 29
	s_mov_b64 s[6:7], s[8:9]
	s_barrier
	s_cbranch_scc0 .LBB0_363
	s_lshl_b32 s6, s0, 8
	s_lshl_b32 s1, s1, 7
	v_mov_b32_e32 v185, v163
	v_mov_b32_e32 v80, v225
	s_add_i32 s6, s6, s56
	s_or_b32 s1, s1, s49
	s_lshl_b32 s0, s0, 3
	v_add_u32_e32 v182, s6, v185
	v_lshl_add_u32 v180, v80, 3, s1
	v_ashrrev_i32_e32 v183, 31, v182
	v_ashrrev_i32_e32 v181, 31, v180
	v_lshl_add_u64 v[78:79], v[182:183], 2, s[12:13]
	v_lshlrev_b64 v[90:91], 2, v[180:181]
	global_load_dword v188, v[78:79], off
	global_load_dword v184, v[78:79], off offset:64
	global_load_dword v186, v[78:79], off offset:128
	global_load_dword v196, v[78:79], off offset:192
	global_load_dword v195, v[78:79], off offset:256
	global_load_dword v77, v[78:79], off offset:320
	global_load_dword v76, v[78:79], off offset:384
	global_load_dword v183, v[78:79], off offset:448
	v_lshl_add_u64 v[190:191], s[82:83], 0, v[90:91]
	v_lshl_add_u64 v[78:79], s[16:17], 0, v[90:91]
	v_lshl_add_u64 v[80:81], s[18:19], 0, v[90:91]
	global_load_dwordx4 v[94:97], v[190:191], off
	global_load_dwordx4 v[102:105], v[78:79], off
	global_load_dwordx4 v[98:101], v[80:81], off
	v_lshl_add_u64 v[192:193], s[84:85], 0, v[90:91]
	v_lshl_add_u64 v[78:79], s[20:21], 0, v[90:91]
	v_lshl_add_u64 v[80:81], s[22:23], 0, v[90:91]
	v_lshl_add_u64 v[82:83], s[24:25], 0, v[90:91]
	v_lshl_add_u64 v[90:91], s[26:27], 0, v[90:91]
	global_load_dwordx4 v[106:109], v[192:193], off
	global_load_dwordx4 v[86:89], v[78:79], off
	s_nop 0
	global_load_dwordx4 v[78:81], v[80:81], off
	s_add_i32 s0, s0, s57
	global_load_dwordx4 v[82:85], v[82:83], off
	v_add_u32_e32 v187, s0, v185
	global_load_dwordx4 v[90:93], v[90:91], off
	v_cmp_gt_i32_e64 s[10:11], 2, v185
	s_waitcnt vmcnt(0)
	v_fmamk_f32 v188, v188, 0x3a000000, v243
	v_rsq_f32_e32 v194, v188
	v_mad_i64_i32 v[188:189], s[0:1], v187, s60, 0
	v_lshl_add_u64 v[188:189], s[70:71], 0, v[188:189]
	v_pk_mul_f32 v[160:161], v[160:161], v[194:195] op_sel_hi:[1,0]
	v_pk_mul_f32 v[158:159], v[158:159], v[194:195] op_sel_hi:[1,0]
	v_pk_mul_f32 v[156:157], v[156:157], v[194:195] op_sel_hi:[1,0]
	v_pk_mul_f32 v[154:155], v[154:155], v[194:195] op_sel_hi:[1,0]
	v_lshl_add_u64 v[188:189], v[180:181], 2, v[188:189]
	s_and_saveexec_b64 s[0:1], s[10:11]
	s_cbranch_execz .LBB0_366
	v_add_co_u32_e32 v198, vcc, 0x5000, v188
	global_store_dwordx4 v[188:189], v[158:161], off
	s_nop 0
	v_addc_co_u32_e32 v199, vcc, 0, v189, vcc
	global_store_dwordx4 v[198:199], v[154:157], off offset:2048

.LBB0_508:
	ds_read_b128 v[136:139], v141
	v_xor_b32_e32 v157, 64, v141
	ds_read_b128 v[146:149], v157
	ds_read_b128 v[150:153], v141 offset:2048
	ds_read_b128 v[154:157], v157 offset:2048
	s_add_u32 s8, s0, 0xffea0080
	s_addc_u32 s9, s1, -1
	s_cmpk_eq_i32 s41, 0x54
	s_cselect_b32 s17, s13, s9
	s_cselect_b32 s16, s12, s8
	s_cselect_b32 s9, s11, s40
	s_cselect_b32 s8, s10, s39
	v_lshl_add_u64 v[204:205], s[0:1], 0, v[128:129]
	s_add_i32 m0, s21, 0xc000
	ds_read_b128 v[158:161], v142
	v_xor_b32_e32 v203, 64, v142
	ds_read_b128 v[176:179], v203
	ds_read_b128 v[180:183], v142 offset:2048
	ds_read_b128 v[184:187], v203 offset:2048
	ds_read_b128 v[188:191], v142 offset:4096
	ds_read_b128 v[192:195], v203 offset:4096
	ds_read_b128 v[196:199], v142 offset:6144
	ds_read_b128 v[200:203], v203 offset:6144
	global_load_lds_dwordx4 v[204:205], off
	v_lshl_add_u64 v[204:205], s[0:1], 0, v[130:131]
	s_add_i32 m0, s21, 0xe000
	s_nop 0
	global_load_lds_dwordx4 v[204:205], off
	s_waitcnt lgkmcnt(8)
	s_barrier
	s_waitcnt lgkmcnt(0)
	s_setprio 1
	s_waitcnt lgkmcnt(0)
	v_mfma_f32_16x16x32_bf16 v[124:127], v[136:139], v[158:161], v[124:127]
	v_mfma_f32_16x16x32_bf16 v[124:127], v[146:149], v[176:179], v[124:127]
	v_mfma_f32_16x16x32_bf16 v[120:123], v[150:153], v[158:161], v[120:123]
	v_mfma_f32_16x16x32_bf16 v[120:123], v[154:157], v[176:179], v[120:123]
	v_mfma_f32_16x16x32_bf16 v[108:111], v[136:139], v[180:183], v[108:111]
	v_mfma_f32_16x16x32_bf16 v[108:111], v[146:149], v[184:187], v[108:111]
	v_mfma_f32_16x16x32_bf16 v[104:107], v[150:153], v[180:183], v[104:107]
	v_mfma_f32_16x16x32_bf16 v[104:107], v[154:157], v[184:187], v[104:107]
	v_mfma_f32_16x16x32_bf16 v[92:95], v[136:139], v[188:191], v[92:95]
	v_mfma_f32_16x16x32_bf16 v[92:95], v[146:149], v[192:195], v[92:95]
	v_mfma_f32_16x16x32_bf16 v[88:91], v[150:153], v[188:191], v[88:91]
	v_mfma_f32_16x16x32_bf16 v[88:91], v[154:157], v[192:195], v[88:91]
	v_mfma_f32_16x16x32_bf16 v[76:79], v[136:139], v[196:199], v[76:79]
	v_mfma_f32_16x16x32_bf16 v[76:79], v[146:149], v[200:203], v[76:79]
	v_mfma_f32_16x16x32_bf16 v[72:75], v[150:153], v[196:199], v[72:75]
	v_mfma_f32_16x16x32_bf16 v[72:75], v[154:157], v[200:203], v[72:75]
	s_setprio 0
	s_barrier
	s_add_i32 s42, s33, s20
	v_lshl_add_u64 v[216:217], s[8:9], 0, v[170:171]
	s_mov_b32 m0, s42
	ds_read_b128 v[204:207], v143
	v_xor_b32_e32 v243, 64, v143
	ds_read_b128 v[208:211], v243
	ds_read_b128 v[212:215], v143 offset:2048
	ds_read_b128 v[240:243], v243 offset:2048
	global_load_lds_dwordx4 v[216:217], off
	v_lshl_add_u64 v[244:245], s[8:9], 0, v[174:175]
	s_add_i32 m0, s42, 0x2000
	s_nop 0
	global_load_lds_dwordx4 v[244:245], off
	s_barrier
	s_waitcnt lgkmcnt(0)
	s_setprio 1
	s_waitcnt lgkmcnt(0)
	v_mfma_f32_16x16x32_bf16 v[116:119], v[204:207], v[158:161], v[116:119]
	v_mfma_f32_16x16x32_bf16 v[116:119], v[208:211], v[176:179], v[116:119]
	v_mfma_f32_16x16x32_bf16 v[112:115], v[212:215], v[158:161], v[112:115]
	v_mfma_f32_16x16x32_bf16 v[112:115], v[240:243], v[176:179], v[112:115]
	v_mfma_f32_16x16x32_bf16 v[100:103], v[204:207], v[180:183], v[100:103]
	v_mfma_f32_16x16x32_bf16 v[100:103], v[208:211], v[184:187], v[100:103]
	v_mfma_f32_16x16x32_bf16 v[96:99], v[212:215], v[180:183], v[96:99]
	v_mfma_f32_16x16x32_bf16 v[96:99], v[240:243], v[184:187], v[96:99]
	v_mfma_f32_16x16x32_bf16 v[84:87], v[204:207], v[188:191], v[84:87]
	v_mfma_f32_16x16x32_bf16 v[84:87], v[208:211], v[192:195], v[84:87]
	v_mfma_f32_16x16x32_bf16 v[80:83], v[212:215], v[188:191], v[80:83]
	v_mfma_f32_16x16x32_bf16 v[80:83], v[240:243], v[192:195], v[80:83]
	v_mfma_f32_16x16x32_bf16 v[68:71], v[204:207], v[196:199], v[68:71]
	v_mfma_f32_16x16x32_bf16 v[68:71], v[208:211], v[200:203], v[68:71]
	v_mfma_f32_16x16x32_bf16 v[64:67], v[212:215], v[196:199], v[64:67]
	v_mfma_f32_16x16x32_bf16 v[64:67], v[240:243], v[200:203], v[64:67]
	s_setprio 0
	s_mov_b32 m0, s21
	v_lshl_add_u64 v[246:247], s[16:17], 0, v[168:169]
	s_barrier
	ds_read_b128 v[158:161], v142 offset:16384
	v_xor_b32_e32 v203, 64, v142
	ds_read_b128 v[176:179], v203 offset:16384
	ds_read_b128 v[180:183], v142 offset:18432
	ds_read_b128 v[184:187], v203 offset:18432
	ds_read_b128 v[188:191], v142 offset:20480
	ds_read_b128 v[192:195], v203 offset:20480
	ds_read_b128 v[196:199], v142 offset:22528
	ds_read_b128 v[200:203], v203 offset:22528
	global_load_lds_dwordx4 v[246:247], off
	v_lshl_add_u64 v[248:249], s[16:17], 0, v[172:173]
	s_mov_b32 m0, s22
	s_nop 0
	global_load_lds_dwordx4 v[248:249], off
	s_barrier
	s_waitcnt lgkmcnt(0)
	s_setprio 1
	s_waitcnt lgkmcnt(0)
	v_mfma_f32_16x16x32_bf16 v[60:63], v[136:139], v[158:161], v[60:63]
	v_mfma_f32_16x16x32_bf16 v[60:63], v[146:149], v[176:179], v[60:63]
	v_mfma_f32_16x16x32_bf16 v[56:59], v[150:153], v[158:161], v[56:59]
	v_mfma_f32_16x16x32_bf16 v[56:59], v[154:157], v[176:179], v[56:59]
	v_mfma_f32_16x16x32_bf16 v[44:47], v[136:139], v[180:183], v[44:47]
	v_mfma_f32_16x16x32_bf16 v[44:47], v[146:149], v[184:187], v[44:47]
	v_mfma_f32_16x16x32_bf16 v[40:43], v[150:153], v[180:183], v[40:43]
	v_mfma_f32_16x16x32_bf16 v[40:43], v[154:157], v[184:187], v[40:43]
	v_mfma_f32_16x16x32_bf16 v[28:31], v[136:139], v[188:191], v[28:31]
	v_mfma_f32_16x16x32_bf16 v[28:31], v[146:149], v[192:195], v[28:31]
	v_mfma_f32_16x16x32_bf16 v[24:27], v[150:153], v[188:191], v[24:27]
	v_mfma_f32_16x16x32_bf16 v[24:27], v[154:157], v[192:195], v[24:27]
	v_mfma_f32_16x16x32_bf16 v[12:15], v[136:139], v[196:199], v[12:15]
	v_mfma_f32_16x16x32_bf16 v[12:15], v[146:149], v[200:203], v[12:15]
	v_mfma_f32_16x16x32_bf16 v[8:11], v[150:153], v[196:199], v[8:11]
	v_mfma_f32_16x16x32_bf16 v[8:11], v[154:157], v[200:203], v[8:11]
	s_setprio 0
	s_barrier
	s_add_u32 s42, s8, 0x160000
	s_addc_u32 s43, s9, 0
	s_add_i32 s44, s34, s20
	v_lshl_add_u64 v[136:137], s[42:43], 0, v[170:171]
	s_mov_b32 m0, s44
	s_nop 0
	global_load_lds_dwordx4 v[136:137], off
	v_lshl_add_u64 v[136:137], s[42:43], 0, v[174:175]
	s_add_i32 m0, s44, 0x2000
	s_nop 0
	global_load_lds_dwordx4 v[136:137], off
	s_waitcnt vmcnt(6)
	s_barrier
	s_setprio 1
	v_mfma_f32_16x16x32_bf16 v[52:55], v[204:207], v[158:161], v[52:55]
	v_mfma_f32_16x16x32_bf16 v[52:55], v[208:211], v[176:179], v[52:55]
	v_mfma_f32_16x16x32_bf16 v[48:51], v[212:215], v[158:161], v[48:51]
	v_mfma_f32_16x16x32_bf16 v[48:51], v[240:243], v[176:179], v[48:51]
	v_mfma_f32_16x16x32_bf16 v[36:39], v[204:207], v[180:183], v[36:39]
	v_mfma_f32_16x16x32_bf16 v[36:39], v[208:211], v[184:187], v[36:39]
	v_mfma_f32_16x16x32_bf16 v[32:35], v[212:215], v[180:183], v[32:35]
	v_mfma_f32_16x16x32_bf16 v[32:35], v[240:243], v[184:187], v[32:35]
	v_mfma_f32_16x16x32_bf16 v[20:23], v[204:207], v[188:191], v[20:23]
	v_mfma_f32_16x16x32_bf16 v[20:23], v[208:211], v[192:195], v[20:23]
	v_mfma_f32_16x16x32_bf16 v[16:19], v[212:215], v[188:191], v[16:19]
	v_mfma_f32_16x16x32_bf16 v[16:19], v[240:243], v[192:195], v[16:19]
	v_mfma_f32_16x16x32_bf16 v[4:7], v[204:207], v[196:199], v[4:7]
	v_mfma_f32_16x16x32_bf16 v[4:7], v[208:211], v[200:203], v[4:7]
	v_mfma_f32_16x16x32_bf16 v[0:3], v[212:215], v[196:199], v[0:3]
	v_mfma_f32_16x16x32_bf16 v[0:3], v[240:243], v[200:203], v[0:3]
	s_setprio 0
	s_add_i32 s42, 0, 0x18000
	v_add_u32_e32 v145, s42, v140
	s_barrier
	ds_read_b128 v[136:139], v145
	v_xor_b32_e32 v157, 64, v145
	ds_read_b128 v[146:149], v157
	ds_read_b128 v[150:153], v145 offset:2048
	ds_read_b128 v[154:157], v157 offset:2048
	s_add_u32 s16, s16, 0x160000
	s_addc_u32 s17, s17, 0
	s_mov_b32 m0, s23
	v_lshl_add_u64 v[204:205], s[16:17], 0, v[168:169]
	ds_read_b128 v[158:161], v142 offset:32768
	v_xor_b32_e32 v203, 64, v142
	ds_read_b128 v[176:179], v203 offset:32768
	ds_read_b128 v[180:183], v142 offset:34816
	ds_read_b128 v[184:187], v203 offset:34816
	ds_read_b128 v[188:191], v142 offset:36864
	ds_read_b128 v[192:195], v203 offset:36864
	ds_read_b128 v[196:199], v142 offset:38912
	ds_read_b128 v[200:203], v203 offset:38912
	global_load_lds_dwordx4 v[204:205], off
	v_lshl_add_u64 v[204:205], s[16:17], 0, v[172:173]
	s_mov_b32 m0, s24
	s_nop 0
	global_load_lds_dwordx4 v[204:205], off
	s_waitcnt lgkmcnt(8)
	s_barrier
	s_waitcnt lgkmcnt(0)
	s_setprio 1
	s_waitcnt lgkmcnt(0)
	v_mfma_f32_16x16x32_bf16 v[124:127], v[136:139], v[158:161], v[124:127]
	v_mfma_f32_16x16x32_bf16 v[124:127], v[146:149], v[176:179], v[124:127]
	v_mfma_f32_16x16x32_bf16 v[120:123], v[150:153], v[158:161], v[120:123]
	v_mfma_f32_16x16x32_bf16 v[120:123], v[154:157], v[176:179], v[120:123]
	v_mfma_f32_16x16x32_bf16 v[108:111], v[136:139], v[180:183], v[108:111]
	v_mfma_f32_16x16x32_bf16 v[108:111], v[146:149], v[184:187], v[108:111]
	v_mfma_f32_16x16x32_bf16 v[104:107], v[150:153], v[180:183], v[104:107]
	v_mfma_f32_16x16x32_bf16 v[104:107], v[154:157], v[184:187], v[104:107]
	v_mfma_f32_16x16x32_bf16 v[92:95], v[136:139], v[188:191], v[92:95]
	v_mfma_f32_16x16x32_bf16 v[92:95], v[146:149], v[192:195], v[92:95]
	v_mfma_f32_16x16x32_bf16 v[88:91], v[150:153], v[188:191], v[88:91]
	v_mfma_f32_16x16x32_bf16 v[88:91], v[154:157], v[192:195], v[88:91]
	v_mfma_f32_16x16x32_bf16 v[76:79], v[136:139], v[196:199], v[76:79]
	v_mfma_f32_16x16x32_bf16 v[76:79], v[146:149], v[200:203], v[76:79]
	v_mfma_f32_16x16x32_bf16 v[72:75], v[150:153], v[196:199], v[72:75]
	v_mfma_f32_16x16x32_bf16 v[72:75], v[154:157], v[200:203], v[72:75]
	s_setprio 0
	s_barrier
	s_add_i32 s16, 0, 0x1c000
	s_add_i32 s17, s42, s20
	v_add_u32_e32 v145, s16, v140
	v_lshl_add_u64 v[216:217], v[216:217], 0, s[4:5]
	s_mov_b32 m0, s17
	ds_read_b128 v[204:207], v145
	v_xor_b32_e32 v243, 64, v145
	ds_read_b128 v[208:211], v243
	ds_read_b128 v[212:215], v145 offset:2048
	ds_read_b128 v[240:243], v243 offset:2048
	global_load_lds_dwordx4 v[216:217], off
	v_lshl_add_u64 v[216:217], v[244:245], 0, s[4:5]
	s_add_i32 m0, s17, 0x2000
	s_nop 0
	global_load_lds_dwordx4 v[216:217], off
	s_barrier
	s_waitcnt lgkmcnt(0)
	s_setprio 1
	s_waitcnt lgkmcnt(0)
	v_mfma_f32_16x16x32_bf16 v[116:119], v[204:207], v[158:161], v[116:119]
	v_mfma_f32_16x16x32_bf16 v[116:119], v[208:211], v[176:179], v[116:119]
	v_mfma_f32_16x16x32_bf16 v[112:115], v[212:215], v[158:161], v[112:115]
	v_mfma_f32_16x16x32_bf16 v[112:115], v[240:243], v[176:179], v[112:115]
	v_mfma_f32_16x16x32_bf16 v[100:103], v[204:207], v[180:183], v[100:103]
	v_mfma_f32_16x16x32_bf16 v[100:103], v[208:211], v[184:187], v[100:103]
	v_mfma_f32_16x16x32_bf16 v[96:99], v[212:215], v[180:183], v[96:99]
	v_mfma_f32_16x16x32_bf16 v[96:99], v[240:243], v[184:187], v[96:99]
	v_mfma_f32_16x16x32_bf16 v[84:87], v[204:207], v[188:191], v[84:87]
	v_mfma_f32_16x16x32_bf16 v[84:87], v[208:211], v[192:195], v[84:87]
	v_mfma_f32_16x16x32_bf16 v[80:83], v[212:215], v[188:191], v[80:83]
	v_mfma_f32_16x16x32_bf16 v[80:83], v[240:243], v[192:195], v[80:83]
	v_mfma_f32_16x16x32_bf16 v[68:71], v[204:207], v[196:199], v[68:71]
	v_mfma_f32_16x16x32_bf16 v[68:71], v[208:211], v[200:203], v[68:71]
	v_mfma_f32_16x16x32_bf16 v[64:67], v[212:215], v[196:199], v[64:67]
	v_mfma_f32_16x16x32_bf16 v[64:67], v[240:243], v[200:203], v[64:67]
	s_setprio 0
	s_mov_b32 m0, s28
	v_lshl_add_u64 v[216:217], v[246:247], 0, s[4:5]
	s_barrier
	ds_read_b128 v[158:161], v142 offset:49152
	v_xor_b32_e32 v203, 64, v142
	ds_read_b128 v[176:179], v203 offset:49152
	ds_read_b128 v[180:183], v142 offset:51200
	ds_read_b128 v[184:187], v203 offset:51200
	ds_read_b128 v[188:191], v142 offset:53248
	ds_read_b128 v[192:195], v203 offset:53248
	ds_read_b128 v[196:199], v142 offset:55296
	ds_read_b128 v[200:203], v203 offset:55296
	global_load_lds_dwordx4 v[216:217], off
	v_lshl_add_u64 v[216:217], v[248:249], 0, s[4:5]
	s_mov_b32 m0, s29
	s_nop 0
	global_load_lds_dwordx4 v[216:217], off
	s_barrier
	s_waitcnt lgkmcnt(0)
	s_setprio 1
	s_waitcnt lgkmcnt(0)
	v_mfma_f32_16x16x32_bf16 v[60:63], v[136:139], v[158:161], v[60:63]
	v_mfma_f32_16x16x32_bf16 v[60:63], v[146:149], v[176:179], v[60:63]
	v_mfma_f32_16x16x32_bf16 v[56:59], v[150:153], v[158:161], v[56:59]
	v_mfma_f32_16x16x32_bf16 v[56:59], v[154:157], v[176:179], v[56:59]
	v_mfma_f32_16x16x32_bf16 v[44:47], v[136:139], v[180:183], v[44:47]
	v_mfma_f32_16x16x32_bf16 v[44:47], v[146:149], v[184:187], v[44:47]
	v_mfma_f32_16x16x32_bf16 v[40:43], v[150:153], v[180:183], v[40:43]
	v_mfma_f32_16x16x32_bf16 v[40:43], v[154:157], v[184:187], v[40:43]
	v_mfma_f32_16x16x32_bf16 v[28:31], v[136:139], v[188:191], v[28:31]
	v_mfma_f32_16x16x32_bf16 v[28:31], v[146:149], v[192:195], v[28:31]
	v_mfma_f32_16x16x32_bf16 v[24:27], v[150:153], v[188:191], v[24:27]
	v_mfma_f32_16x16x32_bf16 v[24:27], v[154:157], v[192:195], v[24:27]
	v_mfma_f32_16x16x32_bf16 v[12:15], v[136:139], v[196:199], v[12:15]
	v_mfma_f32_16x16x32_bf16 v[12:15], v[146:149], v[200:203], v[12:15]
	v_mfma_f32_16x16x32_bf16 v[8:11], v[150:153], v[196:199], v[8:11]
	v_mfma_f32_16x16x32_bf16 v[8:11], v[154:157], v[200:203], v[8:11]
	s_setprio 0
	s_barrier
	s_add_u32 s8, s8, 0x160080
	s_addc_u32 s9, s9, 0
	s_add_i32 s16, s16, s20
	v_lshl_add_u64 v[136:137], s[8:9], 0, v[170:171]
	s_mov_b32 m0, s16
	s_nop 0
	global_load_lds_dwordx4 v[136:137], off
	v_lshl_add_u64 v[136:137], s[8:9], 0, v[174:175]
	s_add_i32 m0, s16, 0x2000
	s_nop 0
	global_load_lds_dwordx4 v[136:137], off
	s_waitcnt vmcnt(6)
	s_barrier
	s_setprio 1
	v_mfma_f32_16x16x32_bf16 v[52:55], v[204:207], v[158:161], v[52:55]
	v_mfma_f32_16x16x32_bf16 v[52:55], v[208:211], v[176:179], v[52:55]
	v_mfma_f32_16x16x32_bf16 v[48:51], v[212:215], v[158:161], v[48:51]
	v_mfma_f32_16x16x32_bf16 v[48:51], v[240:243], v[176:179], v[48:51]
	v_mfma_f32_16x16x32_bf16 v[36:39], v[204:207], v[180:183], v[36:39]
	v_mfma_f32_16x16x32_bf16 v[36:39], v[208:211], v[184:187], v[36:39]
	v_mfma_f32_16x16x32_bf16 v[32:35], v[212:215], v[180:183], v[32:35]
	v_mfma_f32_16x16x32_bf16 v[32:35], v[240:243], v[184:187], v[32:35]
	v_mfma_f32_16x16x32_bf16 v[20:23], v[204:207], v[188:191], v[20:23]
	v_mfma_f32_16x16x32_bf16 v[20:23], v[208:211], v[192:195], v[20:23]
	v_mfma_f32_16x16x32_bf16 v[16:19], v[212:215], v[188:191], v[16:19]
	v_mfma_f32_16x16x32_bf16 v[16:19], v[240:243], v[192:195], v[16:19]
	v_mfma_f32_16x16x32_bf16 v[4:7], v[204:207], v[196:199], v[4:7]
	v_mfma_f32_16x16x32_bf16 v[4:7], v[208:211], v[200:203], v[4:7]
	v_mfma_f32_16x16x32_bf16 v[0:3], v[212:215], v[196:199], v[0:3]
	v_mfma_f32_16x16x32_bf16 v[0:3], v[240:243], v[200:203], v[0:3]
	s_setprio 0
	s_add_i32 s41, s41, 2
	s_add_u32 s0, s0, 0x100
	s_addc_u32 s1, s1, 0
	s_add_u32 s39, s39, 0x100
	s_addc_u32 s40, s40, 0
	s_cmpk_gt_u32 s41, 0x55
	s_barrier
	s_cbranch_scc0 .LBB0_508
	v_lshl_add_u32 v217, s38, 8, v163
	v_add_u32_e32 v217, s26, v217
	v_lshlrev_b32_e32 v208, 2, v217
	v_lshl_add_u32 v214, v225, 3, s27
	v_lshl_add_u32 v214, s37, 8, v214
	v_lshl_add_u32 v209, v217, 11, v214
	v_lshlrev_b32_e32 v209, 1, v209
	v_lshlrev_b32_e32 v210, 1, v209
	v_lshl_add_u32 v217, v225, 4, v163
	v_xor_b32_e32 v215, 16, v217
	v_lshlrev_b32_e32 v215, 2, v215
	v_xor_b32_e32 v216, 32, v217
	v_lshlrev_b32_e32 v216, 2, v216
	v_add_u32_e32 v211, 0x0, v209
	global_load_dwordx4 v[176:179], v211, s[80:81]
	global_load_dwordx4 v[180:183], v211, s[80:81] offset:256
	v_add_u32_e32 v211, 0x10000, v209
	global_load_dwordx4 v[192:195], v211, s[80:81]
	global_load_dwordx4 v[196:199], v211, s[80:81] offset:256
	s_waitcnt vmcnt(2)
	v_lshlrev_b32_e32 v184, 16, v176
	v_and_b32_e32 v185, 0xffff0000, v176
	v_lshlrev_b32_e32 v186, 16, v177
	v_and_b32_e32 v187, 0xffff0000, v177
	v_lshlrev_b32_e32 v188, 16, v178
	v_and_b32_e32 v189, 0xffff0000, v178
	v_lshlrev_b32_e32 v190, 16, v179
	v_and_b32_e32 v191, 0xffff0000, v179
	v_pk_add_f32 v[124:125], v[124:125], v[184:185]
	v_pk_add_f32 v[126:127], v[126:127], v[186:187]
	v_pk_add_f32 v[120:121], v[120:121], v[188:189]
	v_pk_add_f32 v[122:123], v[122:123], v[190:191]
	v_mul_f32_e32 v213, v124, v124
	v_fmac_f32_e32 v213, v125, v125
	v_fmac_f32_e32 v213, v126, v126
	v_fmac_f32_e32 v213, v127, v127
	v_fmac_f32_e32 v213, v120, v120
	v_fmac_f32_e32 v213, v121, v121
	v_fmac_f32_e32 v213, v122, v122
	v_fmac_f32_e32 v213, v123, v123
	v_cvt_pk_bf16_f32 v176, v124, v125
	v_cvt_pk_bf16_f32 v177, v126, v127
	v_cvt_pk_bf16_f32 v178, v120, v121
	v_cvt_pk_bf16_f32 v179, v122, v123
	v_add_u32_e32 v217, 0x0, v209
	global_store_dwordx4 v217, v[176:179], s[80:81]
	v_lshlrev_b32_e32 v184, 16, v180
	v_and_b32_e32 v185, 0xffff0000, v180
	v_lshlrev_b32_e32 v186, 16, v181
	v_and_b32_e32 v187, 0xffff0000, v181
	v_lshlrev_b32_e32 v188, 16, v182
	v_and_b32_e32 v189, 0xffff0000, v182
	v_lshlrev_b32_e32 v190, 16, v183
	v_and_b32_e32 v191, 0xffff0000, v183
	v_pk_add_f32 v[116:117], v[116:117], v[184:185]
	v_pk_add_f32 v[118:119], v[118:119], v[186:187]
	v_pk_add_f32 v[112:113], v[112:113], v[188:189]
	v_pk_add_f32 v[114:115], v[114:115], v[190:191]
	v_fmac_f32_e32 v213, v116, v116
	v_fmac_f32_e32 v213, v117, v117
	v_fmac_f32_e32 v213, v118, v118
	v_fmac_f32_e32 v213, v119, v119
	v_fmac_f32_e32 v213, v112, v112
	v_fmac_f32_e32 v213, v113, v113
	v_fmac_f32_e32 v213, v114, v114
	v_fmac_f32_e32 v213, v115, v115
	v_cvt_pk_bf16_f32 v180, v116, v117
	v_cvt_pk_bf16_f32 v181, v118, v119
	v_cvt_pk_bf16_f32 v182, v112, v113
	v_cvt_pk_bf16_f32 v183, v114, v115
	global_store_dwordx4 v217, v[180:183], s[80:81] offset:256
	ds_bpermute_b32 v214, v215, v213
	s_waitcnt lgkmcnt(0)
	v_add_f32_e32 v213, v213, v214
	ds_bpermute_b32 v214, v216, v213
	s_waitcnt lgkmcnt(0)
	v_add_f32_e32 v213, v213, v214
	s_mov_b64 exec, 0xffff
	global_atomic_add_f32 v208, v213, s[14:15]
	s_mov_b64 exec, -1
	v_add_u32_e32 v211, 0x20000, v209
	global_load_dwordx4 v[176:179], v211, s[80:81]
	global_load_dwordx4 v[180:183], v211, s[80:81] offset:256
	s_waitcnt vmcnt(5)
	v_lshlrev_b32_e32 v200, 16, v192
	v_and_b32_e32 v201, 0xffff0000, v192
	v_lshlrev_b32_e32 v202, 16, v193
	v_and_b32_e32 v203, 0xffff0000, v193
	v_lshlrev_b32_e32 v204, 16, v194
	v_and_b32_e32 v205, 0xffff0000, v194
	v_lshlrev_b32_e32 v206, 16, v195
	v_and_b32_e32 v207, 0xffff0000, v195
	v_pk_add_f32 v[108:109], v[108:109], v[200:201]
	v_pk_add_f32 v[110:111], v[110:111], v[202:203]
	v_pk_add_f32 v[104:105], v[104:105], v[204:205]
	v_pk_add_f32 v[106:107], v[106:107], v[206:207]
	v_mul_f32_e32 v213, v108, v108
	v_fmac_f32_e32 v213, v109, v109
	v_fmac_f32_e32 v213, v110, v110
	v_fmac_f32_e32 v213, v111, v111
	v_fmac_f32_e32 v213, v104, v104
	v_fmac_f32_e32 v213, v105, v105
	v_fmac_f32_e32 v213, v106, v106
	v_fmac_f32_e32 v213, v107, v107
	v_cvt_pk_bf16_f32 v192, v108, v109
	v_cvt_pk_bf16_f32 v193, v110, v111
	v_cvt_pk_bf16_f32 v194, v104, v105
	v_cvt_pk_bf16_f32 v195, v106, v107
	v_add_u32_e32 v217, 0x10000, v209
	global_store_dwordx4 v217, v[192:195], s[80:81]
	v_lshlrev_b32_e32 v200, 16, v196
	v_and_b32_e32 v201, 0xffff0000, v196
	v_lshlrev_b32_e32 v202, 16, v197
	v_and_b32_e32 v203, 0xffff0000, v197
	v_lshlrev_b32_e32 v204, 16, v198
	v_and_b32_e32 v205, 0xffff0000, v198
	v_lshlrev_b32_e32 v206, 16, v199
	v_and_b32_e32 v207, 0xffff0000, v199
	v_pk_add_f32 v[100:101], v[100:101], v[200:201]
	v_pk_add_f32 v[102:103], v[102:103], v[202:203]
	v_pk_add_f32 v[96:97], v[96:97], v[204:205]
	v_pk_add_f32 v[98:99], v[98:99], v[206:207]
	v_fmac_f32_e32 v213, v100, v100
	v_fmac_f32_e32 v213, v101, v101
	v_fmac_f32_e32 v213, v102, v102
	v_fmac_f32_e32 v213, v103, v103
	v_fmac_f32_e32 v213, v96, v96
	v_fmac_f32_e32 v213, v97, v97
	v_fmac_f32_e32 v213, v98, v98
	v_fmac_f32_e32 v213, v99, v99
	v_cvt_pk_bf16_f32 v196, v100, v101
	v_cvt_pk_bf16_f32 v197, v102, v103
	v_cvt_pk_bf16_f32 v198, v96, v97
	v_cvt_pk_bf16_f32 v199, v98, v99
	global_store_dwordx4 v217, v[196:199], s[80:81] offset:256
	ds_bpermute_b32 v214, v215, v213
	s_waitcnt lgkmcnt(0)
	v_add_f32_e32 v213, v213, v214
	ds_bpermute_b32 v214, v216, v213
	s_waitcnt lgkmcnt(0)
	v_add_f32_e32 v213, v213, v214
	s_mov_b64 exec, 0xffff
	global_atomic_add_f32 v208, v213, s[14:15] offset:64
	s_mov_b64 exec, -1
	v_add_u32_e32 v211, 0x30000, v209
	global_load_dwordx4 v[192:195], v211, s[80:81]
	global_load_dwordx4 v[196:199], v211, s[80:81] offset:256
	s_waitcnt vmcnt(5)
	v_lshlrev_b32_e32 v184, 16, v176
	v_and_b32_e32 v185, 0xffff0000, v176
	v_lshlrev_b32_e32 v186, 16, v177
	v_and_b32_e32 v187, 0xffff0000, v177
	v_lshlrev_b32_e32 v188, 16, v178
	v_and_b32_e32 v189, 0xffff0000, v178
	v_lshlrev_b32_e32 v190, 16, v179
	v_and_b32_e32 v191, 0xffff0000, v179
	v_pk_add_f32 v[92:93], v[92:93], v[184:185]
	v_pk_add_f32 v[94:95], v[94:95], v[186:187]
	v_pk_add_f32 v[88:89], v[88:89], v[188:189]
	v_pk_add_f32 v[90:91], v[90:91], v[190:191]
	v_mul_f32_e32 v213, v92, v92
	v_fmac_f32_e32 v213, v93, v93
	v_fmac_f32_e32 v213, v94, v94
	v_fmac_f32_e32 v213, v95, v95
	v_fmac_f32_e32 v213, v88, v88
	v_fmac_f32_e32 v213, v89, v89
	v_fmac_f32_e32 v213, v90, v90
	v_fmac_f32_e32 v213, v91, v91
	v_cvt_pk_bf16_f32 v176, v92, v93
	v_cvt_pk_bf16_f32 v177, v94, v95
	v_cvt_pk_bf16_f32 v178, v88, v89
	v_cvt_pk_bf16_f32 v179, v90, v91
	v_add_u32_e32 v217, 0x20000, v209
	global_store_dwordx4 v217, v[176:179], s[80:81]
	v_lshlrev_b32_e32 v184, 16, v180
	v_and_b32_e32 v185, 0xffff0000, v180
	v_lshlrev_b32_e32 v186, 16, v181
	v_and_b32_e32 v187, 0xffff0000, v181
	v_lshlrev_b32_e32 v188, 16, v182
	v_and_b32_e32 v189, 0xffff0000, v182
	v_lshlrev_b32_e32 v190, 16, v183
	v_and_b32_e32 v191, 0xffff0000, v183
	v_pk_add_f32 v[84:85], v[84:85], v[184:185]
	v_pk_add_f32 v[86:87], v[86:87], v[186:187]
	v_pk_add_f32 v[80:81], v[80:81], v[188:189]
	v_pk_add_f32 v[82:83], v[82:83], v[190:191]
	v_fmac_f32_e32 v213, v84, v84
	v_fmac_f32_e32 v213, v85, v85
	v_fmac_f32_e32 v213, v86, v86
	v_fmac_f32_e32 v213, v87, v87
	v_fmac_f32_e32 v213, v80, v80
	v_fmac_f32_e32 v213, v81, v81
	v_fmac_f32_e32 v213, v82, v82
	v_fmac_f32_e32 v213, v83, v83
	v_cvt_pk_bf16_f32 v180, v84, v85
	v_cvt_pk_bf16_f32 v181, v86, v87
	v_cvt_pk_bf16_f32 v182, v80, v81
	v_cvt_pk_bf16_f32 v183, v82, v83
	global_store_dwordx4 v217, v[180:183], s[80:81] offset:256
	ds_bpermute_b32 v214, v215, v213
	s_waitcnt lgkmcnt(0)
	v_add_f32_e32 v213, v213, v214
	ds_bpermute_b32 v214, v216, v213
	s_waitcnt lgkmcnt(0)
	v_add_f32_e32 v213, v213, v214
	s_mov_b64 exec, 0xffff
	global_atomic_add_f32 v208, v213, s[14:15] offset:128
	s_mov_b64 exec, -1
	v_add_u32_e32 v211, 0x80000, v209
	global_load_dwordx4 v[176:179], v211, s[80:81]
	global_load_dwordx4 v[180:183], v211, s[80:81] offset:256
	s_waitcnt vmcnt(5)
	v_lshlrev_b32_e32 v200, 16, v192
	v_and_b32_e32 v201, 0xffff0000, v192
	v_lshlrev_b32_e32 v202, 16, v193
	v_and_b32_e32 v203, 0xffff0000, v193
	v_lshlrev_b32_e32 v204, 16, v194
	v_and_b32_e32 v205, 0xffff0000, v194
	v_lshlrev_b32_e32 v206, 16, v195
	v_and_b32_e32 v207, 0xffff0000, v195
	v_pk_add_f32 v[76:77], v[76:77], v[200:201]
	v_pk_add_f32 v[78:79], v[78:79], v[202:203]
	v_pk_add_f32 v[72:73], v[72:73], v[204:205]
	v_pk_add_f32 v[74:75], v[74:75], v[206:207]
	v_mul_f32_e32 v213, v76, v76
	v_fmac_f32_e32 v213, v77, v77
	v_fmac_f32_e32 v213, v78, v78
	v_fmac_f32_e32 v213, v79, v79
	v_fmac_f32_e32 v213, v72, v72
	v_fmac_f32_e32 v213, v73, v73
	v_fmac_f32_e32 v213, v74, v74
	v_fmac_f32_e32 v213, v75, v75
	v_cvt_pk_bf16_f32 v192, v76, v77
	v_cvt_pk_bf16_f32 v193, v78, v79
	v_cvt_pk_bf16_f32 v194, v72, v73
	v_cvt_pk_bf16_f32 v195, v74, v75
	v_add_u32_e32 v217, 0x30000, v209
	global_store_dwordx4 v217, v[192:195], s[80:81]
	v_lshlrev_b32_e32 v200, 16, v196
	v_and_b32_e32 v201, 0xffff0000, v196
	v_lshlrev_b32_e32 v202, 16, v197
	v_and_b32_e32 v203, 0xffff0000, v197
	v_lshlrev_b32_e32 v204, 16, v198
	v_and_b32_e32 v205, 0xffff0000, v198
	v_lshlrev_b32_e32 v206, 16, v199
	v_and_b32_e32 v207, 0xffff0000, v199
	v_pk_add_f32 v[68:69], v[68:69], v[200:201]
	v_pk_add_f32 v[70:71], v[70:71], v[202:203]
	v_pk_add_f32 v[64:65], v[64:65], v[204:205]
	v_pk_add_f32 v[66:67], v[66:67], v[206:207]
	v_fmac_f32_e32 v213, v68, v68
	v_fmac_f32_e32 v213, v69, v69
	v_fmac_f32_e32 v213, v70, v70
	v_fmac_f32_e32 v213, v71, v71
	v_fmac_f32_e32 v213, v64, v64
	v_fmac_f32_e32 v213, v65, v65
	v_fmac_f32_e32 v213, v66, v66
	v_fmac_f32_e32 v213, v67, v67
	v_cvt_pk_bf16_f32 v196, v68, v69
	v_cvt_pk_bf16_f32 v197, v70, v71
	v_cvt_pk_bf16_f32 v198, v64, v65
	v_cvt_pk_bf16_f32 v199, v66, v67
	global_store_dwordx4 v217, v[196:199], s[80:81] offset:256
	ds_bpermute_b32 v214, v215, v213
	s_waitcnt lgkmcnt(0)
	v_add_f32_e32 v213, v213, v214
	ds_bpermute_b32 v214, v216, v213
	s_waitcnt lgkmcnt(0)
	v_add_f32_e32 v213, v213, v214
	s_mov_b64 exec, 0xffff
	global_atomic_add_f32 v208, v213, s[14:15] offset:192
	s_mov_b64 exec, -1
	v_add_u32_e32 v211, 0x90000, v209
	global_load_dwordx4 v[192:195], v211, s[80:81]
	global_load_dwordx4 v[196:199], v211, s[80:81] offset:256
	s_waitcnt vmcnt(5)
	v_lshlrev_b32_e32 v184, 16, v176
	v_and_b32_e32 v185, 0xffff0000, v176
	v_lshlrev_b32_e32 v186, 16, v177
	v_and_b32_e32 v187, 0xffff0000, v177
	v_lshlrev_b32_e32 v188, 16, v178
	v_and_b32_e32 v189, 0xffff0000, v178
	v_lshlrev_b32_e32 v190, 16, v179
	v_and_b32_e32 v191, 0xffff0000, v179
	v_pk_add_f32 v[60:61], v[60:61], v[184:185]
	v_pk_add_f32 v[62:63], v[62:63], v[186:187]
	v_pk_add_f32 v[56:57], v[56:57], v[188:189]
	v_pk_add_f32 v[58:59], v[58:59], v[190:191]
	v_mul_f32_e32 v213, v60, v60
	v_fmac_f32_e32 v213, v61, v61
	v_fmac_f32_e32 v213, v62, v62
	v_fmac_f32_e32 v213, v63, v63
	v_fmac_f32_e32 v213, v56, v56
	v_fmac_f32_e32 v213, v57, v57
	v_fmac_f32_e32 v213, v58, v58
	v_fmac_f32_e32 v213, v59, v59
	v_cvt_pk_bf16_f32 v176, v60, v61
	v_cvt_pk_bf16_f32 v177, v62, v63
	v_cvt_pk_bf16_f32 v178, v56, v57
	v_cvt_pk_bf16_f32 v179, v58, v59
	v_add_u32_e32 v217, 0x80000, v209
	global_store_dwordx4 v217, v[176:179], s[80:81]
	v_lshlrev_b32_e32 v184, 16, v180
	v_and_b32_e32 v185, 0xffff0000, v180
	v_lshlrev_b32_e32 v186, 16, v181
	v_and_b32_e32 v187, 0xffff0000, v181
	v_lshlrev_b32_e32 v188, 16, v182
	v_and_b32_e32 v189, 0xffff0000, v182
	v_lshlrev_b32_e32 v190, 16, v183
	v_and_b32_e32 v191, 0xffff0000, v183
	v_pk_add_f32 v[52:53], v[52:53], v[184:185]
	v_pk_add_f32 v[54:55], v[54:55], v[186:187]
	v_pk_add_f32 v[48:49], v[48:49], v[188:189]
	v_pk_add_f32 v[50:51], v[50:51], v[190:191]
	v_fmac_f32_e32 v213, v52, v52
	v_fmac_f32_e32 v213, v53, v53
	v_fmac_f32_e32 v213, v54, v54
	v_fmac_f32_e32 v213, v55, v55
	v_fmac_f32_e32 v213, v48, v48
	v_fmac_f32_e32 v213, v49, v49
	v_fmac_f32_e32 v213, v50, v50
	v_fmac_f32_e32 v213, v51, v51
	v_cvt_pk_bf16_f32 v180, v52, v53
	v_cvt_pk_bf16_f32 v181, v54, v55
	v_cvt_pk_bf16_f32 v182, v48, v49
	v_cvt_pk_bf16_f32 v183, v50, v51
	global_store_dwordx4 v217, v[180:183], s[80:81] offset:256
	ds_bpermute_b32 v214, v215, v213
	s_waitcnt lgkmcnt(0)
	v_add_f32_e32 v213, v213, v214
	ds_bpermute_b32 v214, v216, v213
	s_waitcnt lgkmcnt(0)
	v_add_f32_e32 v213, v213, v214
	s_mov_b64 exec, 0xffff
	global_atomic_add_f32 v208, v213, s[14:15] offset:512
	s_mov_b64 exec, -1
	v_add_u32_e32 v211, 0xa0000, v209
	global_load_dwordx4 v[176:179], v211, s[80:81]
	global_load_dwordx4 v[180:183], v211, s[80:81] offset:256
	s_waitcnt vmcnt(5)
	v_lshlrev_b32_e32 v200, 16, v192
	v_and_b32_e32 v201, 0xffff0000, v192
	v_lshlrev_b32_e32 v202, 16, v193
	v_and_b32_e32 v203, 0xffff0000, v193
	v_lshlrev_b32_e32 v204, 16, v194
	v_and_b32_e32 v205, 0xffff0000, v194
	v_lshlrev_b32_e32 v206, 16, v195
	v_and_b32_e32 v207, 0xffff0000, v195
	v_pk_add_f32 v[44:45], v[44:45], v[200:201]
	v_pk_add_f32 v[46:47], v[46:47], v[202:203]
	v_pk_add_f32 v[40:41], v[40:41], v[204:205]
	v_pk_add_f32 v[42:43], v[42:43], v[206:207]
	v_mul_f32_e32 v213, v44, v44
	v_fmac_f32_e32 v213, v45, v45
	v_fmac_f32_e32 v213, v46, v46
	v_fmac_f32_e32 v213, v47, v47
	v_fmac_f32_e32 v213, v40, v40
	v_fmac_f32_e32 v213, v41, v41
	v_fmac_f32_e32 v213, v42, v42
	v_fmac_f32_e32 v213, v43, v43
	v_cvt_pk_bf16_f32 v192, v44, v45
	v_cvt_pk_bf16_f32 v193, v46, v47
	v_cvt_pk_bf16_f32 v194, v40, v41
	v_cvt_pk_bf16_f32 v195, v42, v43
	v_add_u32_e32 v217, 0x90000, v209
	global_store_dwordx4 v217, v[192:195], s[80:81]
	v_lshlrev_b32_e32 v200, 16, v196
	v_and_b32_e32 v201, 0xffff0000, v196
	v_lshlrev_b32_e32 v202, 16, v197
	v_and_b32_e32 v203, 0xffff0000, v197
	v_lshlrev_b32_e32 v204, 16, v198
	v_and_b32_e32 v205, 0xffff0000, v198
	v_lshlrev_b32_e32 v206, 16, v199
	v_and_b32_e32 v207, 0xffff0000, v199
	v_pk_add_f32 v[36:37], v[36:37], v[200:201]
	v_pk_add_f32 v[38:39], v[38:39], v[202:203]
	v_pk_add_f32 v[32:33], v[32:33], v[204:205]
	v_pk_add_f32 v[34:35], v[34:35], v[206:207]
	v_fmac_f32_e32 v213, v36, v36
	v_fmac_f32_e32 v213, v37, v37
	v_fmac_f32_e32 v213, v38, v38
	v_fmac_f32_e32 v213, v39, v39
	v_fmac_f32_e32 v213, v32, v32
	v_fmac_f32_e32 v213, v33, v33
	v_fmac_f32_e32 v213, v34, v34
	v_fmac_f32_e32 v213, v35, v35
	v_cvt_pk_bf16_f32 v196, v36, v37
	v_cvt_pk_bf16_f32 v197, v38, v39
	v_cvt_pk_bf16_f32 v198, v32, v33
	v_cvt_pk_bf16_f32 v199, v34, v35
	global_store_dwordx4 v217, v[196:199], s[80:81] offset:256
	ds_bpermute_b32 v214, v215, v213
	s_waitcnt lgkmcnt(0)
	v_add_f32_e32 v213, v213, v214
	ds_bpermute_b32 v214, v216, v213
	s_waitcnt lgkmcnt(0)
	v_add_f32_e32 v213, v213, v214
	s_mov_b64 exec, 0xffff
	global_atomic_add_f32 v208, v213, s[14:15] offset:576
	s_mov_b64 exec, -1
	v_add_u32_e32 v211, 0xb0000, v209
	global_load_dwordx4 v[192:195], v211, s[80:81]
	global_load_dwordx4 v[196:199], v211, s[80:81] offset:256
	s_waitcnt vmcnt(5)
	v_lshlrev_b32_e32 v184, 16, v176
	v_and_b32_e32 v185, 0xffff0000, v176
	v_lshlrev_b32_e32 v186, 16, v177
	v_and_b32_e32 v187, 0xffff0000, v177
	v_lshlrev_b32_e32 v188, 16, v178
	v_and_b32_e32 v189, 0xffff0000, v178
	v_lshlrev_b32_e32 v190, 16, v179
	v_and_b32_e32 v191, 0xffff0000, v179
	v_pk_add_f32 v[28:29], v[28:29], v[184:185]
	v_pk_add_f32 v[30:31], v[30:31], v[186:187]
	v_pk_add_f32 v[24:25], v[24:25], v[188:189]
	v_pk_add_f32 v[26:27], v[26:27], v[190:191]
	v_mul_f32_e32 v213, v28, v28
	v_fmac_f32_e32 v213, v29, v29
	v_fmac_f32_e32 v213, v30, v30
	v_fmac_f32_e32 v213, v31, v31
	v_fmac_f32_e32 v213, v24, v24
	v_fmac_f32_e32 v213, v25, v25
	v_fmac_f32_e32 v213, v26, v26
	v_fmac_f32_e32 v213, v27, v27
	v_cvt_pk_bf16_f32 v176, v28, v29
	v_cvt_pk_bf16_f32 v177, v30, v31
	v_cvt_pk_bf16_f32 v178, v24, v25
	v_cvt_pk_bf16_f32 v179, v26, v27
	v_add_u32_e32 v217, 0xa0000, v209
	global_store_dwordx4 v217, v[176:179], s[80:81]
	v_lshlrev_b32_e32 v184, 16, v180
	v_and_b32_e32 v185, 0xffff0000, v180
	v_lshlrev_b32_e32 v186, 16, v181
	v_and_b32_e32 v187, 0xffff0000, v181
	v_lshlrev_b32_e32 v188, 16, v182
	v_and_b32_e32 v189, 0xffff0000, v182
	v_lshlrev_b32_e32 v190, 16, v183
	v_and_b32_e32 v191, 0xffff0000, v183
	v_pk_add_f32 v[20:21], v[20:21], v[184:185]
	v_pk_add_f32 v[22:23], v[22:23], v[186:187]
	v_pk_add_f32 v[16:17], v[16:17], v[188:189]
	v_pk_add_f32 v[18:19], v[18:19], v[190:191]
	v_fmac_f32_e32 v213, v20, v20
	v_fmac_f32_e32 v213, v21, v21
	v_fmac_f32_e32 v213, v22, v22
	v_fmac_f32_e32 v213, v23, v23
	v_fmac_f32_e32 v213, v16, v16
	v_fmac_f32_e32 v213, v17, v17
	v_fmac_f32_e32 v213, v18, v18
	v_fmac_f32_e32 v213, v19, v19
	v_cvt_pk_bf16_f32 v180, v20, v21
	v_cvt_pk_bf16_f32 v181, v22, v23
	v_cvt_pk_bf16_f32 v182, v16, v17
	v_cvt_pk_bf16_f32 v183, v18, v19
	global_store_dwordx4 v217, v[180:183], s[80:81] offset:256
	ds_bpermute_b32 v214, v215, v213
	s_waitcnt lgkmcnt(0)
	v_add_f32_e32 v213, v213, v214
	ds_bpermute_b32 v214, v216, v213
	s_waitcnt lgkmcnt(0)
	v_add_f32_e32 v213, v213, v214
	s_mov_b64 exec, 0xffff
	global_atomic_add_f32 v208, v213, s[14:15] offset:640
	s_mov_b64 exec, -1
	s_waitcnt vmcnt(3)
	v_lshlrev_b32_e32 v200, 16, v192
	v_and_b32_e32 v201, 0xffff0000, v192
	v_lshlrev_b32_e32 v202, 16, v193
	v_and_b32_e32 v203, 0xffff0000, v193
	v_lshlrev_b32_e32 v204, 16, v194
	v_and_b32_e32 v205, 0xffff0000, v194
	v_lshlrev_b32_e32 v206, 16, v195
	v_and_b32_e32 v207, 0xffff0000, v195
	v_pk_add_f32 v[12:13], v[12:13], v[200:201]
	v_pk_add_f32 v[14:15], v[14:15], v[202:203]
	v_pk_add_f32 v[8:9], v[8:9], v[204:205]
	v_pk_add_f32 v[10:11], v[10:11], v[206:207]
	v_mul_f32_e32 v213, v12, v12
	v_fmac_f32_e32 v213, v13, v13
	v_fmac_f32_e32 v213, v14, v14
	v_fmac_f32_e32 v213, v15, v15
	v_fmac_f32_e32 v213, v8, v8
	v_fmac_f32_e32 v213, v9, v9
	v_fmac_f32_e32 v213, v10, v10
	v_fmac_f32_e32 v213, v11, v11
	v_cvt_pk_bf16_f32 v192, v12, v13
	v_cvt_pk_bf16_f32 v193, v14, v15
	v_cvt_pk_bf16_f32 v194, v8, v9
	v_cvt_pk_bf16_f32 v195, v10, v11
	v_add_u32_e32 v217, 0xb0000, v209
	global_store_dwordx4 v217, v[192:195], s[80:81]
	v_lshlrev_b32_e32 v200, 16, v196
	v_and_b32_e32 v201, 0xffff0000, v196
	v_lshlrev_b32_e32 v202, 16, v197
	v_and_b32_e32 v203, 0xffff0000, v197
	v_lshlrev_b32_e32 v204, 16, v198
	v_and_b32_e32 v205, 0xffff0000, v198
	v_lshlrev_b32_e32 v206, 16, v199
	v_and_b32_e32 v207, 0xffff0000, v199
	v_pk_add_f32 v[4:5], v[4:5], v[200:201]
	v_pk_add_f32 v[6:7], v[6:7], v[202:203]
	v_pk_add_f32 v[0:1], v[0:1], v[204:205]
	v_pk_add_f32 v[2:3], v[2:3], v[206:207]
	v_fmac_f32_e32 v213, v4, v4
	v_fmac_f32_e32 v213, v5, v5
	v_fmac_f32_e32 v213, v6, v6
	v_fmac_f32_e32 v213, v7, v7
	v_fmac_f32_e32 v213, v0, v0
	v_fmac_f32_e32 v213, v1, v1
	v_fmac_f32_e32 v213, v2, v2
	v_fmac_f32_e32 v213, v3, v3
	v_cvt_pk_bf16_f32 v196, v4, v5
	v_cvt_pk_bf16_f32 v197, v6, v7
	v_cvt_pk_bf16_f32 v198, v0, v1
	v_cvt_pk_bf16_f32 v199, v2, v3
	global_store_dwordx4 v217, v[196:199], s[80:81] offset:256
	ds_bpermute_b32 v214, v215, v213
	s_waitcnt lgkmcnt(0)
	v_add_f32_e32 v213, v213, v214
	ds_bpermute_b32 v214, v216, v213
	s_waitcnt lgkmcnt(0)
	v_add_f32_e32 v213, v213, v214
	s_mov_b64 exec, 0xffff
	global_atomic_add_f32 v208, v213, s[14:15] offset:704
	s_mov_b64 exec, -1
	s_branch .LBB0_496

.LBB0_599:
	ds_read_b128 v[140:143], v149
	v_xor_b32_e32 v179, 64, v149
	ds_read_b128 v[154:157], v179
	ds_read_b128 v[158:161], v149 offset:2048
	ds_read_b128 v[176:179], v179 offset:2048
	s_add_u32 s28, s26, 0xfff80080
	s_addc_u32 s29, s27, -1
	s_cmp_eq_u32 s49, 28
	s_cselect_b32 s31, s1, s29
	s_cselect_b32 s30, s13, s28
	s_cselect_b32 s29, s19, s48
	s_cselect_b32 s28, s21, s33
	v_lshl_add_u64 v[144:145], s[26:27], 0, v[132:133]
	s_add_i32 m0, s37, 0xc000
	ds_read_b128 v[180:183], v150
	v_xor_b32_e32 v211, 64, v150
	ds_read_b128 v[184:187], v211
	ds_read_b128 v[188:191], v150 offset:2048
	ds_read_b128 v[192:195], v211 offset:2048
	ds_read_b128 v[196:199], v150 offset:4096
	ds_read_b128 v[200:203], v211 offset:4096
	ds_read_b128 v[204:207], v150 offset:6144
	ds_read_b128 v[208:211], v211 offset:6144
	global_load_lds_dwordx4 v[144:145], off
	v_lshl_add_u64 v[144:145], s[26:27], 0, v[134:135]
	s_add_i32 m0, s37, 0xe000
	s_nop 0
	global_load_lds_dwordx4 v[144:145], off
	s_waitcnt lgkmcnt(8)
	s_barrier
	s_waitcnt lgkmcnt(0)
	s_setprio 1
	s_waitcnt lgkmcnt(0)
	v_mfma_f32_16x16x32_bf16 v[124:127], v[140:143], v[180:183], v[124:127]
	v_mfma_f32_16x16x32_bf16 v[124:127], v[154:157], v[184:187], v[124:127]
	v_mfma_f32_16x16x32_bf16 v[120:123], v[158:161], v[180:183], v[120:123]
	v_mfma_f32_16x16x32_bf16 v[120:123], v[176:179], v[184:187], v[120:123]
	v_mfma_f32_16x16x32_bf16 v[108:111], v[140:143], v[188:191], v[108:111]
	v_mfma_f32_16x16x32_bf16 v[108:111], v[154:157], v[192:195], v[108:111]
	v_mfma_f32_16x16x32_bf16 v[104:107], v[158:161], v[188:191], v[104:107]
	v_mfma_f32_16x16x32_bf16 v[104:107], v[176:179], v[192:195], v[104:107]
	v_mfma_f32_16x16x32_bf16 v[92:95], v[140:143], v[196:199], v[92:95]
	v_mfma_f32_16x16x32_bf16 v[92:95], v[154:157], v[200:203], v[92:95]
	v_mfma_f32_16x16x32_bf16 v[88:91], v[158:161], v[196:199], v[88:91]
	v_mfma_f32_16x16x32_bf16 v[88:91], v[176:179], v[200:203], v[88:91]
	v_mfma_f32_16x16x32_bf16 v[76:79], v[140:143], v[204:207], v[76:79]
	v_mfma_f32_16x16x32_bf16 v[76:79], v[154:157], v[208:211], v[76:79]
	v_mfma_f32_16x16x32_bf16 v[72:75], v[158:161], v[204:207], v[72:75]
	v_mfma_f32_16x16x32_bf16 v[72:75], v[176:179], v[208:211], v[72:75]
	s_setprio 0
	s_barrier
	s_add_i32 s52, s46, s36
	v_lshl_add_u64 v[144:145], s[28:29], 0, v[164:165]
	s_mov_b32 m0, s52
	ds_read_b128 v[212:215], v151
	v_xor_b32_e32 v251, 64, v151
	ds_read_b128 v[240:243], v251
	ds_read_b128 v[244:247], v151 offset:2048
	ds_read_b128 v[248:251], v251 offset:2048
	global_load_lds_dwordx4 v[144:145], off
	v_lshl_add_u64 v[216:217], s[28:29], 0, v[166:167]
	s_add_i32 m0, s52, 0x2000
	s_nop 0
	global_load_lds_dwordx4 v[216:217], off
	s_barrier
	s_waitcnt lgkmcnt(0)
	s_setprio 1
	s_waitcnt lgkmcnt(0)
	v_mfma_f32_16x16x32_bf16 v[116:119], v[212:215], v[180:183], v[116:119]
	v_mfma_f32_16x16x32_bf16 v[116:119], v[240:243], v[184:187], v[116:119]
	v_mfma_f32_16x16x32_bf16 v[112:115], v[244:247], v[180:183], v[112:115]
	v_mfma_f32_16x16x32_bf16 v[112:115], v[248:251], v[184:187], v[112:115]
	v_mfma_f32_16x16x32_bf16 v[100:103], v[212:215], v[188:191], v[100:103]
	v_mfma_f32_16x16x32_bf16 v[100:103], v[240:243], v[192:195], v[100:103]
	v_mfma_f32_16x16x32_bf16 v[96:99], v[244:247], v[188:191], v[96:99]
	v_mfma_f32_16x16x32_bf16 v[96:99], v[248:251], v[192:195], v[96:99]
	v_mfma_f32_16x16x32_bf16 v[84:87], v[212:215], v[196:199], v[84:87]
	v_mfma_f32_16x16x32_bf16 v[84:87], v[240:243], v[200:203], v[84:87]
	v_mfma_f32_16x16x32_bf16 v[80:83], v[244:247], v[196:199], v[80:83]
	v_mfma_f32_16x16x32_bf16 v[80:83], v[248:251], v[200:203], v[80:83]
	v_mfma_f32_16x16x32_bf16 v[68:71], v[212:215], v[204:207], v[68:71]
	v_mfma_f32_16x16x32_bf16 v[68:71], v[240:243], v[208:211], v[68:71]
	v_mfma_f32_16x16x32_bf16 v[64:67], v[244:247], v[204:207], v[64:67]
	v_mfma_f32_16x16x32_bf16 v[64:67], v[248:251], v[208:211], v[64:67]
	s_setprio 0
	s_mov_b32 m0, s37
	v_lshl_add_u64 v[252:253], s[30:31], 0, v[128:129]
	s_barrier
	ds_read_b128 v[180:183], v150 offset:16384
	v_xor_b32_e32 v211, 64, v150
	ds_read_b128 v[184:187], v211 offset:16384
	ds_read_b128 v[188:191], v150 offset:18432
	ds_read_b128 v[192:195], v211 offset:18432
	ds_read_b128 v[196:199], v150 offset:20480
	ds_read_b128 v[200:203], v211 offset:20480
	ds_read_b128 v[204:207], v150 offset:22528
	ds_read_b128 v[208:211], v211 offset:22528
	global_load_lds_dwordx4 v[252:253], off
	v_lshl_add_u64 v[234:235], s[30:31], 0, v[130:131]
	s_mov_b32 m0, s38
	s_nop 0
	global_load_lds_dwordx4 v[234:235], off
	s_barrier
	s_waitcnt lgkmcnt(0)
	s_setprio 1
	s_waitcnt lgkmcnt(0)
	v_mfma_f32_16x16x32_bf16 v[60:63], v[140:143], v[180:183], v[60:63]
	v_mfma_f32_16x16x32_bf16 v[60:63], v[154:157], v[184:187], v[60:63]
	v_mfma_f32_16x16x32_bf16 v[56:59], v[158:161], v[180:183], v[56:59]
	v_mfma_f32_16x16x32_bf16 v[56:59], v[176:179], v[184:187], v[56:59]
	v_mfma_f32_16x16x32_bf16 v[44:47], v[140:143], v[188:191], v[44:47]
	v_mfma_f32_16x16x32_bf16 v[44:47], v[154:157], v[192:195], v[44:47]
	v_mfma_f32_16x16x32_bf16 v[40:43], v[158:161], v[188:191], v[40:43]
	v_mfma_f32_16x16x32_bf16 v[40:43], v[176:179], v[192:195], v[40:43]
	v_mfma_f32_16x16x32_bf16 v[28:31], v[140:143], v[196:199], v[28:31]
	v_mfma_f32_16x16x32_bf16 v[28:31], v[154:157], v[200:203], v[28:31]
	v_mfma_f32_16x16x32_bf16 v[24:27], v[158:161], v[196:199], v[24:27]
	v_mfma_f32_16x16x32_bf16 v[24:27], v[176:179], v[200:203], v[24:27]
	v_mfma_f32_16x16x32_bf16 v[12:15], v[140:143], v[204:207], v[12:15]
	v_mfma_f32_16x16x32_bf16 v[12:15], v[154:157], v[208:211], v[12:15]
	v_mfma_f32_16x16x32_bf16 v[8:11], v[158:161], v[204:207], v[8:11]
	v_mfma_f32_16x16x32_bf16 v[8:11], v[176:179], v[208:211], v[8:11]
	s_setprio 0
	s_barrier
	s_add_u32 s52, s28, 0x80000
	s_addc_u32 s53, s29, 0
	s_add_i32 s54, s47, s36
	v_lshl_add_u64 v[140:141], s[52:53], 0, v[164:165]
	s_mov_b32 m0, s54
	s_nop 0
	global_load_lds_dwordx4 v[140:141], off
	v_lshl_add_u64 v[140:141], s[52:53], 0, v[166:167]
	s_add_i32 m0, s54, 0x2000
	s_nop 0
	global_load_lds_dwordx4 v[140:141], off
	s_waitcnt vmcnt(6)
	s_barrier
	s_setprio 1
	v_mfma_f32_16x16x32_bf16 v[52:55], v[212:215], v[180:183], v[52:55]
	v_mfma_f32_16x16x32_bf16 v[52:55], v[240:243], v[184:187], v[52:55]
	v_mfma_f32_16x16x32_bf16 v[48:51], v[244:247], v[180:183], v[48:51]
	v_mfma_f32_16x16x32_bf16 v[48:51], v[248:251], v[184:187], v[48:51]
	v_mfma_f32_16x16x32_bf16 v[36:39], v[212:215], v[188:191], v[36:39]
	v_mfma_f32_16x16x32_bf16 v[36:39], v[240:243], v[192:195], v[36:39]
	v_mfma_f32_16x16x32_bf16 v[32:35], v[244:247], v[188:191], v[32:35]
	v_mfma_f32_16x16x32_bf16 v[32:35], v[248:251], v[192:195], v[32:35]
	v_mfma_f32_16x16x32_bf16 v[20:23], v[212:215], v[196:199], v[20:23]
	v_mfma_f32_16x16x32_bf16 v[20:23], v[240:243], v[200:203], v[20:23]
	v_mfma_f32_16x16x32_bf16 v[16:19], v[244:247], v[196:199], v[16:19]
	v_mfma_f32_16x16x32_bf16 v[16:19], v[248:251], v[200:203], v[16:19]
	v_mfma_f32_16x16x32_bf16 v[4:7], v[212:215], v[204:207], v[4:7]
	v_mfma_f32_16x16x32_bf16 v[4:7], v[240:243], v[208:211], v[4:7]
	v_mfma_f32_16x16x32_bf16 v[0:3], v[244:247], v[204:207], v[0:3]
	v_mfma_f32_16x16x32_bf16 v[0:3], v[248:251], v[208:211], v[0:3]
	s_setprio 0
	s_add_i32 s52, 0, 0x18000
	v_add_u32_e32 v169, s52, v147
	s_barrier
	ds_read_b128 v[140:143], v169
	v_xor_b32_e32 v179, 64, v169
	ds_read_b128 v[154:157], v179
	ds_read_b128 v[158:161], v169 offset:2048
	ds_read_b128 v[176:179], v179 offset:2048
	s_add_u32 s30, s30, 0x80000
	s_addc_u32 s31, s31, 0
	s_mov_b32 m0, s39
	v_lshl_add_u64 v[212:213], s[30:31], 0, v[128:129]
	ds_read_b128 v[180:183], v150 offset:32768
	v_xor_b32_e32 v211, 64, v150
	ds_read_b128 v[184:187], v211 offset:32768
	ds_read_b128 v[188:191], v150 offset:34816
	ds_read_b128 v[192:195], v211 offset:34816
	ds_read_b128 v[196:199], v150 offset:36864
	ds_read_b128 v[200:203], v211 offset:36864
	ds_read_b128 v[204:207], v150 offset:38912
	ds_read_b128 v[208:211], v211 offset:38912
	global_load_lds_dwordx4 v[212:213], off
	v_lshl_add_u64 v[212:213], s[30:31], 0, v[130:131]
	s_mov_b32 m0, s40
	s_nop 0
	global_load_lds_dwordx4 v[212:213], off
	s_waitcnt lgkmcnt(8)
	s_barrier
	s_waitcnt lgkmcnt(0)
	s_setprio 1
	s_waitcnt lgkmcnt(0)
	v_mfma_f32_16x16x32_bf16 v[124:127], v[140:143], v[180:183], v[124:127]
	v_mfma_f32_16x16x32_bf16 v[124:127], v[154:157], v[184:187], v[124:127]
	v_mfma_f32_16x16x32_bf16 v[120:123], v[158:161], v[180:183], v[120:123]
	v_mfma_f32_16x16x32_bf16 v[120:123], v[176:179], v[184:187], v[120:123]
	v_mfma_f32_16x16x32_bf16 v[108:111], v[140:143], v[188:191], v[108:111]
	v_mfma_f32_16x16x32_bf16 v[108:111], v[154:157], v[192:195], v[108:111]
	v_mfma_f32_16x16x32_bf16 v[104:107], v[158:161], v[188:191], v[104:107]
	v_mfma_f32_16x16x32_bf16 v[104:107], v[176:179], v[192:195], v[104:107]
	v_mfma_f32_16x16x32_bf16 v[92:95], v[140:143], v[196:199], v[92:95]
	v_mfma_f32_16x16x32_bf16 v[92:95], v[154:157], v[200:203], v[92:95]
	v_mfma_f32_16x16x32_bf16 v[88:91], v[158:161], v[196:199], v[88:91]
	v_mfma_f32_16x16x32_bf16 v[88:91], v[176:179], v[200:203], v[88:91]
	v_mfma_f32_16x16x32_bf16 v[76:79], v[140:143], v[204:207], v[76:79]
	v_mfma_f32_16x16x32_bf16 v[76:79], v[154:157], v[208:211], v[76:79]
	v_mfma_f32_16x16x32_bf16 v[72:75], v[158:161], v[204:207], v[72:75]
	v_mfma_f32_16x16x32_bf16 v[72:75], v[176:179], v[208:211], v[72:75]
	s_setprio 0
	s_barrier
	s_add_i32 s30, 0, 0x1c000
	s_add_i32 s31, s52, s36
	v_add_u32_e32 v169, s30, v147
	v_lshl_add_u64 v[144:145], v[144:145], 0, s[16:17]
	s_mov_b32 m0, s31
	ds_read_b128 v[212:215], v169
	v_xor_b32_e32 v251, 64, v169
	ds_read_b128 v[240:243], v251
	ds_read_b128 v[244:247], v169 offset:2048
	ds_read_b128 v[248:251], v251 offset:2048
	global_load_lds_dwordx4 v[144:145], off
	v_lshl_add_u64 v[144:145], v[216:217], 0, s[16:17]
	s_add_i32 m0, s31, 0x2000
	s_nop 0
	global_load_lds_dwordx4 v[144:145], off
	s_barrier
	s_waitcnt lgkmcnt(0)
	s_setprio 1
	s_waitcnt lgkmcnt(0)
	v_mfma_f32_16x16x32_bf16 v[116:119], v[212:215], v[180:183], v[116:119]
	v_mfma_f32_16x16x32_bf16 v[116:119], v[240:243], v[184:187], v[116:119]
	v_mfma_f32_16x16x32_bf16 v[112:115], v[244:247], v[180:183], v[112:115]
	v_mfma_f32_16x16x32_bf16 v[112:115], v[248:251], v[184:187], v[112:115]
	v_mfma_f32_16x16x32_bf16 v[100:103], v[212:215], v[188:191], v[100:103]
	v_mfma_f32_16x16x32_bf16 v[100:103], v[240:243], v[192:195], v[100:103]
	v_mfma_f32_16x16x32_bf16 v[96:99], v[244:247], v[188:191], v[96:99]
	v_mfma_f32_16x16x32_bf16 v[96:99], v[248:251], v[192:195], v[96:99]
	v_mfma_f32_16x16x32_bf16 v[84:87], v[212:215], v[196:199], v[84:87]
	v_mfma_f32_16x16x32_bf16 v[84:87], v[240:243], v[200:203], v[84:87]
	v_mfma_f32_16x16x32_bf16 v[80:83], v[244:247], v[196:199], v[80:83]
	v_mfma_f32_16x16x32_bf16 v[80:83], v[248:251], v[200:203], v[80:83]
	v_mfma_f32_16x16x32_bf16 v[68:71], v[212:215], v[204:207], v[68:71]
	v_mfma_f32_16x16x32_bf16 v[68:71], v[240:243], v[208:211], v[68:71]
	v_mfma_f32_16x16x32_bf16 v[64:67], v[244:247], v[204:207], v[64:67]
	v_mfma_f32_16x16x32_bf16 v[64:67], v[248:251], v[208:211], v[64:67]
	s_setprio 0
	s_mov_b32 m0, s42
	v_lshl_add_u64 v[144:145], v[252:253], 0, s[16:17]
	s_barrier
	ds_read_b128 v[180:183], v150 offset:49152
	v_xor_b32_e32 v211, 64, v150
	ds_read_b128 v[184:187], v211 offset:49152
	ds_read_b128 v[188:191], v150 offset:51200
	ds_read_b128 v[192:195], v211 offset:51200
	ds_read_b128 v[196:199], v150 offset:53248
	ds_read_b128 v[200:203], v211 offset:53248
	ds_read_b128 v[204:207], v150 offset:55296
	ds_read_b128 v[208:211], v211 offset:55296
	global_load_lds_dwordx4 v[144:145], off
	v_lshl_add_u64 v[144:145], v[234:235], 0, s[16:17]
	s_mov_b32 m0, s43
	s_nop 0
	global_load_lds_dwordx4 v[144:145], off
	s_barrier
	s_waitcnt lgkmcnt(0)
	s_setprio 1
	s_waitcnt lgkmcnt(0)
	v_mfma_f32_16x16x32_bf16 v[60:63], v[140:143], v[180:183], v[60:63]
	v_mfma_f32_16x16x32_bf16 v[60:63], v[154:157], v[184:187], v[60:63]
	v_mfma_f32_16x16x32_bf16 v[56:59], v[158:161], v[180:183], v[56:59]
	v_mfma_f32_16x16x32_bf16 v[56:59], v[176:179], v[184:187], v[56:59]
	v_mfma_f32_16x16x32_bf16 v[44:47], v[140:143], v[188:191], v[44:47]
	v_mfma_f32_16x16x32_bf16 v[44:47], v[154:157], v[192:195], v[44:47]
	v_mfma_f32_16x16x32_bf16 v[40:43], v[158:161], v[188:191], v[40:43]
	v_mfma_f32_16x16x32_bf16 v[40:43], v[176:179], v[192:195], v[40:43]
	v_mfma_f32_16x16x32_bf16 v[28:31], v[140:143], v[196:199], v[28:31]
	v_mfma_f32_16x16x32_bf16 v[28:31], v[154:157], v[200:203], v[28:31]
	v_mfma_f32_16x16x32_bf16 v[24:27], v[158:161], v[196:199], v[24:27]
	v_mfma_f32_16x16x32_bf16 v[24:27], v[176:179], v[200:203], v[24:27]
	v_mfma_f32_16x16x32_bf16 v[12:15], v[140:143], v[204:207], v[12:15]
	v_mfma_f32_16x16x32_bf16 v[12:15], v[154:157], v[208:211], v[12:15]
	v_mfma_f32_16x16x32_bf16 v[8:11], v[158:161], v[204:207], v[8:11]
	v_mfma_f32_16x16x32_bf16 v[8:11], v[176:179], v[208:211], v[8:11]
	s_setprio 0
	s_barrier
	s_add_u32 s28, s28, 0x80080
	s_addc_u32 s29, s29, 0
	s_add_i32 s30, s30, s36
	v_lshl_add_u64 v[140:141], s[28:29], 0, v[164:165]
	s_mov_b32 m0, s30
	s_nop 0
	global_load_lds_dwordx4 v[140:141], off
	v_lshl_add_u64 v[140:141], s[28:29], 0, v[166:167]
	s_add_i32 m0, s30, 0x2000
	s_nop 0
	global_load_lds_dwordx4 v[140:141], off
	s_waitcnt vmcnt(6)
	s_barrier
	s_setprio 1
	v_mfma_f32_16x16x32_bf16 v[52:55], v[212:215], v[180:183], v[52:55]
	v_mfma_f32_16x16x32_bf16 v[52:55], v[240:243], v[184:187], v[52:55]
	v_mfma_f32_16x16x32_bf16 v[48:51], v[244:247], v[180:183], v[48:51]
	v_mfma_f32_16x16x32_bf16 v[48:51], v[248:251], v[184:187], v[48:51]
	v_mfma_f32_16x16x32_bf16 v[36:39], v[212:215], v[188:191], v[36:39]
	v_mfma_f32_16x16x32_bf16 v[36:39], v[240:243], v[192:195], v[36:39]
	v_mfma_f32_16x16x32_bf16 v[32:35], v[244:247], v[188:191], v[32:35]
	v_mfma_f32_16x16x32_bf16 v[32:35], v[248:251], v[192:195], v[32:35]
	v_mfma_f32_16x16x32_bf16 v[20:23], v[212:215], v[196:199], v[20:23]
	v_mfma_f32_16x16x32_bf16 v[20:23], v[240:243], v[200:203], v[20:23]
	v_mfma_f32_16x16x32_bf16 v[16:19], v[244:247], v[196:199], v[16:19]
	v_mfma_f32_16x16x32_bf16 v[16:19], v[248:251], v[200:203], v[16:19]
	v_mfma_f32_16x16x32_bf16 v[4:7], v[212:215], v[204:207], v[4:7]
	v_mfma_f32_16x16x32_bf16 v[4:7], v[240:243], v[208:211], v[4:7]
	v_mfma_f32_16x16x32_bf16 v[0:3], v[244:247], v[204:207], v[0:3]
	v_mfma_f32_16x16x32_bf16 v[0:3], v[248:251], v[208:211], v[0:3]
	s_setprio 0
	s_add_i32 s49, s49, 2
	s_add_u32 s26, s26, 0x100
	s_addc_u32 s27, s27, 0
	s_add_u32 s33, s33, 0x100
	s_addc_u32 s48, s48, 0
	s_cmp_gt_u32 s49, 29
	s_barrier
	s_cbranch_scc0 .LBB0_599
	v_lshl_add_u32 v142, s12, 8, v146
	v_ashrrev_i32_e32 v143, 31, v142
	v_lshl_add_u64 v[144:145], v[142:143], 2, s[14:15]
	global_load_dword v179, v[144:145], off
	global_load_dword v180, v[144:145], off offset:64
	global_load_dword v181, v[144:145], off offset:128
	global_load_dword v182, v[144:145], off offset:192
	global_load_dword v183, v[144:145], off offset:512
	global_load_dword v184, v[144:145], off offset:576
	global_load_dword v185, v[144:145], off offset:640
	global_load_dword v186, v[144:145], off offset:704
	v_lshl_or_b32 v140, s0, 8, v148
	v_lshlrev_b64 v[156:157], 13, v[142:143]
	v_ashrrev_i32_e32 v141, 31, v140
	v_lshl_add_u64 v[156:157], s[96:97], 0, v[156:157]
	v_lshl_add_u64 v[158:159], v[140:141], 1, v[156:157]
	s_cmp_gt_i32 s0, 7
	s_cselect_b64 s[26:27], -1, 0
	s_cmp_lt_i32 s0, 8
	s_waitcnt vmcnt(0)
	v_fmamk_f32 v154, v179, 0x3a000000, v152
	v_rsq_f32_e32 v154, v154
	s_nop 0
	v_pk_mul_f32 v[126:127], v[126:127], v[154:155] op_sel_hi:[1,0]
	v_pk_mul_f32 v[124:125], v[124:125], v[154:155] op_sel_hi:[1,0]
	v_pk_mul_f32 v[120:121], v[120:121], v[154:155] op_sel_hi:[1,0]
	v_pk_mul_f32 v[122:123], v[122:123], v[154:155] op_sel_hi:[1,0]
	v_pk_mul_f32 v[156:157], v[118:119], v[154:155] op_sel_hi:[1,0]
	v_pk_mul_f32 v[160:161], v[116:117], v[154:155] op_sel_hi:[1,0]
	v_pk_mul_f32 v[176:177], v[114:115], v[154:155] op_sel_hi:[1,0]
	v_pk_mul_f32 v[154:155], v[112:113], v[154:155] op_sel_hi:[1,0]
	v_mul_f32_e32 v112, 0x3d372713, v124
	v_mul_f32_e32 v113, 0x3d372713, v120
	v_mul_f32_e32 v114, 0x3d372713, v125
	v_mul_f32_e32 v115, 0x3d372713, v121
	v_mul_f32_e32 v116, 0x3d372713, v126
	v_mul_f32_e32 v118, 0x3d372713, v127
	v_mul_f32_e32 v117, 0x3d372713, v122
	v_mul_f32_e32 v119, 0x3d372713, v123
	v_mul_f32_e32 v112, v124, v112
	v_mul_f32_e32 v113, v120, v113
	v_mul_f32_e32 v114, v125, v114
	v_mul_f32_e32 v115, v121, v115
	v_mul_f32_e32 v116, v126, v116
	v_mul_f32_e32 v118, v127, v118
	v_mul_f32_e32 v117, v122, v117
	v_mul_f32_e32 v119, v123, v119
	v_fma_f32 v112, v124, v112, v124
	v_fma_f32 v113, v120, v113, v120
	v_fma_f32 v114, v125, v114, v125
	v_fma_f32 v115, v121, v115, v121
	v_fma_f32 v116, v126, v116, v126
	v_fma_f32 v118, v127, v118, v127
	v_fma_f32 v117, v122, v117, v122
	v_fma_f32 v119, v123, v119, v123
	v_mul_f32_e32 v112, 0x3f4c422a, v112
	v_mul_f32_e32 v113, 0x3f4c422a, v113
	v_mul_f32_e32 v114, 0x3f4c422a, v114
	v_mul_f32_e32 v115, 0x3f4c422a, v115
	v_mul_f32_e32 v116, 0x3f4c422a, v116
	v_mul_f32_e32 v118, 0x3f4c422a, v118
	v_mul_f32_e32 v117, 0x3f4c422a, v117
	v_mul_f32_e32 v119, 0x3f4c422a, v119
	v_mul_f32_e32 v112, 0xc038aa3b, v112
	v_mul_f32_e32 v113, 0xc038aa3b, v113
	v_mul_f32_e32 v114, 0xc038aa3b, v114
	v_mul_f32_e32 v115, 0xc038aa3b, v115
	v_mul_f32_e32 v116, 0xc038aa3b, v116
	v_mul_f32_e32 v118, 0xc038aa3b, v118
	v_mul_f32_e32 v117, 0xc038aa3b, v117
	v_mul_f32_e32 v119, 0xc038aa3b, v119
	v_exp_f32_e32 v112, v112
	v_exp_f32_e32 v113, v113
	v_exp_f32_e32 v114, v114
	v_exp_f32_e32 v115, v115
	v_exp_f32_e32 v116, v116
	v_exp_f32_e32 v118, v118
	v_exp_f32_e32 v117, v117
	v_exp_f32_e32 v119, v119
	v_add_f32_e32 v112, 1.0, v112
	v_add_f32_e32 v113, 1.0, v113
	v_add_f32_e32 v114, 1.0, v114
	v_add_f32_e32 v115, 1.0, v115
	v_add_f32_e32 v116, 1.0, v116
	v_add_f32_e32 v118, 1.0, v118
	v_add_f32_e32 v117, 1.0, v117
	v_add_f32_e32 v119, 1.0, v119
	v_rcp_f32_e32 v112, v112
	v_rcp_f32_e32 v113, v113
	v_rcp_f32_e32 v114, v114
	v_rcp_f32_e32 v171, v115
	v_rcp_f32_e32 v173, v116
	v_rcp_f32_e32 v175, v118
	v_rcp_f32_e32 v117, v117
	v_rcp_f32_e32 v178, v119
	v_mul_f32_e32 v116, v124, v112
	v_mul_f32_e32 v119, v120, v113
	v_mul_f32_e32 v115, v125, v114
	v_mul_f32_e32 v118, v121, v171
	v_mul_f32_e32 v113, v126, v173
	v_mul_f32_e32 v112, v127, v175
	v_cvt_pk_bf16_f32 v120, v116, v115
	v_cvt_pk_bf16_f32 v121, v113, v112
	v_mul_f32_e32 v117, v122, v117
	v_mul_f32_e32 v114, v123, v178
	v_cvt_pk_bf16_f32 v122, v119, v118
	v_cvt_pk_bf16_f32 v123, v117, v114
	global_store_dwordx4 v[158:159], v[120:123], off
	v_mul_f32_e32 v169, 0x3d372713, v160
	v_mul_f32_e32 v169, v160, v169
	v_mul_f32_e32 v121, 0x3d372713, v161
	v_mul_f32_e32 v121, v161, v121
	v_fma_f32 v121, v161, v121, v161
	v_mul_f32_e32 v121, 0x3f4c422a, v121
	v_mul_f32_e32 v121, 0xc038aa3b, v121
	v_mul_f32_e32 v120, 0x3d372713, v154
	v_exp_f32_e32 v121, v121
	v_mul_f32_e32 v120, v154, v120
	v_fma_f32 v169, v160, v169, v160
	v_fma_f32 v120, v154, v120, v154
	v_mul_f32_e32 v169, 0x3f4c422a, v169
	v_mul_f32_e32 v120, 0x3f4c422a, v120
	v_mul_f32_e32 v169, 0xc038aa3b, v169
	v_mul_f32_e32 v120, 0xc038aa3b, v120
	v_add_f32_e32 v121, 1.0, v121
	v_exp_f32_e32 v169, v169
	v_exp_f32_e32 v120, v120
	v_rcp_f32_e32 v123, v121
	v_mul_f32_e32 v121, 0x3d372713, v155
	v_mul_f32_e32 v121, v155, v121
	v_fma_f32 v121, v155, v121, v155
	v_mul_f32_e32 v121, 0x3f4c422a, v121
	v_add_f32_e32 v169, 1.0, v169
	v_add_f32_e32 v120, 1.0, v120
	v_mul_f32_e32 v121, 0xc038aa3b, v121
	v_rcp_f32_e32 v122, v169
	v_rcp_f32_e32 v120, v120
	v_exp_f32_e32 v124, v121
	v_mul_f32_e32 v125, 0x3d372713, v176
	v_mul_f32_e32 v125, v176, v125
	v_mul_f32_e32 v126, 0x3d372713, v157
	v_mul_f32_e32 v121, v160, v122
	v_mul_f32_e32 v122, v154, v120
	v_mul_f32_e32 v120, v161, v123
	v_add_f32_e32 v123, 1.0, v124
	v_mul_f32_e32 v124, 0x3d372713, v156
	v_fma_f32 v125, v176, v125, v176
	v_mul_f32_e32 v126, v157, v126
	v_mul_f32_e32 v127, 0x3d372713, v177
	v_mul_f32_e32 v124, v156, v124
	v_mul_f32_e32 v125, 0x3f4c422a, v125
	v_fma_f32 v126, v157, v126, v157
	v_mul_f32_e32 v127, v177, v127
	v_fma_f32 v124, v156, v124, v156
	v_mul_f32_e32 v125, 0xc038aa3b, v125
	v_mul_f32_e32 v126, 0x3f4c422a, v126
	v_fma_f32 v127, v177, v127, v177
	v_mul_f32_e32 v124, 0x3f4c422a, v124
	v_exp_f32_e32 v125, v125
	v_mul_f32_e32 v126, 0xc038aa3b, v126
	v_mul_f32_e32 v127, 0x3f4c422a, v127
	v_mul_f32_e32 v124, 0xc038aa3b, v124
	v_exp_f32_e32 v126, v126
	v_mul_f32_e32 v127, 0xc038aa3b, v127
	v_exp_f32_e32 v124, v124
	v_exp_f32_e32 v127, v127
	v_rcp_f32_e32 v123, v123
	v_add_f32_e32 v125, 1.0, v125
	v_rcp_f32_e32 v154, v125
	v_add_f32_e32 v125, 1.0, v126
	v_add_f32_e32 v124, 1.0, v124
	v_rcp_f32_e32 v126, v125
	v_add_f32_e32 v125, 1.0, v127
	v_mul_f32_e32 v123, v155, v123
	v_rcp_f32_e32 v124, v124
	v_rcp_f32_e32 v155, v125
	v_mul_f32_e32 v127, v176, v154
	v_cvt_pk_bf16_f32 v154, v121, v120
	v_mul_f32_e32 v125, v156, v124
	v_mul_f32_e32 v124, v157, v126
	v_mul_f32_e32 v126, v177, v155
	v_cvt_pk_bf16_f32 v155, v125, v124
	v_cvt_pk_bf16_f32 v156, v122, v123
	v_cvt_pk_bf16_f32 v157, v127, v126
	global_store_dwordx4 v[158:159], v[154:157], off offset:256
	s_cbranch_scc1 .LBB0_604
	v_mul_f32_e32 v119, v119, v119
	v_fmac_f32_e32 v119, v116, v116
	v_mul_f32_e32 v116, v118, v118
	v_fmac_f32_e32 v116, v115, v115
	v_add_f32_e32 v115, v119, v116
	v_mul_f32_e32 v116, v117, v117
	v_fmac_f32_e32 v116, v113, v113
	v_mul_f32_e32 v114, v114, v114
	v_add_f32_e32 v113, v116, v115
	v_fmac_f32_e32 v114, v112, v112
	v_add_f32_e32 v112, v114, v113
	v_mul_f32_e32 v113, v122, v122
	v_fmac_f32_e32 v113, v121, v121
	v_add_f32_e32 v112, v113, v112
	v_mul_f32_e32 v113, v123, v123
	v_fmac_f32_e32 v113, v120, v120
	v_add_f32_e32 v112, v113, v112
	v_mul_f32_e32 v113, v127, v127
	v_fmac_f32_e32 v113, v125, v125
	v_add_f32_e32 v112, v113, v112
	v_mul_f32_e32 v113, v126, v126
	v_fmac_f32_e32 v113, v124, v124
	v_and_b32_e32 v114, 64, v153
	v_add_f32_e32 v112, v113, v112
	v_xor_b32_e32 v113, 16, v153
	v_add_u32_e32 v114, 64, v114
	v_cmp_lt_i32_e32 vcc, v113, v114
	s_nop 1
	v_cndmask_b32_e32 v113, v153, v113, vcc
	v_lshlrev_b32_e32 v113, 2, v113
	ds_bpermute_b32 v113, v113, v112
	s_waitcnt lgkmcnt(0)
	v_add_f32_e32 v112, v112, v113
	v_xor_b32_e32 v113, 32, v153
	v_cmp_lt_i32_e32 vcc, v113, v114
	s_nop 1
	v_cndmask_b32_e32 v113, v153, v113, vcc
	v_lshlrev_b32_e32 v113, 2, v113
	ds_bpermute_b32 v113, v113, v112
	s_and_saveexec_b64 s[0:1], s[8:9]
	s_cbranch_execz .LBB0_603
	v_lshl_add_u64 v[114:115], v[142:143], 2, s[4:5]
	s_waitcnt lgkmcnt(0)
	v_add_f32_e32 v112, v112, v113
	global_atomic_add_f32 v[114:115], v112, off

.LBB0_760:
	ds_read_b128 v[140:143], v145
	v_xor_b32_e32 v161, 64, v145
	ds_read_b128 v[150:153], v161
	ds_read_b128 v[154:157], v145 offset:2048
	ds_read_b128 v[158:161], v161 offset:2048
	s_add_u32 s22, s20, 0xfff00080
	s_addc_u32 s23, s21, -1
	s_cmp_eq_u32 s45, 28
	s_cselect_b32 s25, s1, s23
	s_cselect_b32 s24, s9, s22
	s_cselect_b32 s23, s13, s44
	s_cselect_b32 s22, s15, s43
	v_lshl_add_u64 v[208:209], s[20:21], 0, v[132:133]
	s_add_i32 m0, s29, 0xc000
	ds_read_b128 v[176:179], v146
	v_xor_b32_e32 v207, 64, v146
	ds_read_b128 v[180:183], v207
	ds_read_b128 v[184:187], v146 offset:2048
	ds_read_b128 v[188:191], v207 offset:2048
	ds_read_b128 v[192:195], v146 offset:4096
	ds_read_b128 v[196:199], v207 offset:4096
	ds_read_b128 v[200:203], v146 offset:6144
	ds_read_b128 v[204:207], v207 offset:6144
	global_load_lds_dwordx4 v[208:209], off
	v_lshl_add_u64 v[208:209], s[20:21], 0, v[134:135]
	s_add_i32 m0, s29, 0xe000
	s_nop 0
	global_load_lds_dwordx4 v[208:209], off
	s_waitcnt lgkmcnt(8)
	s_barrier
	s_waitcnt lgkmcnt(0)
	s_setprio 1
	s_waitcnt lgkmcnt(0)
	v_mfma_f32_16x16x32_bf16 v[124:127], v[140:143], v[176:179], v[124:127]
	v_mfma_f32_16x16x32_bf16 v[124:127], v[150:153], v[180:183], v[124:127]
	v_mfma_f32_16x16x32_bf16 v[120:123], v[154:157], v[176:179], v[120:123]
	v_mfma_f32_16x16x32_bf16 v[120:123], v[158:161], v[180:183], v[120:123]
	v_mfma_f32_16x16x32_bf16 v[108:111], v[140:143], v[184:187], v[108:111]
	v_mfma_f32_16x16x32_bf16 v[108:111], v[150:153], v[188:191], v[108:111]
	v_mfma_f32_16x16x32_bf16 v[104:107], v[154:157], v[184:187], v[104:107]
	v_mfma_f32_16x16x32_bf16 v[104:107], v[158:161], v[188:191], v[104:107]
	v_mfma_f32_16x16x32_bf16 v[92:95], v[140:143], v[192:195], v[92:95]
	v_mfma_f32_16x16x32_bf16 v[92:95], v[150:153], v[196:199], v[92:95]
	v_mfma_f32_16x16x32_bf16 v[88:91], v[154:157], v[192:195], v[88:91]
	v_mfma_f32_16x16x32_bf16 v[88:91], v[158:161], v[196:199], v[88:91]
	v_mfma_f32_16x16x32_bf16 v[76:79], v[140:143], v[200:203], v[76:79]
	v_mfma_f32_16x16x32_bf16 v[76:79], v[150:153], v[204:207], v[76:79]
	v_mfma_f32_16x16x32_bf16 v[72:75], v[154:157], v[200:203], v[72:75]
	v_mfma_f32_16x16x32_bf16 v[72:75], v[158:161], v[204:207], v[72:75]
	s_setprio 0
	s_barrier
	s_add_i32 s46, s41, s28
	v_lshl_add_u64 v[216:217], s[22:23], 0, v[164:165]
	s_mov_b32 m0, s46
	ds_read_b128 v[208:211], v147
	v_xor_b32_e32 v243, 64, v147
	ds_read_b128 v[212:215], v243
	ds_read_b128 v[236:239], v147 offset:2048
	ds_read_b128 v[240:243], v243 offset:2048
	global_load_lds_dwordx4 v[216:217], off
	v_lshl_add_u64 v[234:235], s[22:23], 0, v[166:167]
	s_add_i32 m0, s46, 0x2000
	s_nop 0
	global_load_lds_dwordx4 v[234:235], off
	s_barrier
	s_waitcnt lgkmcnt(0)
	s_setprio 1
	s_waitcnt lgkmcnt(0)
	v_mfma_f32_16x16x32_bf16 v[116:119], v[208:211], v[176:179], v[116:119]
	v_mfma_f32_16x16x32_bf16 v[116:119], v[212:215], v[180:183], v[116:119]
	v_mfma_f32_16x16x32_bf16 v[112:115], v[236:239], v[176:179], v[112:115]
	v_mfma_f32_16x16x32_bf16 v[112:115], v[240:243], v[180:183], v[112:115]
	v_mfma_f32_16x16x32_bf16 v[100:103], v[208:211], v[184:187], v[100:103]
	v_mfma_f32_16x16x32_bf16 v[100:103], v[212:215], v[188:191], v[100:103]
	v_mfma_f32_16x16x32_bf16 v[96:99], v[236:239], v[184:187], v[96:99]
	v_mfma_f32_16x16x32_bf16 v[96:99], v[240:243], v[188:191], v[96:99]
	v_mfma_f32_16x16x32_bf16 v[84:87], v[208:211], v[192:195], v[84:87]
	v_mfma_f32_16x16x32_bf16 v[84:87], v[212:215], v[196:199], v[84:87]
	v_mfma_f32_16x16x32_bf16 v[80:83], v[236:239], v[192:195], v[80:83]
	v_mfma_f32_16x16x32_bf16 v[80:83], v[240:243], v[196:199], v[80:83]
	v_mfma_f32_16x16x32_bf16 v[68:71], v[208:211], v[200:203], v[68:71]
	v_mfma_f32_16x16x32_bf16 v[68:71], v[212:215], v[204:207], v[68:71]
	v_mfma_f32_16x16x32_bf16 v[64:67], v[236:239], v[200:203], v[64:67]
	v_mfma_f32_16x16x32_bf16 v[64:67], v[240:243], v[204:207], v[64:67]
	s_setprio 0
	s_mov_b32 m0, s29
	v_lshl_add_u64 v[244:245], s[24:25], 0, v[128:129]
	s_barrier
	ds_read_b128 v[176:179], v146 offset:16384
	v_xor_b32_e32 v207, 64, v146
	ds_read_b128 v[180:183], v207 offset:16384
	ds_read_b128 v[184:187], v146 offset:18432
	ds_read_b128 v[188:191], v207 offset:18432
	ds_read_b128 v[192:195], v146 offset:20480
	ds_read_b128 v[196:199], v207 offset:20480
	ds_read_b128 v[200:203], v146 offset:22528
	ds_read_b128 v[204:207], v207 offset:22528
	global_load_lds_dwordx4 v[244:245], off
	v_lshl_add_u64 v[246:247], s[24:25], 0, v[130:131]
	s_mov_b32 m0, s30
	s_nop 0
	global_load_lds_dwordx4 v[246:247], off
	s_barrier
	s_waitcnt lgkmcnt(0)
	s_setprio 1
	s_waitcnt lgkmcnt(0)
	v_mfma_f32_16x16x32_bf16 v[60:63], v[140:143], v[176:179], v[60:63]
	v_mfma_f32_16x16x32_bf16 v[60:63], v[150:153], v[180:183], v[60:63]
	v_mfma_f32_16x16x32_bf16 v[56:59], v[154:157], v[176:179], v[56:59]
	v_mfma_f32_16x16x32_bf16 v[56:59], v[158:161], v[180:183], v[56:59]
	v_mfma_f32_16x16x32_bf16 v[44:47], v[140:143], v[184:187], v[44:47]
	v_mfma_f32_16x16x32_bf16 v[44:47], v[150:153], v[188:191], v[44:47]
	v_mfma_f32_16x16x32_bf16 v[40:43], v[154:157], v[184:187], v[40:43]
	v_mfma_f32_16x16x32_bf16 v[40:43], v[158:161], v[188:191], v[40:43]
	v_mfma_f32_16x16x32_bf16 v[28:31], v[140:143], v[192:195], v[28:31]
	v_mfma_f32_16x16x32_bf16 v[28:31], v[150:153], v[196:199], v[28:31]
	v_mfma_f32_16x16x32_bf16 v[24:27], v[154:157], v[192:195], v[24:27]
	v_mfma_f32_16x16x32_bf16 v[24:27], v[158:161], v[196:199], v[24:27]
	v_mfma_f32_16x16x32_bf16 v[12:15], v[140:143], v[200:203], v[12:15]
	v_mfma_f32_16x16x32_bf16 v[12:15], v[150:153], v[204:207], v[12:15]
	v_mfma_f32_16x16x32_bf16 v[8:11], v[154:157], v[200:203], v[8:11]
	v_mfma_f32_16x16x32_bf16 v[8:11], v[158:161], v[204:207], v[8:11]
	s_setprio 0
	s_barrier
	s_add_u32 s46, s22, 0x80000
	s_addc_u32 s47, s23, 0
	s_add_i32 s48, s42, s28
	v_lshl_add_u64 v[140:141], s[46:47], 0, v[164:165]
	s_mov_b32 m0, s48
	s_nop 0
	global_load_lds_dwordx4 v[140:141], off
	v_lshl_add_u64 v[140:141], s[46:47], 0, v[166:167]
	s_add_i32 m0, s48, 0x2000
	s_nop 0
	global_load_lds_dwordx4 v[140:141], off
	s_waitcnt vmcnt(6)
	s_barrier
	s_setprio 1
	v_mfma_f32_16x16x32_bf16 v[52:55], v[208:211], v[176:179], v[52:55]
	v_mfma_f32_16x16x32_bf16 v[52:55], v[212:215], v[180:183], v[52:55]
	v_mfma_f32_16x16x32_bf16 v[48:51], v[236:239], v[176:179], v[48:51]
	v_mfma_f32_16x16x32_bf16 v[48:51], v[240:243], v[180:183], v[48:51]
	v_mfma_f32_16x16x32_bf16 v[36:39], v[208:211], v[184:187], v[36:39]
	v_mfma_f32_16x16x32_bf16 v[36:39], v[212:215], v[188:191], v[36:39]
	v_mfma_f32_16x16x32_bf16 v[32:35], v[236:239], v[184:187], v[32:35]
	v_mfma_f32_16x16x32_bf16 v[32:35], v[240:243], v[188:191], v[32:35]
	v_mfma_f32_16x16x32_bf16 v[20:23], v[208:211], v[192:195], v[20:23]
	v_mfma_f32_16x16x32_bf16 v[20:23], v[212:215], v[196:199], v[20:23]
	v_mfma_f32_16x16x32_bf16 v[16:19], v[236:239], v[192:195], v[16:19]
	v_mfma_f32_16x16x32_bf16 v[16:19], v[240:243], v[196:199], v[16:19]
	v_mfma_f32_16x16x32_bf16 v[4:7], v[208:211], v[200:203], v[4:7]
	v_mfma_f32_16x16x32_bf16 v[4:7], v[212:215], v[204:207], v[4:7]
	v_mfma_f32_16x16x32_bf16 v[0:3], v[236:239], v[200:203], v[0:3]
	v_mfma_f32_16x16x32_bf16 v[0:3], v[240:243], v[204:207], v[0:3]
	s_setprio 0
	s_add_i32 s46, 0, 0x18000
	v_add_u32_e32 v149, s46, v144
	s_barrier
	ds_read_b128 v[140:143], v149
	v_xor_b32_e32 v161, 64, v149
	ds_read_b128 v[150:153], v161
	ds_read_b128 v[154:157], v149 offset:2048
	ds_read_b128 v[158:161], v161 offset:2048
	s_add_u32 s24, s24, 0x100000
	s_addc_u32 s25, s25, 0
	s_mov_b32 m0, s31
	v_lshl_add_u64 v[208:209], s[24:25], 0, v[128:129]
	ds_read_b128 v[176:179], v146 offset:32768
	v_xor_b32_e32 v207, 64, v146
	ds_read_b128 v[180:183], v207 offset:32768
	ds_read_b128 v[184:187], v146 offset:34816
	ds_read_b128 v[188:191], v207 offset:34816
	ds_read_b128 v[192:195], v146 offset:36864
	ds_read_b128 v[196:199], v207 offset:36864
	ds_read_b128 v[200:203], v146 offset:38912
	ds_read_b128 v[204:207], v207 offset:38912
	global_load_lds_dwordx4 v[208:209], off
	v_lshl_add_u64 v[208:209], s[24:25], 0, v[130:131]
	s_mov_b32 m0, s33
	s_nop 0
	global_load_lds_dwordx4 v[208:209], off
	s_waitcnt lgkmcnt(8)
	s_barrier
	s_waitcnt lgkmcnt(0)
	s_setprio 1
	s_waitcnt lgkmcnt(0)
	v_mfma_f32_16x16x32_bf16 v[124:127], v[140:143], v[176:179], v[124:127]
	v_mfma_f32_16x16x32_bf16 v[124:127], v[150:153], v[180:183], v[124:127]
	v_mfma_f32_16x16x32_bf16 v[120:123], v[154:157], v[176:179], v[120:123]
	v_mfma_f32_16x16x32_bf16 v[120:123], v[158:161], v[180:183], v[120:123]
	v_mfma_f32_16x16x32_bf16 v[108:111], v[140:143], v[184:187], v[108:111]
	v_mfma_f32_16x16x32_bf16 v[108:111], v[150:153], v[188:191], v[108:111]
	v_mfma_f32_16x16x32_bf16 v[104:107], v[154:157], v[184:187], v[104:107]
	v_mfma_f32_16x16x32_bf16 v[104:107], v[158:161], v[188:191], v[104:107]
	v_mfma_f32_16x16x32_bf16 v[92:95], v[140:143], v[192:195], v[92:95]
	v_mfma_f32_16x16x32_bf16 v[92:95], v[150:153], v[196:199], v[92:95]
	v_mfma_f32_16x16x32_bf16 v[88:91], v[154:157], v[192:195], v[88:91]
	v_mfma_f32_16x16x32_bf16 v[88:91], v[158:161], v[196:199], v[88:91]
	v_mfma_f32_16x16x32_bf16 v[76:79], v[140:143], v[200:203], v[76:79]
	v_mfma_f32_16x16x32_bf16 v[76:79], v[150:153], v[204:207], v[76:79]
	v_mfma_f32_16x16x32_bf16 v[72:75], v[154:157], v[200:203], v[72:75]
	v_mfma_f32_16x16x32_bf16 v[72:75], v[158:161], v[204:207], v[72:75]
	s_setprio 0
	s_barrier
	s_add_i32 s24, 0, 0x1c000
	s_add_i32 s25, s46, s28
	v_add_u32_e32 v149, s24, v144
	v_lshl_add_u64 v[216:217], v[216:217], 0, s[10:11]
	s_mov_b32 m0, s25
	ds_read_b128 v[208:211], v149
	v_xor_b32_e32 v243, 64, v149
	ds_read_b128 v[212:215], v243
	ds_read_b128 v[236:239], v149 offset:2048
	ds_read_b128 v[240:243], v243 offset:2048
	global_load_lds_dwordx4 v[216:217], off
	v_lshl_add_u64 v[216:217], v[234:235], 0, s[10:11]
	s_add_i32 m0, s25, 0x2000
	s_nop 0
	global_load_lds_dwordx4 v[216:217], off
	s_barrier
	s_waitcnt lgkmcnt(0)
	s_setprio 1
	s_waitcnt lgkmcnt(0)
	v_mfma_f32_16x16x32_bf16 v[116:119], v[208:211], v[176:179], v[116:119]
	v_mfma_f32_16x16x32_bf16 v[116:119], v[212:215], v[180:183], v[116:119]
	v_mfma_f32_16x16x32_bf16 v[112:115], v[236:239], v[176:179], v[112:115]
	v_mfma_f32_16x16x32_bf16 v[112:115], v[240:243], v[180:183], v[112:115]
	v_mfma_f32_16x16x32_bf16 v[100:103], v[208:211], v[184:187], v[100:103]
	v_mfma_f32_16x16x32_bf16 v[100:103], v[212:215], v[188:191], v[100:103]
	v_mfma_f32_16x16x32_bf16 v[96:99], v[236:239], v[184:187], v[96:99]
	v_mfma_f32_16x16x32_bf16 v[96:99], v[240:243], v[188:191], v[96:99]
	v_mfma_f32_16x16x32_bf16 v[84:87], v[208:211], v[192:195], v[84:87]
	v_mfma_f32_16x16x32_bf16 v[84:87], v[212:215], v[196:199], v[84:87]
	v_mfma_f32_16x16x32_bf16 v[80:83], v[236:239], v[192:195], v[80:83]
	v_mfma_f32_16x16x32_bf16 v[80:83], v[240:243], v[196:199], v[80:83]
	v_mfma_f32_16x16x32_bf16 v[68:71], v[208:211], v[200:203], v[68:71]
	v_mfma_f32_16x16x32_bf16 v[68:71], v[212:215], v[204:207], v[68:71]
	v_mfma_f32_16x16x32_bf16 v[64:67], v[236:239], v[200:203], v[64:67]
	v_mfma_f32_16x16x32_bf16 v[64:67], v[240:243], v[204:207], v[64:67]
	s_setprio 0
	s_mov_b32 m0, s37
	v_lshl_add_u64 v[216:217], v[244:245], 0, s[10:11]
	s_barrier
	ds_read_b128 v[176:179], v146 offset:49152
	v_xor_b32_e32 v207, 64, v146
	ds_read_b128 v[180:183], v207 offset:49152
	ds_read_b128 v[184:187], v146 offset:51200
	ds_read_b128 v[188:191], v207 offset:51200
	ds_read_b128 v[192:195], v146 offset:53248
	ds_read_b128 v[196:199], v207 offset:53248
	ds_read_b128 v[200:203], v146 offset:55296
	ds_read_b128 v[204:207], v207 offset:55296
	global_load_lds_dwordx4 v[216:217], off
	v_lshl_add_u64 v[216:217], v[246:247], 0, s[10:11]
	s_mov_b32 m0, s38
	s_nop 0
	global_load_lds_dwordx4 v[216:217], off
	s_barrier
	s_waitcnt lgkmcnt(0)
	s_setprio 1
	s_waitcnt lgkmcnt(0)
	v_mfma_f32_16x16x32_bf16 v[60:63], v[140:143], v[176:179], v[60:63]
	v_mfma_f32_16x16x32_bf16 v[60:63], v[150:153], v[180:183], v[60:63]
	v_mfma_f32_16x16x32_bf16 v[56:59], v[154:157], v[176:179], v[56:59]
	v_mfma_f32_16x16x32_bf16 v[56:59], v[158:161], v[180:183], v[56:59]
	v_mfma_f32_16x16x32_bf16 v[44:47], v[140:143], v[184:187], v[44:47]
	v_mfma_f32_16x16x32_bf16 v[44:47], v[150:153], v[188:191], v[44:47]
	v_mfma_f32_16x16x32_bf16 v[40:43], v[154:157], v[184:187], v[40:43]
	v_mfma_f32_16x16x32_bf16 v[40:43], v[158:161], v[188:191], v[40:43]
	v_mfma_f32_16x16x32_bf16 v[28:31], v[140:143], v[192:195], v[28:31]
	v_mfma_f32_16x16x32_bf16 v[28:31], v[150:153], v[196:199], v[28:31]
	v_mfma_f32_16x16x32_bf16 v[24:27], v[154:157], v[192:195], v[24:27]
	v_mfma_f32_16x16x32_bf16 v[24:27], v[158:161], v[196:199], v[24:27]
	v_mfma_f32_16x16x32_bf16 v[12:15], v[140:143], v[200:203], v[12:15]
	v_mfma_f32_16x16x32_bf16 v[12:15], v[150:153], v[204:207], v[12:15]
	v_mfma_f32_16x16x32_bf16 v[8:11], v[154:157], v[200:203], v[8:11]
	v_mfma_f32_16x16x32_bf16 v[8:11], v[158:161], v[204:207], v[8:11]
	s_setprio 0
	s_barrier
	s_add_u32 s22, s22, 0x80080
	s_addc_u32 s23, s23, 0
	s_add_i32 s24, s24, s28
	v_lshl_add_u64 v[140:141], s[22:23], 0, v[164:165]
	s_mov_b32 m0, s24
	s_nop 0
	global_load_lds_dwordx4 v[140:141], off
	v_lshl_add_u64 v[140:141], s[22:23], 0, v[166:167]
	s_add_i32 m0, s24, 0x2000
	s_nop 0
	global_load_lds_dwordx4 v[140:141], off
	s_waitcnt vmcnt(6)
	s_barrier
	s_setprio 1
	v_mfma_f32_16x16x32_bf16 v[52:55], v[208:211], v[176:179], v[52:55]
	v_mfma_f32_16x16x32_bf16 v[52:55], v[212:215], v[180:183], v[52:55]
	v_mfma_f32_16x16x32_bf16 v[48:51], v[236:239], v[176:179], v[48:51]
	v_mfma_f32_16x16x32_bf16 v[48:51], v[240:243], v[180:183], v[48:51]
	v_mfma_f32_16x16x32_bf16 v[36:39], v[208:211], v[184:187], v[36:39]
	v_mfma_f32_16x16x32_bf16 v[36:39], v[212:215], v[188:191], v[36:39]
	v_mfma_f32_16x16x32_bf16 v[32:35], v[236:239], v[184:187], v[32:35]
	v_mfma_f32_16x16x32_bf16 v[32:35], v[240:243], v[188:191], v[32:35]
	v_mfma_f32_16x16x32_bf16 v[20:23], v[208:211], v[192:195], v[20:23]
	v_mfma_f32_16x16x32_bf16 v[20:23], v[212:215], v[196:199], v[20:23]
	v_mfma_f32_16x16x32_bf16 v[16:19], v[236:239], v[192:195], v[16:19]
	v_mfma_f32_16x16x32_bf16 v[16:19], v[240:243], v[196:199], v[16:19]
	v_mfma_f32_16x16x32_bf16 v[4:7], v[208:211], v[200:203], v[4:7]
	v_mfma_f32_16x16x32_bf16 v[4:7], v[212:215], v[204:207], v[4:7]
	v_mfma_f32_16x16x32_bf16 v[0:3], v[236:239], v[200:203], v[0:3]
	v_mfma_f32_16x16x32_bf16 v[0:3], v[240:243], v[204:207], v[0:3]
	s_setprio 0
	s_add_i32 s45, s45, 2
	s_add_u32 s20, s20, 0x100
	s_addc_u32 s21, s21, 0
	s_add_u32 s43, s43, 0x100
	s_addc_u32 s44, s44, 0
	s_cmp_gt_u32 s45, 29
	s_barrier
	s_cbranch_scc0 .LBB0_760
	v_lshl_add_u32 v217, s8, 8, v163
	v_add_u32_e32 v217, s35, v217
	v_lshlrev_b32_e32 v208, 2, v217
	v_lshl_add_u32 v214, v225, 3, s36
	v_lshl_add_u32 v214, s0, 8, v214
	v_lshl_add_u32 v209, v217, 11, v214
	v_lshlrev_b32_e32 v209, 1, v209
	v_lshlrev_b32_e32 v210, 1, v209
	v_lshl_add_u32 v217, v225, 4, v163
	v_xor_b32_e32 v215, 16, v217
	v_lshlrev_b32_e32 v215, 2, v215
	v_xor_b32_e32 v216, 32, v217
	v_lshlrev_b32_e32 v216, 2, v216
	v_add_u32_e32 v211, 0x0, v209
	global_load_dwordx4 v[176:179], v211, s[80:81]
	global_load_dwordx4 v[180:183], v211, s[80:81] offset:256
	v_add_u32_e32 v211, 0x10000, v209
	global_load_dwordx4 v[192:195], v211, s[80:81]
	global_load_dwordx4 v[196:199], v211, s[80:81] offset:256
	s_waitcnt vmcnt(2)
	v_lshlrev_b32_e32 v184, 16, v176
	v_and_b32_e32 v185, 0xffff0000, v176
	v_lshlrev_b32_e32 v186, 16, v177
	v_and_b32_e32 v187, 0xffff0000, v177
	v_lshlrev_b32_e32 v188, 16, v178
	v_and_b32_e32 v189, 0xffff0000, v178
	v_lshlrev_b32_e32 v190, 16, v179
	v_and_b32_e32 v191, 0xffff0000, v179
	v_pk_add_f32 v[124:125], v[124:125], v[184:185]
	v_pk_add_f32 v[126:127], v[126:127], v[186:187]
	v_pk_add_f32 v[120:121], v[120:121], v[188:189]
	v_pk_add_f32 v[122:123], v[122:123], v[190:191]
	v_mul_f32_e32 v213, v124, v124
	v_fmac_f32_e32 v213, v125, v125
	v_fmac_f32_e32 v213, v126, v126
	v_fmac_f32_e32 v213, v127, v127
	v_fmac_f32_e32 v213, v120, v120
	v_fmac_f32_e32 v213, v121, v121
	v_fmac_f32_e32 v213, v122, v122
	v_fmac_f32_e32 v213, v123, v123
	v_cvt_pk_bf16_f32 v176, v124, v125
	v_cvt_pk_bf16_f32 v177, v126, v127
	v_cvt_pk_bf16_f32 v178, v120, v121
	v_cvt_pk_bf16_f32 v179, v122, v123
	v_add_u32_e32 v217, 0x0, v209
	global_store_dwordx4 v217, v[176:179], s[80:81]
	v_lshlrev_b32_e32 v184, 16, v180
	v_and_b32_e32 v185, 0xffff0000, v180
	v_lshlrev_b32_e32 v186, 16, v181
	v_and_b32_e32 v187, 0xffff0000, v181
	v_lshlrev_b32_e32 v188, 16, v182
	v_and_b32_e32 v189, 0xffff0000, v182
	v_lshlrev_b32_e32 v190, 16, v183
	v_and_b32_e32 v191, 0xffff0000, v183
	v_pk_add_f32 v[116:117], v[116:117], v[184:185]
	v_pk_add_f32 v[118:119], v[118:119], v[186:187]
	v_pk_add_f32 v[112:113], v[112:113], v[188:189]
	v_pk_add_f32 v[114:115], v[114:115], v[190:191]
	v_fmac_f32_e32 v213, v116, v116
	v_fmac_f32_e32 v213, v117, v117
	v_fmac_f32_e32 v213, v118, v118
	v_fmac_f32_e32 v213, v119, v119
	v_fmac_f32_e32 v213, v112, v112
	v_fmac_f32_e32 v213, v113, v113
	v_fmac_f32_e32 v213, v114, v114
	v_fmac_f32_e32 v213, v115, v115
	v_cvt_pk_bf16_f32 v180, v116, v117
	v_cvt_pk_bf16_f32 v181, v118, v119
	v_cvt_pk_bf16_f32 v182, v112, v113
	v_cvt_pk_bf16_f32 v183, v114, v115
	global_store_dwordx4 v217, v[180:183], s[80:81] offset:256
	ds_bpermute_b32 v214, v215, v213
	s_waitcnt lgkmcnt(0)
	v_add_f32_e32 v213, v213, v214
	ds_bpermute_b32 v214, v216, v213
	s_waitcnt lgkmcnt(0)
	v_add_f32_e32 v213, v213, v214
	s_mov_b64 exec, 0xffff
	global_atomic_add_f32 v208, v213, s[4:5]
	s_mov_b64 exec, -1
	v_add_u32_e32 v211, 0x20000, v209
	global_load_dwordx4 v[176:179], v211, s[80:81]
	global_load_dwordx4 v[180:183], v211, s[80:81] offset:256
	s_waitcnt vmcnt(5)
	v_lshlrev_b32_e32 v200, 16, v192
	v_and_b32_e32 v201, 0xffff0000, v192
	v_lshlrev_b32_e32 v202, 16, v193
	v_and_b32_e32 v203, 0xffff0000, v193
	v_lshlrev_b32_e32 v204, 16, v194
	v_and_b32_e32 v205, 0xffff0000, v194
	v_lshlrev_b32_e32 v206, 16, v195
	v_and_b32_e32 v207, 0xffff0000, v195
	v_pk_add_f32 v[108:109], v[108:109], v[200:201]
	v_pk_add_f32 v[110:111], v[110:111], v[202:203]
	v_pk_add_f32 v[104:105], v[104:105], v[204:205]
	v_pk_add_f32 v[106:107], v[106:107], v[206:207]
	v_mul_f32_e32 v213, v108, v108
	v_fmac_f32_e32 v213, v109, v109
	v_fmac_f32_e32 v213, v110, v110
	v_fmac_f32_e32 v213, v111, v111
	v_fmac_f32_e32 v213, v104, v104
	v_fmac_f32_e32 v213, v105, v105
	v_fmac_f32_e32 v213, v106, v106
	v_fmac_f32_e32 v213, v107, v107
	v_cvt_pk_bf16_f32 v192, v108, v109
	v_cvt_pk_bf16_f32 v193, v110, v111
	v_cvt_pk_bf16_f32 v194, v104, v105
	v_cvt_pk_bf16_f32 v195, v106, v107
	v_add_u32_e32 v217, 0x10000, v209
	global_store_dwordx4 v217, v[192:195], s[80:81]
	v_lshlrev_b32_e32 v200, 16, v196
	v_and_b32_e32 v201, 0xffff0000, v196
	v_lshlrev_b32_e32 v202, 16, v197
	v_and_b32_e32 v203, 0xffff0000, v197
	v_lshlrev_b32_e32 v204, 16, v198
	v_and_b32_e32 v205, 0xffff0000, v198
	v_lshlrev_b32_e32 v206, 16, v199
	v_and_b32_e32 v207, 0xffff0000, v199
	v_pk_add_f32 v[100:101], v[100:101], v[200:201]
	v_pk_add_f32 v[102:103], v[102:103], v[202:203]
	v_pk_add_f32 v[96:97], v[96:97], v[204:205]
	v_pk_add_f32 v[98:99], v[98:99], v[206:207]
	v_fmac_f32_e32 v213, v100, v100
	v_fmac_f32_e32 v213, v101, v101
	v_fmac_f32_e32 v213, v102, v102
	v_fmac_f32_e32 v213, v103, v103
	v_fmac_f32_e32 v213, v96, v96
	v_fmac_f32_e32 v213, v97, v97
	v_fmac_f32_e32 v213, v98, v98
	v_fmac_f32_e32 v213, v99, v99
	v_cvt_pk_bf16_f32 v196, v100, v101
	v_cvt_pk_bf16_f32 v197, v102, v103
	v_cvt_pk_bf16_f32 v198, v96, v97
	v_cvt_pk_bf16_f32 v199, v98, v99
	global_store_dwordx4 v217, v[196:199], s[80:81] offset:256
	ds_bpermute_b32 v214, v215, v213
	s_waitcnt lgkmcnt(0)
	v_add_f32_e32 v213, v213, v214
	ds_bpermute_b32 v214, v216, v213
	s_waitcnt lgkmcnt(0)
	v_add_f32_e32 v213, v213, v214
	s_mov_b64 exec, 0xffff
	global_atomic_add_f32 v208, v213, s[4:5] offset:64
	s_mov_b64 exec, -1
	v_add_u32_e32 v211, 0x30000, v209
	global_load_dwordx4 v[192:195], v211, s[80:81]
	global_load_dwordx4 v[196:199], v211, s[80:81] offset:256
	s_waitcnt vmcnt(5)
	v_lshlrev_b32_e32 v184, 16, v176
	v_and_b32_e32 v185, 0xffff0000, v176
	v_lshlrev_b32_e32 v186, 16, v177
	v_and_b32_e32 v187, 0xffff0000, v177
	v_lshlrev_b32_e32 v188, 16, v178
	v_and_b32_e32 v189, 0xffff0000, v178
	v_lshlrev_b32_e32 v190, 16, v179
	v_and_b32_e32 v191, 0xffff0000, v179
	v_pk_add_f32 v[92:93], v[92:93], v[184:185]
	v_pk_add_f32 v[94:95], v[94:95], v[186:187]
	v_pk_add_f32 v[88:89], v[88:89], v[188:189]
	v_pk_add_f32 v[90:91], v[90:91], v[190:191]
	v_mul_f32_e32 v213, v92, v92
	v_fmac_f32_e32 v213, v93, v93
	v_fmac_f32_e32 v213, v94, v94
	v_fmac_f32_e32 v213, v95, v95
	v_fmac_f32_e32 v213, v88, v88
	v_fmac_f32_e32 v213, v89, v89
	v_fmac_f32_e32 v213, v90, v90
	v_fmac_f32_e32 v213, v91, v91
	v_cvt_pk_bf16_f32 v176, v92, v93
	v_cvt_pk_bf16_f32 v177, v94, v95
	v_cvt_pk_bf16_f32 v178, v88, v89
	v_cvt_pk_bf16_f32 v179, v90, v91
	v_add_u32_e32 v217, 0x20000, v209
	global_store_dwordx4 v217, v[176:179], s[80:81]
	v_lshlrev_b32_e32 v184, 16, v180
	v_and_b32_e32 v185, 0xffff0000, v180
	v_lshlrev_b32_e32 v186, 16, v181
	v_and_b32_e32 v187, 0xffff0000, v181
	v_lshlrev_b32_e32 v188, 16, v182
	v_and_b32_e32 v189, 0xffff0000, v182
	v_lshlrev_b32_e32 v190, 16, v183
	v_and_b32_e32 v191, 0xffff0000, v183
	v_pk_add_f32 v[84:85], v[84:85], v[184:185]
	v_pk_add_f32 v[86:87], v[86:87], v[186:187]
	v_pk_add_f32 v[80:81], v[80:81], v[188:189]
	v_pk_add_f32 v[82:83], v[82:83], v[190:191]
	v_fmac_f32_e32 v213, v84, v84
	v_fmac_f32_e32 v213, v85, v85
	v_fmac_f32_e32 v213, v86, v86
	v_fmac_f32_e32 v213, v87, v87
	v_fmac_f32_e32 v213, v80, v80
	v_fmac_f32_e32 v213, v81, v81
	v_fmac_f32_e32 v213, v82, v82
	v_fmac_f32_e32 v213, v83, v83
	v_cvt_pk_bf16_f32 v180, v84, v85
	v_cvt_pk_bf16_f32 v181, v86, v87
	v_cvt_pk_bf16_f32 v182, v80, v81
	v_cvt_pk_bf16_f32 v183, v82, v83
	global_store_dwordx4 v217, v[180:183], s[80:81] offset:256
	ds_bpermute_b32 v214, v215, v213
	s_waitcnt lgkmcnt(0)
	v_add_f32_e32 v213, v213, v214
	ds_bpermute_b32 v214, v216, v213
	s_waitcnt lgkmcnt(0)
	v_add_f32_e32 v213, v213, v214
	s_mov_b64 exec, 0xffff
	global_atomic_add_f32 v208, v213, s[4:5] offset:128
	s_mov_b64 exec, -1
	v_add_u32_e32 v211, 0x80000, v209
	global_load_dwordx4 v[176:179], v211, s[80:81]
	global_load_dwordx4 v[180:183], v211, s[80:81] offset:256
	s_waitcnt vmcnt(5)
	v_lshlrev_b32_e32 v200, 16, v192
	v_and_b32_e32 v201, 0xffff0000, v192
	v_lshlrev_b32_e32 v202, 16, v193
	v_and_b32_e32 v203, 0xffff0000, v193
	v_lshlrev_b32_e32 v204, 16, v194
	v_and_b32_e32 v205, 0xffff0000, v194
	v_lshlrev_b32_e32 v206, 16, v195
	v_and_b32_e32 v207, 0xffff0000, v195
	v_pk_add_f32 v[76:77], v[76:77], v[200:201]
	v_pk_add_f32 v[78:79], v[78:79], v[202:203]
	v_pk_add_f32 v[72:73], v[72:73], v[204:205]
	v_pk_add_f32 v[74:75], v[74:75], v[206:207]
	v_mul_f32_e32 v213, v76, v76
	v_fmac_f32_e32 v213, v77, v77
	v_fmac_f32_e32 v213, v78, v78
	v_fmac_f32_e32 v213, v79, v79
	v_fmac_f32_e32 v213, v72, v72
	v_fmac_f32_e32 v213, v73, v73
	v_fmac_f32_e32 v213, v74, v74
	v_fmac_f32_e32 v213, v75, v75
	v_cvt_pk_bf16_f32 v192, v76, v77
	v_cvt_pk_bf16_f32 v193, v78, v79
	v_cvt_pk_bf16_f32 v194, v72, v73
	v_cvt_pk_bf16_f32 v195, v74, v75
	v_add_u32_e32 v217, 0x30000, v209
	global_store_dwordx4 v217, v[192:195], s[80:81]
	v_lshlrev_b32_e32 v200, 16, v196
	v_and_b32_e32 v201, 0xffff0000, v196
	v_lshlrev_b32_e32 v202, 16, v197
	v_and_b32_e32 v203, 0xffff0000, v197
	v_lshlrev_b32_e32 v204, 16, v198
	v_and_b32_e32 v205, 0xffff0000, v198
	v_lshlrev_b32_e32 v206, 16, v199
	v_and_b32_e32 v207, 0xffff0000, v199
	v_pk_add_f32 v[68:69], v[68:69], v[200:201]
	v_pk_add_f32 v[70:71], v[70:71], v[202:203]
	v_pk_add_f32 v[64:65], v[64:65], v[204:205]
	v_pk_add_f32 v[66:67], v[66:67], v[206:207]
	v_fmac_f32_e32 v213, v68, v68
	v_fmac_f32_e32 v213, v69, v69
	v_fmac_f32_e32 v213, v70, v70
	v_fmac_f32_e32 v213, v71, v71
	v_fmac_f32_e32 v213, v64, v64
	v_fmac_f32_e32 v213, v65, v65
	v_fmac_f32_e32 v213, v66, v66
	v_fmac_f32_e32 v213, v67, v67
	v_cvt_pk_bf16_f32 v196, v68, v69
	v_cvt_pk_bf16_f32 v197, v70, v71
	v_cvt_pk_bf16_f32 v198, v64, v65
	v_cvt_pk_bf16_f32 v199, v66, v67
	global_store_dwordx4 v217, v[196:199], s[80:81] offset:256
	ds_bpermute_b32 v214, v215, v213
	s_waitcnt lgkmcnt(0)
	v_add_f32_e32 v213, v213, v214
	ds_bpermute_b32 v214, v216, v213
	s_waitcnt lgkmcnt(0)
	v_add_f32_e32 v213, v213, v214
	s_mov_b64 exec, 0xffff
	global_atomic_add_f32 v208, v213, s[4:5] offset:192
	s_mov_b64 exec, -1
	v_add_u32_e32 v211, 0x90000, v209
	global_load_dwordx4 v[192:195], v211, s[80:81]
	global_load_dwordx4 v[196:199], v211, s[80:81] offset:256
	s_waitcnt vmcnt(5)
	v_lshlrev_b32_e32 v184, 16, v176
	v_and_b32_e32 v185, 0xffff0000, v176
	v_lshlrev_b32_e32 v186, 16, v177
	v_and_b32_e32 v187, 0xffff0000, v177
	v_lshlrev_b32_e32 v188, 16, v178
	v_and_b32_e32 v189, 0xffff0000, v178
	v_lshlrev_b32_e32 v190, 16, v179
	v_and_b32_e32 v191, 0xffff0000, v179
	v_pk_add_f32 v[60:61], v[60:61], v[184:185]
	v_pk_add_f32 v[62:63], v[62:63], v[186:187]
	v_pk_add_f32 v[56:57], v[56:57], v[188:189]
	v_pk_add_f32 v[58:59], v[58:59], v[190:191]
	v_mul_f32_e32 v213, v60, v60
	v_fmac_f32_e32 v213, v61, v61
	v_fmac_f32_e32 v213, v62, v62
	v_fmac_f32_e32 v213, v63, v63
	v_fmac_f32_e32 v213, v56, v56
	v_fmac_f32_e32 v213, v57, v57
	v_fmac_f32_e32 v213, v58, v58
	v_fmac_f32_e32 v213, v59, v59
	v_cvt_pk_bf16_f32 v176, v60, v61
	v_cvt_pk_bf16_f32 v177, v62, v63
	v_cvt_pk_bf16_f32 v178, v56, v57
	v_cvt_pk_bf16_f32 v179, v58, v59
	v_add_u32_e32 v217, 0x80000, v209
	global_store_dwordx4 v217, v[176:179], s[80:81]
	v_lshlrev_b32_e32 v184, 16, v180
	v_and_b32_e32 v185, 0xffff0000, v180
	v_lshlrev_b32_e32 v186, 16, v181
	v_and_b32_e32 v187, 0xffff0000, v181
	v_lshlrev_b32_e32 v188, 16, v182
	v_and_b32_e32 v189, 0xffff0000, v182
	v_lshlrev_b32_e32 v190, 16, v183
	v_and_b32_e32 v191, 0xffff0000, v183
	v_pk_add_f32 v[52:53], v[52:53], v[184:185]
	v_pk_add_f32 v[54:55], v[54:55], v[186:187]
	v_pk_add_f32 v[48:49], v[48:49], v[188:189]
	v_pk_add_f32 v[50:51], v[50:51], v[190:191]
	v_fmac_f32_e32 v213, v52, v52
	v_fmac_f32_e32 v213, v53, v53
	v_fmac_f32_e32 v213, v54, v54
	v_fmac_f32_e32 v213, v55, v55
	v_fmac_f32_e32 v213, v48, v48
	v_fmac_f32_e32 v213, v49, v49
	v_fmac_f32_e32 v213, v50, v50
	v_fmac_f32_e32 v213, v51, v51
	v_cvt_pk_bf16_f32 v180, v52, v53
	v_cvt_pk_bf16_f32 v181, v54, v55
	v_cvt_pk_bf16_f32 v182, v48, v49
	v_cvt_pk_bf16_f32 v183, v50, v51
	global_store_dwordx4 v217, v[180:183], s[80:81] offset:256
	ds_bpermute_b32 v214, v215, v213
	s_waitcnt lgkmcnt(0)
	v_add_f32_e32 v213, v213, v214
	ds_bpermute_b32 v214, v216, v213
	s_waitcnt lgkmcnt(0)
	v_add_f32_e32 v213, v213, v214
	s_mov_b64 exec, 0xffff
	global_atomic_add_f32 v208, v213, s[4:5] offset:512
	s_mov_b64 exec, -1
	v_add_u32_e32 v211, 0xa0000, v209
	global_load_dwordx4 v[176:179], v211, s[80:81]
	global_load_dwordx4 v[180:183], v211, s[80:81] offset:256
	s_waitcnt vmcnt(5)
	v_lshlrev_b32_e32 v200, 16, v192
	v_and_b32_e32 v201, 0xffff0000, v192
	v_lshlrev_b32_e32 v202, 16, v193
	v_and_b32_e32 v203, 0xffff0000, v193
	v_lshlrev_b32_e32 v204, 16, v194
	v_and_b32_e32 v205, 0xffff0000, v194
	v_lshlrev_b32_e32 v206, 16, v195
	v_and_b32_e32 v207, 0xffff0000, v195
	v_pk_add_f32 v[44:45], v[44:45], v[200:201]
	v_pk_add_f32 v[46:47], v[46:47], v[202:203]
	v_pk_add_f32 v[40:41], v[40:41], v[204:205]
	v_pk_add_f32 v[42:43], v[42:43], v[206:207]
	v_mul_f32_e32 v213, v44, v44
	v_fmac_f32_e32 v213, v45, v45
	v_fmac_f32_e32 v213, v46, v46
	v_fmac_f32_e32 v213, v47, v47
	v_fmac_f32_e32 v213, v40, v40
	v_fmac_f32_e32 v213, v41, v41
	v_fmac_f32_e32 v213, v42, v42
	v_fmac_f32_e32 v213, v43, v43
	v_cvt_pk_bf16_f32 v192, v44, v45
	v_cvt_pk_bf16_f32 v193, v46, v47
	v_cvt_pk_bf16_f32 v194, v40, v41
	v_cvt_pk_bf16_f32 v195, v42, v43
	v_add_u32_e32 v217, 0x90000, v209
	global_store_dwordx4 v217, v[192:195], s[80:81]
	v_lshlrev_b32_e32 v200, 16, v196
	v_and_b32_e32 v201, 0xffff0000, v196
	v_lshlrev_b32_e32 v202, 16, v197
	v_and_b32_e32 v203, 0xffff0000, v197
	v_lshlrev_b32_e32 v204, 16, v198
	v_and_b32_e32 v205, 0xffff0000, v198
	v_lshlrev_b32_e32 v206, 16, v199
	v_and_b32_e32 v207, 0xffff0000, v199
	v_pk_add_f32 v[36:37], v[36:37], v[200:201]
	v_pk_add_f32 v[38:39], v[38:39], v[202:203]
	v_pk_add_f32 v[32:33], v[32:33], v[204:205]
	v_pk_add_f32 v[34:35], v[34:35], v[206:207]
	v_fmac_f32_e32 v213, v36, v36
	v_fmac_f32_e32 v213, v37, v37
	v_fmac_f32_e32 v213, v38, v38
	v_fmac_f32_e32 v213, v39, v39
	v_fmac_f32_e32 v213, v32, v32
	v_fmac_f32_e32 v213, v33, v33
	v_fmac_f32_e32 v213, v34, v34
	v_fmac_f32_e32 v213, v35, v35
	v_cvt_pk_bf16_f32 v196, v36, v37
	v_cvt_pk_bf16_f32 v197, v38, v39
	v_cvt_pk_bf16_f32 v198, v32, v33
	v_cvt_pk_bf16_f32 v199, v34, v35
	global_store_dwordx4 v217, v[196:199], s[80:81] offset:256
	ds_bpermute_b32 v214, v215, v213
	s_waitcnt lgkmcnt(0)
	v_add_f32_e32 v213, v213, v214
	ds_bpermute_b32 v214, v216, v213
	s_waitcnt lgkmcnt(0)
	v_add_f32_e32 v213, v213, v214
	s_mov_b64 exec, 0xffff
	global_atomic_add_f32 v208, v213, s[4:5] offset:576
	s_mov_b64 exec, -1
	v_add_u32_e32 v211, 0xb0000, v209
	global_load_dwordx4 v[192:195], v211, s[80:81]
	global_load_dwordx4 v[196:199], v211, s[80:81] offset:256
	s_waitcnt vmcnt(5)
	v_lshlrev_b32_e32 v184, 16, v176
	v_and_b32_e32 v185, 0xffff0000, v176
	v_lshlrev_b32_e32 v186, 16, v177
	v_and_b32_e32 v187, 0xffff0000, v177
	v_lshlrev_b32_e32 v188, 16, v178
	v_and_b32_e32 v189, 0xffff0000, v178
	v_lshlrev_b32_e32 v190, 16, v179
	v_and_b32_e32 v191, 0xffff0000, v179
	v_pk_add_f32 v[28:29], v[28:29], v[184:185]
	v_pk_add_f32 v[30:31], v[30:31], v[186:187]
	v_pk_add_f32 v[24:25], v[24:25], v[188:189]
	v_pk_add_f32 v[26:27], v[26:27], v[190:191]
	v_mul_f32_e32 v213, v28, v28
	v_fmac_f32_e32 v213, v29, v29
	v_fmac_f32_e32 v213, v30, v30
	v_fmac_f32_e32 v213, v31, v31
	v_fmac_f32_e32 v213, v24, v24
	v_fmac_f32_e32 v213, v25, v25
	v_fmac_f32_e32 v213, v26, v26
	v_fmac_f32_e32 v213, v27, v27
	v_cvt_pk_bf16_f32 v176, v28, v29
	v_cvt_pk_bf16_f32 v177, v30, v31
	v_cvt_pk_bf16_f32 v178, v24, v25
	v_cvt_pk_bf16_f32 v179, v26, v27
	v_add_u32_e32 v217, 0xa0000, v209
	global_store_dwordx4 v217, v[176:179], s[80:81]
	v_lshlrev_b32_e32 v184, 16, v180
	v_and_b32_e32 v185, 0xffff0000, v180
	v_lshlrev_b32_e32 v186, 16, v181
	v_and_b32_e32 v187, 0xffff0000, v181
	v_lshlrev_b32_e32 v188, 16, v182
	v_and_b32_e32 v189, 0xffff0000, v182
	v_lshlrev_b32_e32 v190, 16, v183
	v_and_b32_e32 v191, 0xffff0000, v183
	v_pk_add_f32 v[20:21], v[20:21], v[184:185]
	v_pk_add_f32 v[22:23], v[22:23], v[186:187]
	v_pk_add_f32 v[16:17], v[16:17], v[188:189]
	v_pk_add_f32 v[18:19], v[18:19], v[190:191]
	v_fmac_f32_e32 v213, v20, v20
	v_fmac_f32_e32 v213, v21, v21
	v_fmac_f32_e32 v213, v22, v22
	v_fmac_f32_e32 v213, v23, v23
	v_fmac_f32_e32 v213, v16, v16
	v_fmac_f32_e32 v213, v17, v17
	v_fmac_f32_e32 v213, v18, v18
	v_fmac_f32_e32 v213, v19, v19
	v_cvt_pk_bf16_f32 v180, v20, v21
	v_cvt_pk_bf16_f32 v181, v22, v23
	v_cvt_pk_bf16_f32 v182, v16, v17
	v_cvt_pk_bf16_f32 v183, v18, v19
	global_store_dwordx4 v217, v[180:183], s[80:81] offset:256
	ds_bpermute_b32 v214, v215, v213
	s_waitcnt lgkmcnt(0)
	v_add_f32_e32 v213, v213, v214
	ds_bpermute_b32 v214, v216, v213
	s_waitcnt lgkmcnt(0)
	v_add_f32_e32 v213, v213, v214
	s_mov_b64 exec, 0xffff
	global_atomic_add_f32 v208, v213, s[4:5] offset:640
	s_mov_b64 exec, -1
	s_waitcnt vmcnt(3)
	v_lshlrev_b32_e32 v200, 16, v192
	v_and_b32_e32 v201, 0xffff0000, v192
	v_lshlrev_b32_e32 v202, 16, v193
	v_and_b32_e32 v203, 0xffff0000, v193
	v_lshlrev_b32_e32 v204, 16, v194
	v_and_b32_e32 v205, 0xffff0000, v194
	v_lshlrev_b32_e32 v206, 16, v195
	v_and_b32_e32 v207, 0xffff0000, v195
	v_pk_add_f32 v[12:13], v[12:13], v[200:201]
	v_pk_add_f32 v[14:15], v[14:15], v[202:203]
	v_pk_add_f32 v[8:9], v[8:9], v[204:205]
	v_pk_add_f32 v[10:11], v[10:11], v[206:207]
	v_mul_f32_e32 v213, v12, v12
	v_fmac_f32_e32 v213, v13, v13
	v_fmac_f32_e32 v213, v14, v14
	v_fmac_f32_e32 v213, v15, v15
	v_fmac_f32_e32 v213, v8, v8
	v_fmac_f32_e32 v213, v9, v9
	v_fmac_f32_e32 v213, v10, v10
	v_fmac_f32_e32 v213, v11, v11
	v_cvt_pk_bf16_f32 v192, v12, v13
	v_cvt_pk_bf16_f32 v193, v14, v15
	v_cvt_pk_bf16_f32 v194, v8, v9
	v_cvt_pk_bf16_f32 v195, v10, v11
	v_add_u32_e32 v217, 0xb0000, v209
	global_store_dwordx4 v217, v[192:195], s[80:81]
	v_lshlrev_b32_e32 v200, 16, v196
	v_and_b32_e32 v201, 0xffff0000, v196
	v_lshlrev_b32_e32 v202, 16, v197
	v_and_b32_e32 v203, 0xffff0000, v197
	v_lshlrev_b32_e32 v204, 16, v198
	v_and_b32_e32 v205, 0xffff0000, v198
	v_lshlrev_b32_e32 v206, 16, v199
	v_and_b32_e32 v207, 0xffff0000, v199
	v_pk_add_f32 v[4:5], v[4:5], v[200:201]
	v_pk_add_f32 v[6:7], v[6:7], v[202:203]
	v_pk_add_f32 v[0:1], v[0:1], v[204:205]
	v_pk_add_f32 v[2:3], v[2:3], v[206:207]
	v_fmac_f32_e32 v213, v4, v4
	v_fmac_f32_e32 v213, v5, v5
	v_fmac_f32_e32 v213, v6, v6
	v_fmac_f32_e32 v213, v7, v7
	v_fmac_f32_e32 v213, v0, v0
	v_fmac_f32_e32 v213, v1, v1
	v_fmac_f32_e32 v213, v2, v2
	v_fmac_f32_e32 v213, v3, v3
	v_cvt_pk_bf16_f32 v196, v4, v5
	v_cvt_pk_bf16_f32 v197, v6, v7
	v_cvt_pk_bf16_f32 v198, v0, v1
	v_cvt_pk_bf16_f32 v199, v2, v3
	global_store_dwordx4 v217, v[196:199], s[80:81] offset:256
	ds_bpermute_b32 v214, v215, v213
	s_waitcnt lgkmcnt(0)
	v_add_f32_e32 v213, v213, v214
	ds_bpermute_b32 v214, v216, v213
	s_waitcnt lgkmcnt(0)
	v_add_f32_e32 v213, v213, v214
	s_mov_b64 exec, 0xffff
	global_atomic_add_f32 v208, v213, s[4:5] offset:704
	s_mov_b64 exec, -1
	s_branch .LBB0_752

.LBB0_840:
	ds_read_b128 v[76:79], v171
	v_xor_b32_e32 v91, 64, v171
	ds_read_b128 v[80:83], v91
	ds_read_b128 v[84:87], v171 offset:2048
	ds_read_b128 v[88:91], v91 offset:2048
	s_add_u32 s10, s8, 0x100
	s_addc_u32 s11, s9, 0
	s_cmp_eq_u32 s67, 28
	s_cselect_b32 s43, s33, s11
	s_cselect_b32 s42, s37, s10
	s_cselect_b32 s13, s35, s66
	s_cselect_b32 s12, s64, s65
	v_lshl_add_u64 v[108:109], s[8:9], 0, v[180:181]
	s_add_i32 m0, s48, 0xc000
	ds_read_b128 v[92:95], v173
	v_xor_b32_e32 v203, 64, v173
	ds_read_b128 v[96:99], v203
	ds_read_b128 v[100:103], v173 offset:2048
	ds_read_b128 v[104:107], v203 offset:2048
	ds_read_b128 v[188:191], v173 offset:4096
	ds_read_b128 v[192:195], v203 offset:4096
	ds_read_b128 v[196:199], v173 offset:6144
	ds_read_b128 v[200:203], v203 offset:6144
	global_load_lds_dwordx4 v[108:109], off
	v_lshl_add_u64 v[108:109], s[8:9], 0, v[182:183]
	s_add_i32 m0, s48, 0xe000
	s_nop 0
	global_load_lds_dwordx4 v[108:109], off
	s_waitcnt lgkmcnt(8)
	s_barrier
	s_waitcnt lgkmcnt(0)
	s_setprio 1
	s_waitcnt lgkmcnt(0)
	v_mfma_f32_16x16x32_bf16 v[158:161], v[76:79], v[92:95], v[158:161]
	v_mfma_f32_16x16x32_bf16 v[158:161], v[80:83], v[96:99], v[158:161]
	v_mfma_f32_16x16x32_bf16 v[60:63], v[84:87], v[92:95], v[60:63]
	v_mfma_f32_16x16x32_bf16 v[60:63], v[88:91], v[96:99], v[60:63]
	v_mfma_f32_16x16x32_bf16 v[150:153], v[76:79], v[100:103], v[150:153]
	v_mfma_f32_16x16x32_bf16 v[150:153], v[80:83], v[104:107], v[150:153]
	v_mfma_f32_16x16x32_bf16 v[52:55], v[84:87], v[100:103], v[52:55]
	v_mfma_f32_16x16x32_bf16 v[52:55], v[88:91], v[104:107], v[52:55]
	v_mfma_f32_16x16x32_bf16 v[146:149], v[76:79], v[188:191], v[146:149]
	v_mfma_f32_16x16x32_bf16 v[146:149], v[80:83], v[192:195], v[146:149]
	v_mfma_f32_16x16x32_bf16 v[48:51], v[84:87], v[188:191], v[48:51]
	v_mfma_f32_16x16x32_bf16 v[48:51], v[88:91], v[192:195], v[48:51]
	v_mfma_f32_16x16x32_bf16 v[138:141], v[76:79], v[196:199], v[138:141]
	v_mfma_f32_16x16x32_bf16 v[138:141], v[80:83], v[200:203], v[138:141]
	v_mfma_f32_16x16x32_bf16 v[40:43], v[84:87], v[196:199], v[40:43]
	v_mfma_f32_16x16x32_bf16 v[40:43], v[88:91], v[200:203], v[40:43]
	s_setprio 0
	s_barrier
	s_add_i32 s8, s60, s46
	v_lshl_add_u64 v[220:221], s[12:13], 0, v[164:165]
	s_mov_b32 m0, s8
	ds_read_b128 v[204:207], v175
	v_xor_b32_e32 v219, 64, v175
	ds_read_b128 v[208:211], v219
	ds_read_b128 v[212:215], v175 offset:2048
	ds_read_b128 v[216:219], v219 offset:2048
	global_load_lds_dwordx4 v[220:221], off
	v_lshl_add_u64 v[238:239], s[12:13], 0, v[166:167]
	s_add_i32 m0, s8, 0x2000
	s_nop 0
	global_load_lds_dwordx4 v[238:239], off
	s_barrier
	s_waitcnt lgkmcnt(0)
	s_setprio 1
	s_waitcnt lgkmcnt(0)
	v_mfma_f32_16x16x32_bf16 v[154:157], v[204:207], v[92:95], v[154:157]
	v_mfma_f32_16x16x32_bf16 v[56:59], v[212:215], v[92:95], v[56:59]
	v_mfma_f32_16x16x32_bf16 v[44:47], v[212:215], v[100:103], v[44:47]
	v_mfma_f32_16x16x32_bf16 v[36:39], v[212:215], v[188:191], v[36:39]
	v_mfma_f32_16x16x32_bf16 v[32:35], v[212:215], v[196:199], v[32:35]
	v_mfma_f32_16x16x32_bf16 v[154:157], v[208:211], v[96:99], v[154:157]
	v_mfma_f32_16x16x32_bf16 v[56:59], v[216:219], v[96:99], v[56:59]
	v_mfma_f32_16x16x32_bf16 v[92:95], v[204:207], v[100:103], v[142:145]
	v_mfma_f32_16x16x32_bf16 v[44:47], v[216:219], v[104:107], v[44:47]
	v_mfma_f32_16x16x32_bf16 v[96:99], v[204:207], v[188:191], v[134:137]
	v_mfma_f32_16x16x32_bf16 v[36:39], v[216:219], v[192:195], v[36:39]
	v_mfma_f32_16x16x32_bf16 v[100:103], v[204:207], v[196:199], v[130:133]
	v_mfma_f32_16x16x32_bf16 v[32:35], v[216:219], v[200:203], v[32:35]
	v_mfma_f32_16x16x32_bf16 v[92:95], v[208:211], v[104:107], v[92:95]
	v_mfma_f32_16x16x32_bf16 v[96:99], v[208:211], v[192:195], v[96:99]
	v_mfma_f32_16x16x32_bf16 v[100:103], v[208:211], v[200:203], v[100:103]
	s_setprio 0
	s_mov_b32 m0, s48
	v_lshl_add_u64 v[240:241], s[42:43], 0, v[178:179]
	s_barrier
	ds_read_b128 v[104:107], v173 offset:16384
	v_xor_b32_e32 v203, 64, v173
	ds_read_b128 v[130:133], v203 offset:16384
	ds_read_b128 v[134:137], v173 offset:18432
	ds_read_b128 v[142:145], v203 offset:18432
	ds_read_b128 v[188:191], v173 offset:20480
	ds_read_b128 v[192:195], v203 offset:20480
	ds_read_b128 v[196:199], v173 offset:22528
	ds_read_b128 v[200:203], v203 offset:22528
	global_load_lds_dwordx4 v[240:241], off
	v_lshl_add_u64 v[242:243], s[42:43], 0, v[176:177]
	s_mov_b32 m0, s49
	s_nop 0
	global_load_lds_dwordx4 v[242:243], off
	s_barrier
	s_waitcnt lgkmcnt(0)
	s_setprio 1
	s_waitcnt lgkmcnt(0)
	v_mfma_f32_16x16x32_bf16 v[126:129], v[76:79], v[104:107], v[126:129]
	v_mfma_f32_16x16x32_bf16 v[126:129], v[80:83], v[130:133], v[126:129]
	v_mfma_f32_16x16x32_bf16 v[28:31], v[84:87], v[104:107], v[28:31]
	v_mfma_f32_16x16x32_bf16 v[28:31], v[88:91], v[130:133], v[28:31]
	v_mfma_f32_16x16x32_bf16 v[122:125], v[76:79], v[134:137], v[122:125]
	v_mfma_f32_16x16x32_bf16 v[122:125], v[80:83], v[142:145], v[122:125]
	v_mfma_f32_16x16x32_bf16 v[24:27], v[84:87], v[134:137], v[24:27]
	v_mfma_f32_16x16x32_bf16 v[24:27], v[88:91], v[142:145], v[24:27]
	v_mfma_f32_16x16x32_bf16 v[114:117], v[76:79], v[188:191], v[114:117]
	v_mfma_f32_16x16x32_bf16 v[114:117], v[80:83], v[192:195], v[114:117]
	v_mfma_f32_16x16x32_bf16 v[20:23], v[84:87], v[188:191], v[20:23]
	v_mfma_f32_16x16x32_bf16 v[20:23], v[88:91], v[192:195], v[20:23]
	v_mfma_f32_16x16x32_bf16 v[72:75], v[76:79], v[196:199], v[72:75]
	v_mfma_f32_16x16x32_bf16 v[72:75], v[80:83], v[200:203], v[72:75]
	v_mfma_f32_16x16x32_bf16 v[4:7], v[84:87], v[196:199], v[4:7]
	v_mfma_f32_16x16x32_bf16 v[4:7], v[88:91], v[200:203], v[4:7]
	s_setprio 0
	s_barrier
	s_add_u32 s8, s12, 0x1600000
	s_addc_u32 s9, s13, 0
	s_add_i32 s68, s61, s46
	v_lshl_add_u64 v[76:77], s[8:9], 0, v[164:165]
	s_mov_b32 m0, s68
	s_nop 0
	global_load_lds_dwordx4 v[76:77], off
	v_lshl_add_u64 v[76:77], s[8:9], 0, v[166:167]
	s_add_i32 m0, s68, 0x2000
	s_nop 0
	global_load_lds_dwordx4 v[76:77], off
	s_waitcnt vmcnt(6)
	s_barrier
	s_setprio 1
	v_mfma_f32_16x16x32_bf16 v[16:19], v[212:215], v[104:107], v[16:19]
	v_mfma_f32_16x16x32_bf16 v[12:15], v[212:215], v[134:137], v[12:15]
	v_mfma_f32_16x16x32_bf16 v[68:71], v[204:207], v[188:191], v[68:71]
	v_mfma_f32_16x16x32_bf16 v[8:11], v[212:215], v[188:191], v[8:11]
	v_mfma_f32_16x16x32_bf16 v[64:67], v[204:207], v[196:199], v[64:67]
	v_mfma_f32_16x16x32_bf16 v[0:3], v[212:215], v[196:199], v[0:3]
	v_mfma_f32_16x16x32_bf16 v[76:79], v[204:207], v[104:107], v[118:121]
	v_mfma_f32_16x16x32_bf16 v[16:19], v[216:219], v[130:133], v[16:19]
	v_mfma_f32_16x16x32_bf16 v[80:83], v[204:207], v[134:137], v[110:113]
	v_mfma_f32_16x16x32_bf16 v[12:15], v[216:219], v[142:145], v[12:15]
	v_mfma_f32_16x16x32_bf16 v[68:71], v[208:211], v[192:195], v[68:71]
	v_mfma_f32_16x16x32_bf16 v[8:11], v[216:219], v[192:195], v[8:11]
	v_mfma_f32_16x16x32_bf16 v[64:67], v[208:211], v[200:203], v[64:67]
	v_mfma_f32_16x16x32_bf16 v[0:3], v[216:219], v[200:203], v[0:3]
	v_mfma_f32_16x16x32_bf16 v[76:79], v[208:211], v[130:133], v[76:79]
	v_mfma_f32_16x16x32_bf16 v[80:83], v[208:211], v[142:145], v[80:83]
	s_setprio 0
	s_add_i32 s68, 0, 0x18000
	v_add_u32_e32 v108, s68, v169
	s_barrier
	ds_read_b128 v[84:87], v108
	v_xor_b32_e32 v111, 64, v108
	ds_read_b128 v[88:91], v111
	ds_read_b128 v[104:107], v108 offset:2048
	ds_read_b128 v[108:111], v111 offset:2048
	s_add_u32 s8, s42, 0x40000
	s_addc_u32 s9, s43, 0
	s_mov_b32 m0, s50
	v_lshl_add_u64 v[112:113], s[8:9], 0, v[178:179]
	ds_read_b128 v[118:121], v173 offset:32768
	v_xor_b32_e32 v207, 64, v173
	ds_read_b128 v[130:133], v207 offset:32768
	ds_read_b128 v[134:137], v173 offset:34816
	ds_read_b128 v[188:191], v207 offset:34816
	ds_read_b128 v[192:195], v173 offset:36864
	ds_read_b128 v[196:199], v207 offset:36864
	ds_read_b128 v[200:203], v173 offset:38912
	ds_read_b128 v[204:207], v207 offset:38912
	global_load_lds_dwordx4 v[112:113], off
	v_lshl_add_u64 v[112:113], s[8:9], 0, v[176:177]
	s_mov_b32 m0, s51
	s_nop 0
	global_load_lds_dwordx4 v[112:113], off
	s_waitcnt lgkmcnt(8)
	s_barrier
	s_waitcnt lgkmcnt(0)
	s_setprio 1
	s_waitcnt lgkmcnt(0)
	v_mfma_f32_16x16x32_bf16 v[142:145], v[84:87], v[118:121], v[158:161]
	v_mfma_f32_16x16x32_bf16 v[158:161], v[88:91], v[130:133], v[142:145]
	v_mfma_f32_16x16x32_bf16 v[142:145], v[84:87], v[134:137], v[150:153]
	v_mfma_f32_16x16x32_bf16 v[60:63], v[104:107], v[118:121], v[60:63]
	v_mfma_f32_16x16x32_bf16 v[150:153], v[88:91], v[188:191], v[142:145]
	v_mfma_f32_16x16x32_bf16 v[52:55], v[104:107], v[134:137], v[52:55]
	v_mfma_f32_16x16x32_bf16 v[142:145], v[84:87], v[192:195], v[146:149]
	v_mfma_f32_16x16x32_bf16 v[48:51], v[104:107], v[192:195], v[48:51]
	v_mfma_f32_16x16x32_bf16 v[138:141], v[84:87], v[200:203], v[138:141]
	v_mfma_f32_16x16x32_bf16 v[40:43], v[104:107], v[200:203], v[40:43]
	v_mfma_f32_16x16x32_bf16 v[60:63], v[108:111], v[130:133], v[60:63]
	v_mfma_f32_16x16x32_bf16 v[52:55], v[108:111], v[188:191], v[52:55]
	v_mfma_f32_16x16x32_bf16 v[146:149], v[88:91], v[196:199], v[142:145]
	v_mfma_f32_16x16x32_bf16 v[48:51], v[108:111], v[196:199], v[48:51]
	v_mfma_f32_16x16x32_bf16 v[138:141], v[88:91], v[204:207], v[138:141]
	v_mfma_f32_16x16x32_bf16 v[40:43], v[108:111], v[204:207], v[40:43]
	s_setprio 0
	s_barrier
	s_add_i32 s42, 0, 0x1c000
	v_add_u32_e32 v112, s42, v169
	s_add_i32 s8, s68, s46
	ds_read_b128 v[208:211], v112
	v_xor_b32_e32 v237, 64, v112
	ds_read_b128 v[212:215], v237
	ds_read_b128 v[216:219], v112 offset:2048
	ds_read_b128 v[234:237], v237 offset:2048
	v_lshl_add_u64 v[112:113], v[220:221], 0, s[18:19]
	s_mov_b32 m0, s8
	s_nop 0
	global_load_lds_dwordx4 v[112:113], off
	v_lshl_add_u64 v[112:113], v[238:239], 0, s[18:19]
	s_add_i32 m0, s8, 0x2000
	s_nop 0
	global_load_lds_dwordx4 v[112:113], off
	s_barrier
	s_waitcnt lgkmcnt(0)
	s_setprio 1
	s_waitcnt lgkmcnt(0)
	v_mfma_f32_16x16x32_bf16 v[142:145], v[208:211], v[118:121], v[154:157]
	v_mfma_f32_16x16x32_bf16 v[92:95], v[208:211], v[134:137], v[92:95]
	v_mfma_f32_16x16x32_bf16 v[154:157], v[212:215], v[130:133], v[142:145]
	v_mfma_f32_16x16x32_bf16 v[142:145], v[212:215], v[188:191], v[92:95]
	v_mfma_f32_16x16x32_bf16 v[92:95], v[208:211], v[192:195], v[96:99]
	v_mfma_f32_16x16x32_bf16 v[56:59], v[216:219], v[118:121], v[56:59]
	v_mfma_f32_16x16x32_bf16 v[44:47], v[216:219], v[134:137], v[44:47]
	v_mfma_f32_16x16x32_bf16 v[134:137], v[212:215], v[196:199], v[92:95]
	v_mfma_f32_16x16x32_bf16 v[36:39], v[216:219], v[192:195], v[36:39]
	v_mfma_f32_16x16x32_bf16 v[92:95], v[208:211], v[200:203], v[100:103]
	v_mfma_f32_16x16x32_bf16 v[32:35], v[216:219], v[200:203], v[32:35]
	v_mfma_f32_16x16x32_bf16 v[56:59], v[234:237], v[130:133], v[56:59]
	v_mfma_f32_16x16x32_bf16 v[44:47], v[234:237], v[188:191], v[44:47]
	v_mfma_f32_16x16x32_bf16 v[36:39], v[234:237], v[196:199], v[36:39]
	v_mfma_f32_16x16x32_bf16 v[130:133], v[212:215], v[204:207], v[92:95]
	v_mfma_f32_16x16x32_bf16 v[32:35], v[234:237], v[204:207], v[32:35]
	s_setprio 0
	s_mov_b32 m0, s54
	v_lshl_add_u64 v[112:113], v[240:241], 0, s[18:19]
	s_barrier
	ds_read_b128 v[92:95], v173 offset:49152
	v_xor_b32_e32 v207, 64, v173
	ds_read_b128 v[96:99], v207 offset:49152
	ds_read_b128 v[100:103], v173 offset:51200
	ds_read_b128 v[188:191], v207 offset:51200
	ds_read_b128 v[192:195], v173 offset:53248
	ds_read_b128 v[196:199], v207 offset:53248
	ds_read_b128 v[200:203], v173 offset:55296
	ds_read_b128 v[204:207], v207 offset:55296
	global_load_lds_dwordx4 v[112:113], off
	v_lshl_add_u64 v[112:113], v[242:243], 0, s[18:19]
	s_mov_b32 m0, s55
	s_nop 0
	global_load_lds_dwordx4 v[112:113], off
	s_barrier
	s_waitcnt lgkmcnt(0)
	s_setprio 1
	s_waitcnt lgkmcnt(0)
	v_mfma_f32_16x16x32_bf16 v[118:121], v[84:87], v[92:95], v[126:129]
	v_mfma_f32_16x16x32_bf16 v[126:129], v[88:91], v[96:99], v[118:121]
	v_mfma_f32_16x16x32_bf16 v[28:31], v[104:107], v[92:95], v[28:31]
	v_mfma_f32_16x16x32_bf16 v[118:121], v[84:87], v[100:103], v[122:125]
	v_mfma_f32_16x16x32_bf16 v[24:27], v[104:107], v[100:103], v[24:27]
	v_mfma_f32_16x16x32_bf16 v[112:115], v[84:87], v[192:195], v[114:117]
	v_mfma_f32_16x16x32_bf16 v[20:23], v[104:107], v[192:195], v[20:23]
	v_mfma_f32_16x16x32_bf16 v[72:75], v[84:87], v[200:203], v[72:75]
	v_mfma_f32_16x16x32_bf16 v[4:7], v[104:107], v[200:203], v[4:7]
	v_mfma_f32_16x16x32_bf16 v[28:31], v[108:111], v[96:99], v[28:31]
	v_mfma_f32_16x16x32_bf16 v[122:125], v[88:91], v[188:191], v[118:121]
	v_mfma_f32_16x16x32_bf16 v[24:27], v[108:111], v[188:191], v[24:27]
	v_mfma_f32_16x16x32_bf16 v[114:117], v[88:91], v[196:199], v[112:115]
	v_mfma_f32_16x16x32_bf16 v[20:23], v[108:111], v[196:199], v[20:23]
	v_mfma_f32_16x16x32_bf16 v[72:75], v[88:91], v[204:207], v[72:75]
	v_mfma_f32_16x16x32_bf16 v[4:7], v[108:111], v[204:207], v[4:7]
	s_setprio 0
	s_barrier
	s_add_u32 s8, s12, 0x1600080
	s_addc_u32 s9, s13, 0
	s_add_i32 s12, s42, s46
	v_lshl_add_u64 v[84:85], s[8:9], 0, v[164:165]
	s_mov_b32 m0, s12
	s_nop 0
	global_load_lds_dwordx4 v[84:85], off
	v_lshl_add_u64 v[84:85], s[8:9], 0, v[166:167]
	s_add_i32 m0, s12, 0x2000
	s_nop 0
	global_load_lds_dwordx4 v[84:85], off
	s_waitcnt vmcnt(6)
	s_barrier
	s_setprio 1
	v_mfma_f32_16x16x32_bf16 v[76:79], v[208:211], v[92:95], v[76:79]
	v_mfma_f32_16x16x32_bf16 v[118:121], v[212:215], v[96:99], v[76:79]
	v_mfma_f32_16x16x32_bf16 v[16:19], v[216:219], v[92:95], v[16:19]
	v_mfma_f32_16x16x32_bf16 v[76:79], v[208:211], v[100:103], v[80:83]
	v_mfma_f32_16x16x32_bf16 v[12:15], v[216:219], v[100:103], v[12:15]
	v_mfma_f32_16x16x32_bf16 v[68:71], v[208:211], v[192:195], v[68:71]
	v_mfma_f32_16x16x32_bf16 v[8:11], v[216:219], v[192:195], v[8:11]
	v_mfma_f32_16x16x32_bf16 v[64:67], v[208:211], v[200:203], v[64:67]
	v_mfma_f32_16x16x32_bf16 v[0:3], v[216:219], v[200:203], v[0:3]
	v_mfma_f32_16x16x32_bf16 v[16:19], v[234:237], v[96:99], v[16:19]
	v_mfma_f32_16x16x32_bf16 v[110:113], v[212:215], v[188:191], v[76:79]
	v_mfma_f32_16x16x32_bf16 v[12:15], v[234:237], v[188:191], v[12:15]
	v_mfma_f32_16x16x32_bf16 v[68:71], v[212:215], v[196:199], v[68:71]
	v_mfma_f32_16x16x32_bf16 v[8:11], v[234:237], v[196:199], v[8:11]
	v_mfma_f32_16x16x32_bf16 v[64:67], v[212:215], v[204:207], v[64:67]
	v_mfma_f32_16x16x32_bf16 v[0:3], v[234:237], v[204:207], v[0:3]
	s_setprio 0
	s_add_i32 s67, s67, 2
	s_add_u32 s65, s65, 0x100
	s_addc_u32 s66, s66, 0
	s_cmp_gt_u32 s67, 29
	s_mov_b64 s[8:9], s[10:11]
	s_barrier
	s_cbranch_scc0 .LBB0_840
	s_lshl_b32 s8, s0, 8
	s_lshl_b32 s1, s1, 7
	v_mov_b32_e32 v80, v225
	v_mov_b32_e32 v193, v163
	s_add_i32 s8, s8, s58
	s_or_b32 s1, s1, s53
	s_lshl_b32 s0, s0, 3
	v_add_u32_e32 v190, s8, v193
	v_lshl_add_u32 v188, v80, 3, s1
	v_ashrrev_i32_e32 v191, 31, v190
	v_ashrrev_i32_e32 v189, 31, v188
	v_lshl_add_u64 v[78:79], v[190:191], 2, s[4:5]
	v_lshlrev_b64 v[90:91], 2, v[188:189]
	global_load_dword v196, v[78:79], off
	global_load_dword v192, v[78:79], off offset:64
	global_load_dword v194, v[78:79], off offset:128
	global_load_dword v200, v[78:79], off offset:192
	global_load_dword v199, v[78:79], off offset:256
	global_load_dword v77, v[78:79], off offset:320
	global_load_dword v76, v[78:79], off offset:384
	global_load_dword v191, v[78:79], off offset:448
	v_lshl_add_u64 v[78:79], s[14:15], 0, v[90:91]
	v_lshl_add_u64 v[80:81], s[20:21], 0, v[90:91]
	global_load_dwordx4 v[102:105], v[78:79], off
	global_load_dwordx4 v[94:97], v[80:81], off
	v_lshl_add_u64 v[78:79], s[22:23], 0, v[90:91]
	global_load_dwordx4 v[98:101], v[78:79], off
	v_lshl_add_u64 v[78:79], s[16:17], 0, v[90:91]
	global_load_dwordx4 v[106:109], v[78:79], off
	v_lshl_add_u64 v[78:79], s[24:25], 0, v[90:91]
	v_lshl_add_u64 v[80:81], s[26:27], 0, v[90:91]
	v_lshl_add_u64 v[82:83], s[28:29], 0, v[90:91]
	v_lshl_add_u64 v[90:91], s[30:31], 0, v[90:91]
	global_load_dwordx4 v[86:89], v[78:79], off
	s_nop 0
	global_load_dwordx4 v[78:81], v[80:81], off
	s_add_i32 s0, s0, s59
	global_load_dwordx4 v[82:85], v[82:83], off
	v_add_u32_e32 v195, s0, v193
	global_load_dwordx4 v[90:93], v[90:91], off
	v_cmp_gt_i32_e64 s[12:13], 2, v193
	s_waitcnt vmcnt(0)
	v_fmamk_f32 v196, v196, 0x3a000000, v230
	v_rsq_f32_e32 v198, v196
	v_mad_i64_i32 v[196:197], s[0:1], v195, s62, 0
	v_lshl_add_u64 v[196:197], s[70:71], 0, v[196:197]
	v_pk_mul_f32 v[160:161], v[160:161], v[198:199] op_sel_hi:[1,0]
	v_pk_mul_f32 v[158:159], v[158:159], v[198:199] op_sel_hi:[1,0]
	v_pk_mul_f32 v[156:157], v[156:157], v[198:199] op_sel_hi:[1,0]
	v_pk_mul_f32 v[154:155], v[154:155], v[198:199] op_sel_hi:[1,0]
	v_lshl_add_u64 v[196:197], v[188:189], 2, v[196:197]
	s_and_saveexec_b64 s[0:1], s[12:13]
	s_cbranch_execz .LBB0_843
	v_add_co_u32_e32 v202, vcc, 0x5000, v196
	global_store_dwordx4 v[196:197], v[158:161], off
	s_nop 0
	v_addc_co_u32_e32 v203, vcc, 0, v197, vcc
	global_store_dwordx4 v[202:203], v[154:157], off offset:2048

.LBB0_985:
	ds_read_b128 v[136:139], v141
	v_xor_b32_e32 v157, 64, v141
	ds_read_b128 v[146:149], v157
	ds_read_b128 v[150:153], v141 offset:2048
	ds_read_b128 v[154:157], v157 offset:2048
	s_add_u32 s14, s0, 0xffea0080
	s_addc_u32 s15, s1, -1
	s_cmpk_eq_i32 s41, 0x54
	s_cselect_b32 s17, s5, s15
	s_cselect_b32 s16, s4, s14
	s_cselect_b32 s15, s7, s40
	s_cselect_b32 s14, s6, s39
	v_lshl_add_u64 v[200:201], s[0:1], 0, v[128:129]
	s_add_i32 m0, s21, 0xc000
	ds_read_b128 v[158:161], v142
	v_xor_b32_e32 v199, 64, v142
	ds_read_b128 v[164:167], v199
	ds_read_b128 v[176:179], v142 offset:2048
	ds_read_b128 v[180:183], v199 offset:2048
	ds_read_b128 v[184:187], v142 offset:4096
	ds_read_b128 v[188:191], v199 offset:4096
	ds_read_b128 v[192:195], v142 offset:6144
	ds_read_b128 v[196:199], v199 offset:6144
	global_load_lds_dwordx4 v[200:201], off
	v_lshl_add_u64 v[200:201], s[0:1], 0, v[130:131]
	s_add_i32 m0, s21, 0xe000
	s_nop 0
	global_load_lds_dwordx4 v[200:201], off
	s_waitcnt lgkmcnt(8)
	s_barrier
	s_waitcnt lgkmcnt(0)
	s_setprio 1
	s_waitcnt lgkmcnt(0)
	v_mfma_f32_16x16x32_bf16 v[124:127], v[136:139], v[158:161], v[124:127]
	v_mfma_f32_16x16x32_bf16 v[124:127], v[146:149], v[164:167], v[124:127]
	v_mfma_f32_16x16x32_bf16 v[120:123], v[150:153], v[158:161], v[120:123]
	v_mfma_f32_16x16x32_bf16 v[120:123], v[154:157], v[164:167], v[120:123]
	v_mfma_f32_16x16x32_bf16 v[108:111], v[136:139], v[176:179], v[108:111]
	v_mfma_f32_16x16x32_bf16 v[108:111], v[146:149], v[180:183], v[108:111]
	v_mfma_f32_16x16x32_bf16 v[104:107], v[150:153], v[176:179], v[104:107]
	v_mfma_f32_16x16x32_bf16 v[104:107], v[154:157], v[180:183], v[104:107]
	v_mfma_f32_16x16x32_bf16 v[92:95], v[136:139], v[184:187], v[92:95]
	v_mfma_f32_16x16x32_bf16 v[92:95], v[146:149], v[188:191], v[92:95]
	v_mfma_f32_16x16x32_bf16 v[88:91], v[150:153], v[184:187], v[88:91]
	v_mfma_f32_16x16x32_bf16 v[88:91], v[154:157], v[188:191], v[88:91]
	v_mfma_f32_16x16x32_bf16 v[76:79], v[136:139], v[192:195], v[76:79]
	v_mfma_f32_16x16x32_bf16 v[76:79], v[146:149], v[196:199], v[76:79]
	v_mfma_f32_16x16x32_bf16 v[72:75], v[150:153], v[192:195], v[72:75]
	v_mfma_f32_16x16x32_bf16 v[72:75], v[154:157], v[196:199], v[72:75]
	s_setprio 0
	s_barrier
	s_add_i32 s42, s33, s20
	v_lshl_add_u64 v[216:217], s[14:15], 0, v[170:171]
	s_mov_b32 m0, s42
	ds_read_b128 v[200:203], v143
	v_xor_b32_e32 v215, 64, v143
	ds_read_b128 v[204:207], v215
	ds_read_b128 v[208:211], v143 offset:2048
	ds_read_b128 v[212:215], v215 offset:2048
	global_load_lds_dwordx4 v[216:217], off
	v_lshl_add_u64 v[218:219], s[14:15], 0, v[174:175]
	s_add_i32 m0, s42, 0x2000
	s_nop 0
	global_load_lds_dwordx4 v[218:219], off
	s_barrier
	s_waitcnt lgkmcnt(0)
	s_setprio 1
	s_waitcnt lgkmcnt(0)
	v_mfma_f32_16x16x32_bf16 v[116:119], v[200:203], v[158:161], v[116:119]
	v_mfma_f32_16x16x32_bf16 v[116:119], v[204:207], v[164:167], v[116:119]
	v_mfma_f32_16x16x32_bf16 v[112:115], v[208:211], v[158:161], v[112:115]
	v_mfma_f32_16x16x32_bf16 v[112:115], v[212:215], v[164:167], v[112:115]
	v_mfma_f32_16x16x32_bf16 v[100:103], v[200:203], v[176:179], v[100:103]
	v_mfma_f32_16x16x32_bf16 v[100:103], v[204:207], v[180:183], v[100:103]
	v_mfma_f32_16x16x32_bf16 v[96:99], v[208:211], v[176:179], v[96:99]
	v_mfma_f32_16x16x32_bf16 v[96:99], v[212:215], v[180:183], v[96:99]
	v_mfma_f32_16x16x32_bf16 v[84:87], v[200:203], v[184:187], v[84:87]
	v_mfma_f32_16x16x32_bf16 v[84:87], v[204:207], v[188:191], v[84:87]
	v_mfma_f32_16x16x32_bf16 v[80:83], v[208:211], v[184:187], v[80:83]
	v_mfma_f32_16x16x32_bf16 v[80:83], v[212:215], v[188:191], v[80:83]
	v_mfma_f32_16x16x32_bf16 v[68:71], v[200:203], v[192:195], v[68:71]
	v_mfma_f32_16x16x32_bf16 v[68:71], v[204:207], v[196:199], v[68:71]
	v_mfma_f32_16x16x32_bf16 v[64:67], v[208:211], v[192:195], v[64:67]
	v_mfma_f32_16x16x32_bf16 v[64:67], v[212:215], v[196:199], v[64:67]
	s_setprio 0
	s_mov_b32 m0, s21
	v_lshl_add_u64 v[220:221], s[16:17], 0, v[168:169]
	s_barrier
	ds_read_b128 v[158:161], v142 offset:16384
	v_xor_b32_e32 v199, 64, v142
	ds_read_b128 v[164:167], v199 offset:16384
	ds_read_b128 v[176:179], v142 offset:18432
	ds_read_b128 v[180:183], v199 offset:18432
	ds_read_b128 v[184:187], v142 offset:20480
	ds_read_b128 v[188:191], v199 offset:20480
	ds_read_b128 v[192:195], v142 offset:22528
	ds_read_b128 v[196:199], v199 offset:22528
	global_load_lds_dwordx4 v[220:221], off
	v_lshl_add_u64 v[222:223], s[16:17], 0, v[172:173]
	s_mov_b32 m0, s22
	s_nop 0
	global_load_lds_dwordx4 v[222:223], off
	s_barrier
	s_waitcnt lgkmcnt(0)
	s_setprio 1
	s_waitcnt lgkmcnt(0)
	v_mfma_f32_16x16x32_bf16 v[60:63], v[136:139], v[158:161], v[60:63]
	v_mfma_f32_16x16x32_bf16 v[60:63], v[146:149], v[164:167], v[60:63]
	v_mfma_f32_16x16x32_bf16 v[56:59], v[150:153], v[158:161], v[56:59]
	v_mfma_f32_16x16x32_bf16 v[56:59], v[154:157], v[164:167], v[56:59]
	v_mfma_f32_16x16x32_bf16 v[44:47], v[136:139], v[176:179], v[44:47]
	v_mfma_f32_16x16x32_bf16 v[44:47], v[146:149], v[180:183], v[44:47]
	v_mfma_f32_16x16x32_bf16 v[40:43], v[150:153], v[176:179], v[40:43]
	v_mfma_f32_16x16x32_bf16 v[40:43], v[154:157], v[180:183], v[40:43]
	v_mfma_f32_16x16x32_bf16 v[28:31], v[136:139], v[184:187], v[28:31]
	v_mfma_f32_16x16x32_bf16 v[28:31], v[146:149], v[188:191], v[28:31]
	v_mfma_f32_16x16x32_bf16 v[24:27], v[150:153], v[184:187], v[24:27]
	v_mfma_f32_16x16x32_bf16 v[24:27], v[154:157], v[188:191], v[24:27]
	v_mfma_f32_16x16x32_bf16 v[12:15], v[136:139], v[192:195], v[12:15]
	v_mfma_f32_16x16x32_bf16 v[12:15], v[146:149], v[196:199], v[12:15]
	v_mfma_f32_16x16x32_bf16 v[8:11], v[150:153], v[192:195], v[8:11]
	v_mfma_f32_16x16x32_bf16 v[8:11], v[154:157], v[196:199], v[8:11]
	s_setprio 0
	s_barrier
	s_add_u32 s42, s14, 0x160000
	s_addc_u32 s43, s15, 0
	s_add_i32 s44, s34, s20
	v_lshl_add_u64 v[136:137], s[42:43], 0, v[170:171]
	s_mov_b32 m0, s44
	s_nop 0
	global_load_lds_dwordx4 v[136:137], off
	v_lshl_add_u64 v[136:137], s[42:43], 0, v[174:175]
	s_add_i32 m0, s44, 0x2000
	s_nop 0
	global_load_lds_dwordx4 v[136:137], off
	s_waitcnt vmcnt(6)
	s_barrier
	s_setprio 1
	v_mfma_f32_16x16x32_bf16 v[52:55], v[200:203], v[158:161], v[52:55]
	v_mfma_f32_16x16x32_bf16 v[52:55], v[204:207], v[164:167], v[52:55]
	v_mfma_f32_16x16x32_bf16 v[48:51], v[208:211], v[158:161], v[48:51]
	v_mfma_f32_16x16x32_bf16 v[48:51], v[212:215], v[164:167], v[48:51]
	v_mfma_f32_16x16x32_bf16 v[36:39], v[200:203], v[176:179], v[36:39]
	v_mfma_f32_16x16x32_bf16 v[36:39], v[204:207], v[180:183], v[36:39]
	v_mfma_f32_16x16x32_bf16 v[32:35], v[208:211], v[176:179], v[32:35]
	v_mfma_f32_16x16x32_bf16 v[32:35], v[212:215], v[180:183], v[32:35]
	v_mfma_f32_16x16x32_bf16 v[20:23], v[200:203], v[184:187], v[20:23]
	v_mfma_f32_16x16x32_bf16 v[20:23], v[204:207], v[188:191], v[20:23]
	v_mfma_f32_16x16x32_bf16 v[16:19], v[208:211], v[184:187], v[16:19]
	v_mfma_f32_16x16x32_bf16 v[16:19], v[212:215], v[188:191], v[16:19]
	v_mfma_f32_16x16x32_bf16 v[4:7], v[200:203], v[192:195], v[4:7]
	v_mfma_f32_16x16x32_bf16 v[4:7], v[204:207], v[196:199], v[4:7]
	v_mfma_f32_16x16x32_bf16 v[0:3], v[208:211], v[192:195], v[0:3]
	v_mfma_f32_16x16x32_bf16 v[0:3], v[212:215], v[196:199], v[0:3]
	s_setprio 0
	s_add_i32 s42, 0, 0x18000
	v_add_u32_e32 v145, s42, v140
	s_barrier
	ds_read_b128 v[136:139], v145
	v_xor_b32_e32 v157, 64, v145
	ds_read_b128 v[146:149], v157
	ds_read_b128 v[150:153], v145 offset:2048
	ds_read_b128 v[154:157], v157 offset:2048
	s_add_u32 s16, s16, 0x160000
	s_addc_u32 s17, s17, 0
	s_mov_b32 m0, s23
	v_lshl_add_u64 v[200:201], s[16:17], 0, v[168:169]
	ds_read_b128 v[158:161], v142 offset:32768
	v_xor_b32_e32 v199, 64, v142
	ds_read_b128 v[164:167], v199 offset:32768
	ds_read_b128 v[176:179], v142 offset:34816
	ds_read_b128 v[180:183], v199 offset:34816
	ds_read_b128 v[184:187], v142 offset:36864
	ds_read_b128 v[188:191], v199 offset:36864
	ds_read_b128 v[192:195], v142 offset:38912
	ds_read_b128 v[196:199], v199 offset:38912
	global_load_lds_dwordx4 v[200:201], off
	v_lshl_add_u64 v[200:201], s[16:17], 0, v[172:173]
	s_mov_b32 m0, s24
	s_nop 0
	global_load_lds_dwordx4 v[200:201], off
	s_waitcnt lgkmcnt(8)
	s_barrier
	s_waitcnt lgkmcnt(0)
	s_setprio 1
	s_waitcnt lgkmcnt(0)
	v_mfma_f32_16x16x32_bf16 v[124:127], v[136:139], v[158:161], v[124:127]
	v_mfma_f32_16x16x32_bf16 v[124:127], v[146:149], v[164:167], v[124:127]
	v_mfma_f32_16x16x32_bf16 v[120:123], v[150:153], v[158:161], v[120:123]
	v_mfma_f32_16x16x32_bf16 v[120:123], v[154:157], v[164:167], v[120:123]
	v_mfma_f32_16x16x32_bf16 v[108:111], v[136:139], v[176:179], v[108:111]
	v_mfma_f32_16x16x32_bf16 v[108:111], v[146:149], v[180:183], v[108:111]
	v_mfma_f32_16x16x32_bf16 v[104:107], v[150:153], v[176:179], v[104:107]
	v_mfma_f32_16x16x32_bf16 v[104:107], v[154:157], v[180:183], v[104:107]
	v_mfma_f32_16x16x32_bf16 v[92:95], v[136:139], v[184:187], v[92:95]
	v_mfma_f32_16x16x32_bf16 v[92:95], v[146:149], v[188:191], v[92:95]
	v_mfma_f32_16x16x32_bf16 v[88:91], v[150:153], v[184:187], v[88:91]
	v_mfma_f32_16x16x32_bf16 v[88:91], v[154:157], v[188:191], v[88:91]
	v_mfma_f32_16x16x32_bf16 v[76:79], v[136:139], v[192:195], v[76:79]
	v_mfma_f32_16x16x32_bf16 v[76:79], v[146:149], v[196:199], v[76:79]
	v_mfma_f32_16x16x32_bf16 v[72:75], v[150:153], v[192:195], v[72:75]
	v_mfma_f32_16x16x32_bf16 v[72:75], v[154:157], v[196:199], v[72:75]
	s_setprio 0
	s_barrier
	s_add_i32 s16, 0, 0x1c000
	s_add_i32 s17, s42, s20
	v_add_u32_e32 v145, s16, v140
	v_lshl_add_u64 v[216:217], v[216:217], 0, s[12:13]
	s_mov_b32 m0, s17
	ds_read_b128 v[200:203], v145
	v_xor_b32_e32 v215, 64, v145
	ds_read_b128 v[204:207], v215
	ds_read_b128 v[208:211], v145 offset:2048
	ds_read_b128 v[212:215], v215 offset:2048
	global_load_lds_dwordx4 v[216:217], off
	v_lshl_add_u64 v[216:217], v[218:219], 0, s[12:13]
	s_add_i32 m0, s17, 0x2000
	s_nop 0
	global_load_lds_dwordx4 v[216:217], off
	s_barrier
	s_waitcnt lgkmcnt(0)
	s_setprio 1
	s_waitcnt lgkmcnt(0)
	v_mfma_f32_16x16x32_bf16 v[116:119], v[200:203], v[158:161], v[116:119]
	v_mfma_f32_16x16x32_bf16 v[116:119], v[204:207], v[164:167], v[116:119]
	v_mfma_f32_16x16x32_bf16 v[112:115], v[208:211], v[158:161], v[112:115]
	v_mfma_f32_16x16x32_bf16 v[112:115], v[212:215], v[164:167], v[112:115]
	v_mfma_f32_16x16x32_bf16 v[100:103], v[200:203], v[176:179], v[100:103]
	v_mfma_f32_16x16x32_bf16 v[100:103], v[204:207], v[180:183], v[100:103]
	v_mfma_f32_16x16x32_bf16 v[96:99], v[208:211], v[176:179], v[96:99]
	v_mfma_f32_16x16x32_bf16 v[96:99], v[212:215], v[180:183], v[96:99]
	v_mfma_f32_16x16x32_bf16 v[84:87], v[200:203], v[184:187], v[84:87]
	v_mfma_f32_16x16x32_bf16 v[84:87], v[204:207], v[188:191], v[84:87]
	v_mfma_f32_16x16x32_bf16 v[80:83], v[208:211], v[184:187], v[80:83]
	v_mfma_f32_16x16x32_bf16 v[80:83], v[212:215], v[188:191], v[80:83]
	v_mfma_f32_16x16x32_bf16 v[68:71], v[200:203], v[192:195], v[68:71]
	v_mfma_f32_16x16x32_bf16 v[68:71], v[204:207], v[196:199], v[68:71]
	v_mfma_f32_16x16x32_bf16 v[64:67], v[208:211], v[192:195], v[64:67]
	v_mfma_f32_16x16x32_bf16 v[64:67], v[212:215], v[196:199], v[64:67]
	s_setprio 0
	s_mov_b32 m0, s28
	v_lshl_add_u64 v[216:217], v[220:221], 0, s[12:13]
	s_barrier
	ds_read_b128 v[158:161], v142 offset:49152
	v_xor_b32_e32 v199, 64, v142
	ds_read_b128 v[164:167], v199 offset:49152
	ds_read_b128 v[176:179], v142 offset:51200
	ds_read_b128 v[180:183], v199 offset:51200
	ds_read_b128 v[184:187], v142 offset:53248
	ds_read_b128 v[188:191], v199 offset:53248
	ds_read_b128 v[192:195], v142 offset:55296
	ds_read_b128 v[196:199], v199 offset:55296
	global_load_lds_dwordx4 v[216:217], off
	v_lshl_add_u64 v[216:217], v[222:223], 0, s[12:13]
	s_mov_b32 m0, s29
	s_nop 0
	global_load_lds_dwordx4 v[216:217], off
	s_barrier
	s_waitcnt lgkmcnt(0)
	s_setprio 1
	s_waitcnt lgkmcnt(0)
	v_mfma_f32_16x16x32_bf16 v[60:63], v[136:139], v[158:161], v[60:63]
	v_mfma_f32_16x16x32_bf16 v[60:63], v[146:149], v[164:167], v[60:63]
	v_mfma_f32_16x16x32_bf16 v[56:59], v[150:153], v[158:161], v[56:59]
	v_mfma_f32_16x16x32_bf16 v[56:59], v[154:157], v[164:167], v[56:59]
	v_mfma_f32_16x16x32_bf16 v[44:47], v[136:139], v[176:179], v[44:47]
	v_mfma_f32_16x16x32_bf16 v[44:47], v[146:149], v[180:183], v[44:47]
	v_mfma_f32_16x16x32_bf16 v[40:43], v[150:153], v[176:179], v[40:43]
	v_mfma_f32_16x16x32_bf16 v[40:43], v[154:157], v[180:183], v[40:43]
	v_mfma_f32_16x16x32_bf16 v[28:31], v[136:139], v[184:187], v[28:31]
	v_mfma_f32_16x16x32_bf16 v[28:31], v[146:149], v[188:191], v[28:31]
	v_mfma_f32_16x16x32_bf16 v[24:27], v[150:153], v[184:187], v[24:27]
	v_mfma_f32_16x16x32_bf16 v[24:27], v[154:157], v[188:191], v[24:27]
	v_mfma_f32_16x16x32_bf16 v[12:15], v[136:139], v[192:195], v[12:15]
	v_mfma_f32_16x16x32_bf16 v[12:15], v[146:149], v[196:199], v[12:15]
	v_mfma_f32_16x16x32_bf16 v[8:11], v[150:153], v[192:195], v[8:11]
	v_mfma_f32_16x16x32_bf16 v[8:11], v[154:157], v[196:199], v[8:11]
	s_setprio 0
	s_barrier
	s_add_u32 s14, s14, 0x160080
	s_addc_u32 s15, s15, 0
	s_add_i32 s16, s16, s20
	v_lshl_add_u64 v[136:137], s[14:15], 0, v[170:171]
	s_mov_b32 m0, s16
	s_nop 0
	global_load_lds_dwordx4 v[136:137], off
	v_lshl_add_u64 v[136:137], s[14:15], 0, v[174:175]
	s_add_i32 m0, s16, 0x2000
	s_nop 0
	global_load_lds_dwordx4 v[136:137], off
	s_waitcnt vmcnt(6)
	s_barrier
	s_setprio 1
	v_mfma_f32_16x16x32_bf16 v[52:55], v[200:203], v[158:161], v[52:55]
	v_mfma_f32_16x16x32_bf16 v[52:55], v[204:207], v[164:167], v[52:55]
	v_mfma_f32_16x16x32_bf16 v[48:51], v[208:211], v[158:161], v[48:51]
	v_mfma_f32_16x16x32_bf16 v[48:51], v[212:215], v[164:167], v[48:51]
	v_mfma_f32_16x16x32_bf16 v[36:39], v[200:203], v[176:179], v[36:39]
	v_mfma_f32_16x16x32_bf16 v[36:39], v[204:207], v[180:183], v[36:39]
	v_mfma_f32_16x16x32_bf16 v[32:35], v[208:211], v[176:179], v[32:35]
	v_mfma_f32_16x16x32_bf16 v[32:35], v[212:215], v[180:183], v[32:35]
	v_mfma_f32_16x16x32_bf16 v[20:23], v[200:203], v[184:187], v[20:23]
	v_mfma_f32_16x16x32_bf16 v[20:23], v[204:207], v[188:191], v[20:23]
	v_mfma_f32_16x16x32_bf16 v[16:19], v[208:211], v[184:187], v[16:19]
	v_mfma_f32_16x16x32_bf16 v[16:19], v[212:215], v[188:191], v[16:19]
	v_mfma_f32_16x16x32_bf16 v[4:7], v[200:203], v[192:195], v[4:7]
	v_mfma_f32_16x16x32_bf16 v[4:7], v[204:207], v[196:199], v[4:7]
	v_mfma_f32_16x16x32_bf16 v[0:3], v[208:211], v[192:195], v[0:3]
	v_mfma_f32_16x16x32_bf16 v[0:3], v[212:215], v[196:199], v[0:3]
	s_setprio 0
	s_add_i32 s41, s41, 2
	s_add_u32 s0, s0, 0x100
	s_addc_u32 s1, s1, 0
	s_add_u32 s39, s39, 0x100
	s_addc_u32 s40, s40, 0
	s_cmpk_gt_u32 s41, 0x55
	s_barrier
	s_cbranch_scc0 .LBB0_985
	v_lshl_add_u32 v217, s38, 8, v163
	v_add_u32_e32 v217, s26, v217
	v_lshlrev_b32_e32 v208, 2, v217
	v_lshl_add_u32 v214, v225, 3, s27
	v_lshl_add_u32 v214, s37, 8, v214
	v_lshl_add_u32 v209, v217, 11, v214
	v_lshlrev_b32_e32 v209, 1, v209
	v_lshlrev_b32_e32 v210, 1, v209
	v_lshl_add_u32 v217, v225, 4, v163
	v_xor_b32_e32 v215, 16, v217
	v_lshlrev_b32_e32 v215, 2, v215
	v_xor_b32_e32 v216, 32, v217
	v_lshlrev_b32_e32 v216, 2, v216
	v_add_u32_e32 v211, 0x0, v209
	global_load_dwordx4 v[176:179], v211, s[80:81]
	global_load_dwordx4 v[180:183], v211, s[80:81] offset:256
	v_add_u32_e32 v211, 0x10000, v209
	global_load_dwordx4 v[192:195], v211, s[80:81]
	global_load_dwordx4 v[196:199], v211, s[80:81] offset:256
	s_waitcnt vmcnt(2)
	v_lshlrev_b32_e32 v184, 16, v176
	v_and_b32_e32 v185, 0xffff0000, v176
	v_lshlrev_b32_e32 v186, 16, v177
	v_and_b32_e32 v187, 0xffff0000, v177
	v_lshlrev_b32_e32 v188, 16, v178
	v_and_b32_e32 v189, 0xffff0000, v178
	v_lshlrev_b32_e32 v190, 16, v179
	v_and_b32_e32 v191, 0xffff0000, v179
	v_pk_add_f32 v[124:125], v[124:125], v[184:185]
	v_pk_add_f32 v[126:127], v[126:127], v[186:187]
	v_pk_add_f32 v[120:121], v[120:121], v[188:189]
	v_pk_add_f32 v[122:123], v[122:123], v[190:191]
	v_mul_f32_e32 v213, v124, v124
	v_fmac_f32_e32 v213, v125, v125
	v_fmac_f32_e32 v213, v126, v126
	v_fmac_f32_e32 v213, v127, v127
	v_fmac_f32_e32 v213, v120, v120
	v_fmac_f32_e32 v213, v121, v121
	v_fmac_f32_e32 v213, v122, v122
	v_fmac_f32_e32 v213, v123, v123
	v_add_u32_e32 v212, 0x0, v210
	global_store_dwordx4 v212, v[124:127], s[90:91]
	global_store_dwordx4 v212, v[120:123], s[90:91] offset:16
	v_lshlrev_b32_e32 v184, 16, v180
	v_and_b32_e32 v185, 0xffff0000, v180
	v_lshlrev_b32_e32 v186, 16, v181
	v_and_b32_e32 v187, 0xffff0000, v181
	v_lshlrev_b32_e32 v188, 16, v182
	v_and_b32_e32 v189, 0xffff0000, v182
	v_lshlrev_b32_e32 v190, 16, v183
	v_and_b32_e32 v191, 0xffff0000, v183
	v_pk_add_f32 v[116:117], v[116:117], v[184:185]
	v_pk_add_f32 v[118:119], v[118:119], v[186:187]
	v_pk_add_f32 v[112:113], v[112:113], v[188:189]
	v_pk_add_f32 v[114:115], v[114:115], v[190:191]
	v_fmac_f32_e32 v213, v116, v116
	v_fmac_f32_e32 v213, v117, v117
	v_fmac_f32_e32 v213, v118, v118
	v_fmac_f32_e32 v213, v119, v119
	v_fmac_f32_e32 v213, v112, v112
	v_fmac_f32_e32 v213, v113, v113
	v_fmac_f32_e32 v213, v114, v114
	v_fmac_f32_e32 v213, v115, v115
	global_store_dwordx4 v212, v[116:119], s[90:91] offset:512
	global_store_dwordx4 v212, v[112:115], s[90:91] offset:528
	ds_bpermute_b32 v214, v215, v213
	s_waitcnt lgkmcnt(0)
	v_add_f32_e32 v213, v213, v214
	ds_bpermute_b32 v214, v216, v213
	s_waitcnt lgkmcnt(0)
	v_add_f32_e32 v213, v213, v214
	s_mov_b64 exec, 0xffff
	global_atomic_add_f32 v208, v213, s[10:11]
	s_mov_b64 exec, -1
	v_add_u32_e32 v211, 0x20000, v209
	global_load_dwordx4 v[176:179], v211, s[80:81]
	global_load_dwordx4 v[180:183], v211, s[80:81] offset:256
	s_waitcnt vmcnt(7)
	v_lshlrev_b32_e32 v200, 16, v192
	v_and_b32_e32 v201, 0xffff0000, v192
	v_lshlrev_b32_e32 v202, 16, v193
	v_and_b32_e32 v203, 0xffff0000, v193
	v_lshlrev_b32_e32 v204, 16, v194
	v_and_b32_e32 v205, 0xffff0000, v194
	v_lshlrev_b32_e32 v206, 16, v195
	v_and_b32_e32 v207, 0xffff0000, v195
	v_pk_add_f32 v[108:109], v[108:109], v[200:201]
	v_pk_add_f32 v[110:111], v[110:111], v[202:203]
	v_pk_add_f32 v[104:105], v[104:105], v[204:205]
	v_pk_add_f32 v[106:107], v[106:107], v[206:207]
	v_mul_f32_e32 v213, v108, v108
	v_fmac_f32_e32 v213, v109, v109
	v_fmac_f32_e32 v213, v110, v110
	v_fmac_f32_e32 v213, v111, v111
	v_fmac_f32_e32 v213, v104, v104
	v_fmac_f32_e32 v213, v105, v105
	v_fmac_f32_e32 v213, v106, v106
	v_fmac_f32_e32 v213, v107, v107
	v_add_u32_e32 v212, 0x20000, v210
	global_store_dwordx4 v212, v[108:111], s[90:91]
	global_store_dwordx4 v212, v[104:107], s[90:91] offset:16
	v_lshlrev_b32_e32 v200, 16, v196
	v_and_b32_e32 v201, 0xffff0000, v196
	v_lshlrev_b32_e32 v202, 16, v197
	v_and_b32_e32 v203, 0xffff0000, v197
	v_lshlrev_b32_e32 v204, 16, v198
	v_and_b32_e32 v205, 0xffff0000, v198
	v_lshlrev_b32_e32 v206, 16, v199
	v_and_b32_e32 v207, 0xffff0000, v199
	v_pk_add_f32 v[100:101], v[100:101], v[200:201]
	v_pk_add_f32 v[102:103], v[102:103], v[202:203]
	v_pk_add_f32 v[96:97], v[96:97], v[204:205]
	v_pk_add_f32 v[98:99], v[98:99], v[206:207]
	v_fmac_f32_e32 v213, v100, v100
	v_fmac_f32_e32 v213, v101, v101
	v_fmac_f32_e32 v213, v102, v102
	v_fmac_f32_e32 v213, v103, v103
	v_fmac_f32_e32 v213, v96, v96
	v_fmac_f32_e32 v213, v97, v97
	v_fmac_f32_e32 v213, v98, v98
	v_fmac_f32_e32 v213, v99, v99
	global_store_dwordx4 v212, v[100:103], s[90:91] offset:512
	global_store_dwordx4 v212, v[96:99], s[90:91] offset:528
	ds_bpermute_b32 v214, v215, v213
	s_waitcnt lgkmcnt(0)
	v_add_f32_e32 v213, v213, v214
	ds_bpermute_b32 v214, v216, v213
	s_waitcnt lgkmcnt(0)
	v_add_f32_e32 v213, v213, v214
	s_mov_b64 exec, 0xffff
	global_atomic_add_f32 v208, v213, s[10:11] offset:64
	s_mov_b64 exec, -1
	v_add_u32_e32 v211, 0x30000, v209
	global_load_dwordx4 v[192:195], v211, s[80:81]
	global_load_dwordx4 v[196:199], v211, s[80:81] offset:256
	s_waitcnt vmcnt(7)
	v_lshlrev_b32_e32 v184, 16, v176
	v_and_b32_e32 v185, 0xffff0000, v176
	v_lshlrev_b32_e32 v186, 16, v177
	v_and_b32_e32 v187, 0xffff0000, v177
	v_lshlrev_b32_e32 v188, 16, v178
	v_and_b32_e32 v189, 0xffff0000, v178
	v_lshlrev_b32_e32 v190, 16, v179
	v_and_b32_e32 v191, 0xffff0000, v179
	v_pk_add_f32 v[92:93], v[92:93], v[184:185]
	v_pk_add_f32 v[94:95], v[94:95], v[186:187]
	v_pk_add_f32 v[88:89], v[88:89], v[188:189]
	v_pk_add_f32 v[90:91], v[90:91], v[190:191]
	v_mul_f32_e32 v213, v92, v92
	v_fmac_f32_e32 v213, v93, v93
	v_fmac_f32_e32 v213, v94, v94
	v_fmac_f32_e32 v213, v95, v95
	v_fmac_f32_e32 v213, v88, v88
	v_fmac_f32_e32 v213, v89, v89
	v_fmac_f32_e32 v213, v90, v90
	v_fmac_f32_e32 v213, v91, v91
	v_add_u32_e32 v212, 0x40000, v210
	global_store_dwordx4 v212, v[92:95], s[90:91]
	global_store_dwordx4 v212, v[88:91], s[90:91] offset:16
	v_lshlrev_b32_e32 v184, 16, v180
	v_and_b32_e32 v185, 0xffff0000, v180
	v_lshlrev_b32_e32 v186, 16, v181
	v_and_b32_e32 v187, 0xffff0000, v181
	v_lshlrev_b32_e32 v188, 16, v182
	v_and_b32_e32 v189, 0xffff0000, v182
	v_lshlrev_b32_e32 v190, 16, v183
	v_and_b32_e32 v191, 0xffff0000, v183
	v_pk_add_f32 v[84:85], v[84:85], v[184:185]
	v_pk_add_f32 v[86:87], v[86:87], v[186:187]
	v_pk_add_f32 v[80:81], v[80:81], v[188:189]
	v_pk_add_f32 v[82:83], v[82:83], v[190:191]
	v_fmac_f32_e32 v213, v84, v84
	v_fmac_f32_e32 v213, v85, v85
	v_fmac_f32_e32 v213, v86, v86
	v_fmac_f32_e32 v213, v87, v87
	v_fmac_f32_e32 v213, v80, v80
	v_fmac_f32_e32 v213, v81, v81
	v_fmac_f32_e32 v213, v82, v82
	v_fmac_f32_e32 v213, v83, v83
	global_store_dwordx4 v212, v[84:87], s[90:91] offset:512
	global_store_dwordx4 v212, v[80:83], s[90:91] offset:528
	ds_bpermute_b32 v214, v215, v213
	s_waitcnt lgkmcnt(0)
	v_add_f32_e32 v213, v213, v214
	ds_bpermute_b32 v214, v216, v213
	s_waitcnt lgkmcnt(0)
	v_add_f32_e32 v213, v213, v214
	s_mov_b64 exec, 0xffff
	global_atomic_add_f32 v208, v213, s[10:11] offset:128
	s_mov_b64 exec, -1
	v_add_u32_e32 v211, 0x80000, v209
	global_load_dwordx4 v[176:179], v211, s[80:81]
	global_load_dwordx4 v[180:183], v211, s[80:81] offset:256
	s_waitcnt vmcnt(7)
	v_lshlrev_b32_e32 v200, 16, v192
	v_and_b32_e32 v201, 0xffff0000, v192
	v_lshlrev_b32_e32 v202, 16, v193
	v_and_b32_e32 v203, 0xffff0000, v193
	v_lshlrev_b32_e32 v204, 16, v194
	v_and_b32_e32 v205, 0xffff0000, v194
	v_lshlrev_b32_e32 v206, 16, v195
	v_and_b32_e32 v207, 0xffff0000, v195
	v_pk_add_f32 v[76:77], v[76:77], v[200:201]
	v_pk_add_f32 v[78:79], v[78:79], v[202:203]
	v_pk_add_f32 v[72:73], v[72:73], v[204:205]
	v_pk_add_f32 v[74:75], v[74:75], v[206:207]
	v_mul_f32_e32 v213, v76, v76
	v_fmac_f32_e32 v213, v77, v77
	v_fmac_f32_e32 v213, v78, v78
	v_fmac_f32_e32 v213, v79, v79
	v_fmac_f32_e32 v213, v72, v72
	v_fmac_f32_e32 v213, v73, v73
	v_fmac_f32_e32 v213, v74, v74
	v_fmac_f32_e32 v213, v75, v75
	v_add_u32_e32 v212, 0x60000, v210
	global_store_dwordx4 v212, v[76:79], s[90:91]
	global_store_dwordx4 v212, v[72:75], s[90:91] offset:16
	v_lshlrev_b32_e32 v200, 16, v196
	v_and_b32_e32 v201, 0xffff0000, v196
	v_lshlrev_b32_e32 v202, 16, v197
	v_and_b32_e32 v203, 0xffff0000, v197
	v_lshlrev_b32_e32 v204, 16, v198
	v_and_b32_e32 v205, 0xffff0000, v198
	v_lshlrev_b32_e32 v206, 16, v199
	v_and_b32_e32 v207, 0xffff0000, v199
	v_pk_add_f32 v[68:69], v[68:69], v[200:201]
	v_pk_add_f32 v[70:71], v[70:71], v[202:203]
	v_pk_add_f32 v[64:65], v[64:65], v[204:205]
	v_pk_add_f32 v[66:67], v[66:67], v[206:207]
	v_fmac_f32_e32 v213, v68, v68
	v_fmac_f32_e32 v213, v69, v69
	v_fmac_f32_e32 v213, v70, v70
	v_fmac_f32_e32 v213, v71, v71
	v_fmac_f32_e32 v213, v64, v64
	v_fmac_f32_e32 v213, v65, v65
	v_fmac_f32_e32 v213, v66, v66
	v_fmac_f32_e32 v213, v67, v67
	global_store_dwordx4 v212, v[68:71], s[90:91] offset:512
	global_store_dwordx4 v212, v[64:67], s[90:91] offset:528
	ds_bpermute_b32 v214, v215, v213
	s_waitcnt lgkmcnt(0)
	v_add_f32_e32 v213, v213, v214
	ds_bpermute_b32 v214, v216, v213
	s_waitcnt lgkmcnt(0)
	v_add_f32_e32 v213, v213, v214
	s_mov_b64 exec, 0xffff
	global_atomic_add_f32 v208, v213, s[10:11] offset:192
	s_mov_b64 exec, -1
	v_add_u32_e32 v211, 0x90000, v209
	global_load_dwordx4 v[192:195], v211, s[80:81]
	global_load_dwordx4 v[196:199], v211, s[80:81] offset:256
	s_waitcnt vmcnt(7)
	v_lshlrev_b32_e32 v184, 16, v176
	v_and_b32_e32 v185, 0xffff0000, v176
	v_lshlrev_b32_e32 v186, 16, v177
	v_and_b32_e32 v187, 0xffff0000, v177
	v_lshlrev_b32_e32 v188, 16, v178
	v_and_b32_e32 v189, 0xffff0000, v178
	v_lshlrev_b32_e32 v190, 16, v179
	v_and_b32_e32 v191, 0xffff0000, v179
	v_pk_add_f32 v[60:61], v[60:61], v[184:185]
	v_pk_add_f32 v[62:63], v[62:63], v[186:187]
	v_pk_add_f32 v[56:57], v[56:57], v[188:189]
	v_pk_add_f32 v[58:59], v[58:59], v[190:191]
	v_mul_f32_e32 v213, v60, v60
	v_fmac_f32_e32 v213, v61, v61
	v_fmac_f32_e32 v213, v62, v62
	v_fmac_f32_e32 v213, v63, v63
	v_fmac_f32_e32 v213, v56, v56
	v_fmac_f32_e32 v213, v57, v57
	v_fmac_f32_e32 v213, v58, v58
	v_fmac_f32_e32 v213, v59, v59
	v_add_u32_e32 v212, 0x100000, v210
	global_store_dwordx4 v212, v[60:63], s[90:91]
	global_store_dwordx4 v212, v[56:59], s[90:91] offset:16
	v_lshlrev_b32_e32 v184, 16, v180
	v_and_b32_e32 v185, 0xffff0000, v180
	v_lshlrev_b32_e32 v186, 16, v181
	v_and_b32_e32 v187, 0xffff0000, v181
	v_lshlrev_b32_e32 v188, 16, v182
	v_and_b32_e32 v189, 0xffff0000, v182
	v_lshlrev_b32_e32 v190, 16, v183
	v_and_b32_e32 v191, 0xffff0000, v183
	v_pk_add_f32 v[52:53], v[52:53], v[184:185]
	v_pk_add_f32 v[54:55], v[54:55], v[186:187]
	v_pk_add_f32 v[48:49], v[48:49], v[188:189]
	v_pk_add_f32 v[50:51], v[50:51], v[190:191]
	v_fmac_f32_e32 v213, v52, v52
	v_fmac_f32_e32 v213, v53, v53
	v_fmac_f32_e32 v213, v54, v54
	v_fmac_f32_e32 v213, v55, v55
	v_fmac_f32_e32 v213, v48, v48
	v_fmac_f32_e32 v213, v49, v49
	v_fmac_f32_e32 v213, v50, v50
	v_fmac_f32_e32 v213, v51, v51
	global_store_dwordx4 v212, v[52:55], s[90:91] offset:512
	global_store_dwordx4 v212, v[48:51], s[90:91] offset:528
	ds_bpermute_b32 v214, v215, v213
	s_waitcnt lgkmcnt(0)
	v_add_f32_e32 v213, v213, v214
	ds_bpermute_b32 v214, v216, v213
	s_waitcnt lgkmcnt(0)
	v_add_f32_e32 v213, v213, v214
	s_mov_b64 exec, 0xffff
	global_atomic_add_f32 v208, v213, s[10:11] offset:512
	s_mov_b64 exec, -1
	v_add_u32_e32 v211, 0xa0000, v209
	global_load_dwordx4 v[176:179], v211, s[80:81]
	global_load_dwordx4 v[180:183], v211, s[80:81] offset:256
	s_waitcnt vmcnt(7)
	v_lshlrev_b32_e32 v200, 16, v192
	v_and_b32_e32 v201, 0xffff0000, v192
	v_lshlrev_b32_e32 v202, 16, v193
	v_and_b32_e32 v203, 0xffff0000, v193
	v_lshlrev_b32_e32 v204, 16, v194
	v_and_b32_e32 v205, 0xffff0000, v194
	v_lshlrev_b32_e32 v206, 16, v195
	v_and_b32_e32 v207, 0xffff0000, v195
	v_pk_add_f32 v[44:45], v[44:45], v[200:201]
	v_pk_add_f32 v[46:47], v[46:47], v[202:203]
	v_pk_add_f32 v[40:41], v[40:41], v[204:205]
	v_pk_add_f32 v[42:43], v[42:43], v[206:207]
	v_mul_f32_e32 v213, v44, v44
	v_fmac_f32_e32 v213, v45, v45
	v_fmac_f32_e32 v213, v46, v46
	v_fmac_f32_e32 v213, v47, v47
	v_fmac_f32_e32 v213, v40, v40
	v_fmac_f32_e32 v213, v41, v41
	v_fmac_f32_e32 v213, v42, v42
	v_fmac_f32_e32 v213, v43, v43
	v_add_u32_e32 v212, 0x120000, v210
	global_store_dwordx4 v212, v[44:47], s[90:91]
	global_store_dwordx4 v212, v[40:43], s[90:91] offset:16
	v_lshlrev_b32_e32 v200, 16, v196
	v_and_b32_e32 v201, 0xffff0000, v196
	v_lshlrev_b32_e32 v202, 16, v197
	v_and_b32_e32 v203, 0xffff0000, v197
	v_lshlrev_b32_e32 v204, 16, v198
	v_and_b32_e32 v205, 0xffff0000, v198
	v_lshlrev_b32_e32 v206, 16, v199
	v_and_b32_e32 v207, 0xffff0000, v199
	v_pk_add_f32 v[36:37], v[36:37], v[200:201]
	v_pk_add_f32 v[38:39], v[38:39], v[202:203]
	v_pk_add_f32 v[32:33], v[32:33], v[204:205]
	v_pk_add_f32 v[34:35], v[34:35], v[206:207]
	v_fmac_f32_e32 v213, v36, v36
	v_fmac_f32_e32 v213, v37, v37
	v_fmac_f32_e32 v213, v38, v38
	v_fmac_f32_e32 v213, v39, v39
	v_fmac_f32_e32 v213, v32, v32
	v_fmac_f32_e32 v213, v33, v33
	v_fmac_f32_e32 v213, v34, v34
	v_fmac_f32_e32 v213, v35, v35
	global_store_dwordx4 v212, v[36:39], s[90:91] offset:512
	global_store_dwordx4 v212, v[32:35], s[90:91] offset:528
	ds_bpermute_b32 v214, v215, v213
	s_waitcnt lgkmcnt(0)
	v_add_f32_e32 v213, v213, v214
	ds_bpermute_b32 v214, v216, v213
	s_waitcnt lgkmcnt(0)
	v_add_f32_e32 v213, v213, v214
	s_mov_b64 exec, 0xffff
	global_atomic_add_f32 v208, v213, s[10:11] offset:576
	s_mov_b64 exec, -1
	v_add_u32_e32 v211, 0xb0000, v209
	global_load_dwordx4 v[192:195], v211, s[80:81]
	global_load_dwordx4 v[196:199], v211, s[80:81] offset:256
	s_waitcnt vmcnt(7)
	v_lshlrev_b32_e32 v184, 16, v176
	v_and_b32_e32 v185, 0xffff0000, v176
	v_lshlrev_b32_e32 v186, 16, v177
	v_and_b32_e32 v187, 0xffff0000, v177
	v_lshlrev_b32_e32 v188, 16, v178
	v_and_b32_e32 v189, 0xffff0000, v178
	v_lshlrev_b32_e32 v190, 16, v179
	v_and_b32_e32 v191, 0xffff0000, v179
	v_pk_add_f32 v[28:29], v[28:29], v[184:185]
	v_pk_add_f32 v[30:31], v[30:31], v[186:187]
	v_pk_add_f32 v[24:25], v[24:25], v[188:189]
	v_pk_add_f32 v[26:27], v[26:27], v[190:191]
	v_mul_f32_e32 v213, v28, v28
	v_fmac_f32_e32 v213, v29, v29
	v_fmac_f32_e32 v213, v30, v30
	v_fmac_f32_e32 v213, v31, v31
	v_fmac_f32_e32 v213, v24, v24
	v_fmac_f32_e32 v213, v25, v25
	v_fmac_f32_e32 v213, v26, v26
	v_fmac_f32_e32 v213, v27, v27
	v_add_u32_e32 v212, 0x140000, v210
	global_store_dwordx4 v212, v[28:31], s[90:91]
	global_store_dwordx4 v212, v[24:27], s[90:91] offset:16
	v_lshlrev_b32_e32 v184, 16, v180
	v_and_b32_e32 v185, 0xffff0000, v180
	v_lshlrev_b32_e32 v186, 16, v181
	v_and_b32_e32 v187, 0xffff0000, v181
	v_lshlrev_b32_e32 v188, 16, v182
	v_and_b32_e32 v189, 0xffff0000, v182
	v_lshlrev_b32_e32 v190, 16, v183
	v_and_b32_e32 v191, 0xffff0000, v183
	v_pk_add_f32 v[20:21], v[20:21], v[184:185]
	v_pk_add_f32 v[22:23], v[22:23], v[186:187]
	v_pk_add_f32 v[16:17], v[16:17], v[188:189]
	v_pk_add_f32 v[18:19], v[18:19], v[190:191]
	v_fmac_f32_e32 v213, v20, v20
	v_fmac_f32_e32 v213, v21, v21
	v_fmac_f32_e32 v213, v22, v22
	v_fmac_f32_e32 v213, v23, v23
	v_fmac_f32_e32 v213, v16, v16
	v_fmac_f32_e32 v213, v17, v17
	v_fmac_f32_e32 v213, v18, v18
	v_fmac_f32_e32 v213, v19, v19
	global_store_dwordx4 v212, v[20:23], s[90:91] offset:512
	global_store_dwordx4 v212, v[16:19], s[90:91] offset:528
	ds_bpermute_b32 v214, v215, v213
	s_waitcnt lgkmcnt(0)
	v_add_f32_e32 v213, v213, v214
	ds_bpermute_b32 v214, v216, v213
	s_waitcnt lgkmcnt(0)
	v_add_f32_e32 v213, v213, v214
	s_mov_b64 exec, 0xffff
	global_atomic_add_f32 v208, v213, s[10:11] offset:640
	s_mov_b64 exec, -1
	s_waitcnt vmcnt(5)
	v_lshlrev_b32_e32 v200, 16, v192
	v_and_b32_e32 v201, 0xffff0000, v192
	v_lshlrev_b32_e32 v202, 16, v193
	v_and_b32_e32 v203, 0xffff0000, v193
	v_lshlrev_b32_e32 v204, 16, v194
	v_and_b32_e32 v205, 0xffff0000, v194
	v_lshlrev_b32_e32 v206, 16, v195
	v_and_b32_e32 v207, 0xffff0000, v195
	v_pk_add_f32 v[12:13], v[12:13], v[200:201]
	v_pk_add_f32 v[14:15], v[14:15], v[202:203]
	v_pk_add_f32 v[8:9], v[8:9], v[204:205]
	v_pk_add_f32 v[10:11], v[10:11], v[206:207]
	v_mul_f32_e32 v213, v12, v12
	v_fmac_f32_e32 v213, v13, v13
	v_fmac_f32_e32 v213, v14, v14
	v_fmac_f32_e32 v213, v15, v15
	v_fmac_f32_e32 v213, v8, v8
	v_fmac_f32_e32 v213, v9, v9
	v_fmac_f32_e32 v213, v10, v10
	v_fmac_f32_e32 v213, v11, v11
	v_add_u32_e32 v212, 0x160000, v210
	global_store_dwordx4 v212, v[12:15], s[90:91]
	global_store_dwordx4 v212, v[8:11], s[90:91] offset:16
	v_lshlrev_b32_e32 v200, 16, v196
	v_and_b32_e32 v201, 0xffff0000, v196
	v_lshlrev_b32_e32 v202, 16, v197
	v_and_b32_e32 v203, 0xffff0000, v197
	v_lshlrev_b32_e32 v204, 16, v198
	v_and_b32_e32 v205, 0xffff0000, v198
	v_lshlrev_b32_e32 v206, 16, v199
	v_and_b32_e32 v207, 0xffff0000, v199
	v_pk_add_f32 v[4:5], v[4:5], v[200:201]
	v_pk_add_f32 v[6:7], v[6:7], v[202:203]
	v_pk_add_f32 v[0:1], v[0:1], v[204:205]
	v_pk_add_f32 v[2:3], v[2:3], v[206:207]
	v_fmac_f32_e32 v213, v4, v4
	v_fmac_f32_e32 v213, v5, v5
	v_fmac_f32_e32 v213, v6, v6
	v_fmac_f32_e32 v213, v7, v7
	v_fmac_f32_e32 v213, v0, v0
	v_fmac_f32_e32 v213, v1, v1
	v_fmac_f32_e32 v213, v2, v2
	v_fmac_f32_e32 v213, v3, v3
	global_store_dwordx4 v212, v[4:7], s[90:91] offset:512
	global_store_dwordx4 v212, v[0:3], s[90:91] offset:528
	ds_bpermute_b32 v214, v215, v213
	s_waitcnt lgkmcnt(0)
	v_add_f32_e32 v213, v213, v214
	ds_bpermute_b32 v214, v216, v213
	s_waitcnt lgkmcnt(0)
	v_add_f32_e32 v213, v213, v214
	s_mov_b64 exec, 0xffff
	global_atomic_add_f32 v208, v213, s[10:11] offset:704
	s_mov_b64 exec, -1
	s_branch .LBB0_973
